# GEMM K-loops: the back-to-back s_setprio 0 / s_setprio 1 pair between the two 16-MFMA groups of each phase removed (A/B per asm guide 6.3)
# baseline (speedup 1.0000x reference)
; #define PG8_STAGE(bufoff, gbase, voff) do { _Pragma("unroll") for (int _i = 0; _i < 2; ++_i) \
;         __builtin_amdgcn_global_load_lds((const unsigned*)((const char*)(gbase) + (voff)[_i]), (LAS unsigned*)(lds + (bufoff) + ldsw + _i * 8192), 16, 0, 0); } while (0)
; #define PG8_LDA(dst, b, h) do { _Pragma("unroll") for (int m = 0; m < 4; ++m) _Pragma("unroll") for (int k = 0; k < 2; ++k) dst[m][k] = *(const LAS bf16x8*)(lds + PG8_SA(b, h) + aoff + m * 2048 + k * 1024); } while (0)
; #define PG8_LDB(dst, b, h) do { _Pragma("unroll") for (int n = 0; n < 2; ++n) _Pragma("unroll") for (int k = 0; k < 2; ++k) dst[n][k] = *(const LAS bf16x8*)(lds + PG8_SB(b, h) + boff + n * 2048 + k * 1024); } while (0)
; #define PG8_MMA(ai, bj, At, Bt) do { __builtin_amdgcn_s_setprio(1); _Pragma("unroll") for (int k = 0; k < 2; ++k) _Pragma("unroll") for (int m = 0; m < 4; ++m) _Pragma("unroll") for (int n = 0; n < 2; ++n) \
;         acc[ai][bj][m][n] = __builtin_amdgcn_mfma_f32_16x16x32_bf16(Bt[n][k], At[m][k], acc[ai][bj][m][n], 0, 0, 0); __builtin_amdgcn_s_setprio(0); } while (0)
; #define PG8_WAIT_V(n) asm volatile("s_waitcnt vmcnt(" #n ")" ::: "memory")
; #define PG8_WAIT_L(n) asm volatile("s_waitcnt lgkmcnt(" #n ")" ::: "memory")
; #define PG8_BAR __builtin_amdgcn_s_barrier()
; #define PG8_SCHED __builtin_amdgcn_sched_barrier(0)
; template <class Epi, bool ALIGN_EPI = PG8_ALIGN, bool SP2 = PG8_SP2>
; __device__ __forceinline__ void gemm_phase(LAS unsigned char* lds, const int tid, const int K, const Order& S, const Epi& E) {
;     ...
;             PG8_LDB(B0, 0, 0); PG8_LDB(B1, 0, 1); PG8_SCHED; PG8_LDA(At, 0, 0); PG8_STAGE(PG8_SA(1, 1), a1 + hstep, voffA);
;             PG8_WAIT_V(8); PG8_WAIT_L(0); PG8_BAR; PG8_MMA(0, 0, At, B0); PG8_MMA(0, 1, At, B1); PG8_BAR; PG8_SCHED;
;             PG8_LDA(At, 0, 1); PG8_STAGE(PG8_SB(0, 0), b2, voffB); PG8_STAGE(PG8_SB(0, 1), b2 + hstep, voffB); PG8_STAGE(PG8_SA(0, 0), a2, voffA);
;             PG8_WAIT_V(8); PG8_WAIT_L(0); PG8_BAR; PG8_MMA(1, 0, At, B0); PG8_MMA(1, 1, At, B1); PG8_BAR; PG8_SCHED;
.LBB0_265:
	ds_read_b128 v[142:145], v151
	ds_read_b128 v[154:157], v151 offset:1024
	ds_read_b128 v[158:161], v151 offset:2048
	ds_read_b128 v[162:165], v151 offset:3072
	ds_read_b128 v[166:169], v152
	ds_read_b128 v[170:173], v152 offset:1024
	ds_read_b128 v[174:177], v152 offset:2048
	ds_read_b128 v[178:181], v152 offset:3072
	s_add_u32 s42, s34, 0xfff80080
	s_addc_u32 s43, s35, -1
	s_cmp_eq_u32 s65, 28
	s_cselect_b32 s45, s5, s43
	s_cselect_b32 s44, s25, s42
	s_cselect_b32 s43, s23, s64
	s_cselect_b32 s42, s62, s63
	v_lshl_add_u64 v[214:215], s[34:35], 0, v[138:139]
	s_add_i32 m0, s37, 0xc000
	ds_read_b128 v[182:185], v153
	ds_read_b128 v[186:189], v153 offset:1024
	ds_read_b128 v[190:193], v153 offset:2048
	ds_read_b128 v[194:197], v153 offset:3072
	ds_read_b128 v[198:201], v153 offset:4096
	ds_read_b128 v[202:205], v153 offset:5120
	ds_read_b128 v[206:209], v153 offset:6144
	ds_read_b128 v[210:213], v153 offset:7168
	global_load_lds_dwordx4 v[214:215], off
	v_lshl_add_u64 v[214:215], s[34:35], 0, v[136:137]
	s_add_i32 m0, s37, 0xe000
	s_nop 0
	global_load_lds_dwordx4 v[214:215], off
	s_waitcnt vmcnt(8)
	s_waitcnt lgkmcnt(0)
	s_barrier
	s_setprio 1
	s_waitcnt lgkmcnt(0)
	v_mfma_f32_16x16x32_bf16 v[124:127], v[142:145], v[182:185], v[124:127]
	v_mfma_f32_16x16x32_bf16 v[120:123], v[158:161], v[182:185], v[120:123]
	v_mfma_f32_16x16x32_bf16 v[108:111], v[142:145], v[190:193], v[108:111]
	v_mfma_f32_16x16x32_bf16 v[104:107], v[158:161], v[190:193], v[104:107]
	v_mfma_f32_16x16x32_bf16 v[92:95], v[142:145], v[198:201], v[92:95]
	v_mfma_f32_16x16x32_bf16 v[88:91], v[158:161], v[198:201], v[88:91]
	v_mfma_f32_16x16x32_bf16 v[76:79], v[142:145], v[206:209], v[76:79]
	v_mfma_f32_16x16x32_bf16 v[72:75], v[158:161], v[206:209], v[72:75]
	v_mfma_f32_16x16x32_bf16 v[124:127], v[154:157], v[186:189], v[124:127]
	v_mfma_f32_16x16x32_bf16 v[120:123], v[162:165], v[186:189], v[120:123]
	v_mfma_f32_16x16x32_bf16 v[108:111], v[154:157], v[194:197], v[108:111]
	v_mfma_f32_16x16x32_bf16 v[104:107], v[162:165], v[194:197], v[104:107]
	v_mfma_f32_16x16x32_bf16 v[92:95], v[154:157], v[202:205], v[92:95]
	v_mfma_f32_16x16x32_bf16 v[88:91], v[162:165], v[202:205], v[88:91]
	v_mfma_f32_16x16x32_bf16 v[76:79], v[154:157], v[210:213], v[76:79]
	v_mfma_f32_16x16x32_bf16 v[72:75], v[162:165], v[210:213], v[72:75]
	v_mfma_f32_16x16x32_bf16 v[116:119], v[166:169], v[182:185], v[116:119]
	v_mfma_f32_16x16x32_bf16 v[112:115], v[174:177], v[182:185], v[112:115]
	v_mfma_f32_16x16x32_bf16 v[100:103], v[166:169], v[190:193], v[100:103]
	v_mfma_f32_16x16x32_bf16 v[96:99], v[174:177], v[190:193], v[96:99]
	v_mfma_f32_16x16x32_bf16 v[84:87], v[166:169], v[198:201], v[84:87]
	v_mfma_f32_16x16x32_bf16 v[80:83], v[174:177], v[198:201], v[80:83]
	v_mfma_f32_16x16x32_bf16 v[68:71], v[166:169], v[206:209], v[68:71]
	v_mfma_f32_16x16x32_bf16 v[64:67], v[174:177], v[206:209], v[64:67]
	v_mfma_f32_16x16x32_bf16 v[116:119], v[170:173], v[186:189], v[116:119]
	v_mfma_f32_16x16x32_bf16 v[112:115], v[178:181], v[186:189], v[112:115]
	v_mfma_f32_16x16x32_bf16 v[100:103], v[170:173], v[194:197], v[100:103]
	v_mfma_f32_16x16x32_bf16 v[96:99], v[178:181], v[194:197], v[96:99]
	v_mfma_f32_16x16x32_bf16 v[84:87], v[170:173], v[202:205], v[84:87]
	v_mfma_f32_16x16x32_bf16 v[80:83], v[178:181], v[202:205], v[80:83]
	v_mfma_f32_16x16x32_bf16 v[68:71], v[170:173], v[210:213], v[68:71]
	v_mfma_f32_16x16x32_bf16 v[64:67], v[178:181], v[210:213], v[64:67]
	s_setprio 0
	s_barrier
	s_add_i32 s66, s60, s49
	v_lshl_add_u64 v[214:215], s[42:43], 0, v[130:131]
	s_mov_b32 m0, s66
	ds_read_b128 v[182:185], v153 offset:16384
	ds_read_b128 v[186:189], v153 offset:17408
	ds_read_b128 v[190:193], v153 offset:18432
	ds_read_b128 v[194:197], v153 offset:19456
	ds_read_b128 v[198:201], v153 offset:20480
	ds_read_b128 v[202:205], v153 offset:21504
	ds_read_b128 v[206:209], v153 offset:22528
	ds_read_b128 v[210:213], v153 offset:23552
	global_load_lds_dwordx4 v[214:215], off
	s_add_i32 m0, s66, 0x2000
	s_add_u32 s66, s42, 0x80000
	v_lshl_add_u64 v[218:219], s[42:43], 0, v[134:135]
	s_addc_u32 s67, s43, 0
	s_add_i32 s68, s61, s49
	global_load_lds_dwordx4 v[218:219], off
	v_lshl_add_u64 v[220:221], s[66:67], 0, v[130:131]
	s_mov_b32 m0, s68
	v_lshl_add_u64 v[222:223], s[44:45], 0, v[132:133]
	global_load_lds_dwordx4 v[220:221], off
	v_lshl_add_u64 v[220:221], s[66:67], 0, v[134:135]
	s_add_i32 m0, s68, 0x2000
	s_nop 0
	global_load_lds_dwordx4 v[220:221], off
	v_lshl_add_u64 v[220:221], s[44:45], 0, v[128:129]
	s_mov_b32 m0, s37
	s_nop 0
	global_load_lds_dwordx4 v[220:221], off
	s_mov_b32 m0, s50
	s_nop 0
	global_load_lds_dwordx4 v[222:223], off
	s_waitcnt vmcnt(8)
	s_waitcnt lgkmcnt(0)
	s_barrier
; #define PG8_STAGE(bufoff, gbase, voff) do { _Pragma("unroll") for (int _i = 0; _i < 2; ++_i) \
;         __builtin_amdgcn_global_load_lds((const unsigned*)((const char*)(gbase) + (voff)[_i]), (LAS unsigned*)(lds + (bufoff) + ldsw + _i * 8192), 16, 0, 0); } while (0)
; #define PG8_LDA(dst, b, h) do { _Pragma("unroll") for (int m = 0; m < 4; ++m) _Pragma("unroll") for (int k = 0; k < 2; ++k) dst[m][k] = *(const LAS bf16x8*)(lds + PG8_SA(b, h) + aoff + m * 2048 + k * 1024); } while (0)
; #define PG8_LDB(dst, b, h) do { _Pragma("unroll") for (int n = 0; n < 2; ++n) _Pragma("unroll") for (int k = 0; k < 2; ++k) dst[n][k] = *(const LAS bf16x8*)(lds + PG8_SB(b, h) + boff + n * 2048 + k * 1024); } while (0)
; #define PG8_MMA(ai, bj, At, Bt) do { __builtin_amdgcn_s_setprio(1); _Pragma("unroll") for (int k = 0; k < 2; ++k) _Pragma("unroll") for (int m = 0; m < 4; ++m) _Pragma("unroll") for (int n = 0; n < 2; ++n) \
;         acc[ai][bj][m][n] = __builtin_amdgcn_mfma_f32_16x16x32_bf16(Bt[n][k], At[m][k], acc[ai][bj][m][n], 0, 0, 0); __builtin_amdgcn_s_setprio(0); } while (0)
; #define PG8_WAIT_V(n) asm volatile("s_waitcnt vmcnt(" #n ")" ::: "memory")
; #define PG8_WAIT_L(n) asm volatile("s_waitcnt lgkmcnt(" #n ")" ::: "memory")
; #define PG8_BAR __builtin_amdgcn_s_barrier()
; #define PG8_SCHED __builtin_amdgcn_sched_barrier(0)
; template <class Epi, bool ALIGN_EPI = PG8_ALIGN, bool SP2 = PG8_SP2>
; __device__ __forceinline__ void gemm_phase(LAS unsigned char* lds, const int tid, const int K, const Order& S, const Epi& E) {
;     ...
;             PG8_WAIT_V(8); PG8_WAIT_L(0); PG8_BAR; PG8_MMA(1, 0, At, B0); PG8_MMA(1, 1, At, B1); PG8_BAR; PG8_SCHED;
;             PG8_LDB(B0, 1, 0); PG8_LDB(B1, 1, 1); PG8_SCHED; PG8_LDA(At, 1, 0); PG8_STAGE(PG8_SA(0, 1), a2 + hstep, voffA);
;             PG8_WAIT_V(8); PG8_WAIT_L(0); PG8_BAR; PG8_MMA(0, 0, At, B0); PG8_MMA(0, 1, At, B1); PG8_BAR; PG8_SCHED;
	s_setprio 1
	s_waitcnt lgkmcnt(0)
	v_mfma_f32_16x16x32_bf16 v[60:63], v[142:145], v[182:185], v[60:63]
	v_mfma_f32_16x16x32_bf16 v[56:59], v[158:161], v[182:185], v[56:59]
	v_mfma_f32_16x16x32_bf16 v[44:47], v[142:145], v[190:193], v[44:47]
	v_mfma_f32_16x16x32_bf16 v[40:43], v[158:161], v[190:193], v[40:43]
	v_mfma_f32_16x16x32_bf16 v[28:31], v[142:145], v[198:201], v[28:31]
	v_mfma_f32_16x16x32_bf16 v[24:27], v[158:161], v[198:201], v[24:27]
	v_mfma_f32_16x16x32_bf16 v[12:15], v[142:145], v[206:209], v[12:15]
	v_mfma_f32_16x16x32_bf16 v[8:11], v[158:161], v[206:209], v[8:11]
	v_mfma_f32_16x16x32_bf16 v[60:63], v[154:157], v[186:189], v[60:63]
	v_mfma_f32_16x16x32_bf16 v[56:59], v[162:165], v[186:189], v[56:59]
	v_mfma_f32_16x16x32_bf16 v[44:47], v[154:157], v[194:197], v[44:47]
	v_mfma_f32_16x16x32_bf16 v[40:43], v[162:165], v[194:197], v[40:43]
	v_mfma_f32_16x16x32_bf16 v[28:31], v[154:157], v[202:205], v[28:31]
	v_mfma_f32_16x16x32_bf16 v[24:27], v[162:165], v[202:205], v[24:27]
	v_mfma_f32_16x16x32_bf16 v[12:15], v[154:157], v[210:213], v[12:15]
	v_mfma_f32_16x16x32_bf16 v[8:11], v[162:165], v[210:213], v[8:11]
	v_mfma_f32_16x16x32_bf16 v[52:55], v[166:169], v[182:185], v[52:55]
	v_mfma_f32_16x16x32_bf16 v[48:51], v[174:177], v[182:185], v[48:51]
	v_mfma_f32_16x16x32_bf16 v[36:39], v[166:169], v[190:193], v[36:39]
	v_mfma_f32_16x16x32_bf16 v[32:35], v[174:177], v[190:193], v[32:35]
	v_mfma_f32_16x16x32_bf16 v[20:23], v[166:169], v[198:201], v[20:23]
	v_mfma_f32_16x16x32_bf16 v[16:19], v[174:177], v[198:201], v[16:19]
	v_mfma_f32_16x16x32_bf16 v[4:7], v[166:169], v[206:209], v[4:7]
	v_mfma_f32_16x16x32_bf16 v[0:3], v[174:177], v[206:209], v[0:3]
	v_mfma_f32_16x16x32_bf16 v[52:55], v[170:173], v[186:189], v[52:55]
	v_mfma_f32_16x16x32_bf16 v[48:51], v[178:181], v[186:189], v[48:51]
	v_mfma_f32_16x16x32_bf16 v[36:39], v[170:173], v[194:197], v[36:39]
	v_mfma_f32_16x16x32_bf16 v[32:35], v[178:181], v[194:197], v[32:35]
	v_mfma_f32_16x16x32_bf16 v[20:23], v[170:173], v[202:205], v[20:23]
	v_mfma_f32_16x16x32_bf16 v[16:19], v[178:181], v[202:205], v[16:19]
	v_mfma_f32_16x16x32_bf16 v[4:7], v[170:173], v[210:213], v[4:7]
	v_mfma_f32_16x16x32_bf16 v[0:3], v[178:181], v[210:213], v[0:3]
	s_setprio 0
	s_barrier
	s_add_i32 s66, 0, 0x18000
	s_add_i32 s67, 0, 0x1c000
	v_add_u32_e32 v162, s66, v149
	v_add_u32_e32 v178, s67, v149
	ds_read_b128 v[142:145], v162
	ds_read_b128 v[154:157], v162 offset:1024
	ds_read_b128 v[158:161], v162 offset:2048
	ds_read_b128 v[162:165], v162 offset:3072
	ds_read_b128 v[166:169], v178
	ds_read_b128 v[170:173], v178 offset:1024
	ds_read_b128 v[174:177], v178 offset:2048
	ds_read_b128 v[178:181], v178 offset:3072
	s_add_u32 s44, s44, 0x80000
	s_addc_u32 s45, s45, 0
	s_mov_b32 m0, s51
	v_lshl_add_u64 v[224:225], s[44:45], 0, v[128:129]
	ds_read_b128 v[182:185], v153 offset:32768
	ds_read_b128 v[186:189], v153 offset:33792
	ds_read_b128 v[190:193], v153 offset:34816
	ds_read_b128 v[194:197], v153 offset:35840
	ds_read_b128 v[198:201], v153 offset:36864
	ds_read_b128 v[202:205], v153 offset:37888
	ds_read_b128 v[206:209], v153 offset:38912
	ds_read_b128 v[210:213], v153 offset:39936
	global_load_lds_dwordx4 v[224:225], off
	v_lshl_add_u64 v[224:225], s[44:45], 0, v[132:133]
	s_mov_b32 m0, s52
	s_nop 0
	global_load_lds_dwordx4 v[224:225], off
	s_waitcnt vmcnt(8)
	s_waitcnt lgkmcnt(0)
	s_barrier
	s_setprio 1
	s_waitcnt lgkmcnt(0)
	v_mfma_f32_16x16x32_bf16 v[124:127], v[142:145], v[182:185], v[124:127]
	v_mfma_f32_16x16x32_bf16 v[120:123], v[158:161], v[182:185], v[120:123]
	v_mfma_f32_16x16x32_bf16 v[108:111], v[142:145], v[190:193], v[108:111]
	v_mfma_f32_16x16x32_bf16 v[104:107], v[158:161], v[190:193], v[104:107]
	v_mfma_f32_16x16x32_bf16 v[92:95], v[142:145], v[198:201], v[92:95]
	v_mfma_f32_16x16x32_bf16 v[88:91], v[158:161], v[198:201], v[88:91]
	v_mfma_f32_16x16x32_bf16 v[76:79], v[142:145], v[206:209], v[76:79]
	v_mfma_f32_16x16x32_bf16 v[72:75], v[158:161], v[206:209], v[72:75]
	v_mfma_f32_16x16x32_bf16 v[124:127], v[154:157], v[186:189], v[124:127]
	v_mfma_f32_16x16x32_bf16 v[120:123], v[162:165], v[186:189], v[120:123]
	v_mfma_f32_16x16x32_bf16 v[108:111], v[154:157], v[194:197], v[108:111]
	v_mfma_f32_16x16x32_bf16 v[104:107], v[162:165], v[194:197], v[104:107]
	v_mfma_f32_16x16x32_bf16 v[92:95], v[154:157], v[202:205], v[92:95]
	v_mfma_f32_16x16x32_bf16 v[88:91], v[162:165], v[202:205], v[88:91]
	v_mfma_f32_16x16x32_bf16 v[76:79], v[154:157], v[210:213], v[76:79]
	v_mfma_f32_16x16x32_bf16 v[72:75], v[162:165], v[210:213], v[72:75]
	v_mfma_f32_16x16x32_bf16 v[116:119], v[166:169], v[182:185], v[116:119]
	v_mfma_f32_16x16x32_bf16 v[112:115], v[174:177], v[182:185], v[112:115]
	v_mfma_f32_16x16x32_bf16 v[100:103], v[166:169], v[190:193], v[100:103]
	v_mfma_f32_16x16x32_bf16 v[96:99], v[174:177], v[190:193], v[96:99]
	v_mfma_f32_16x16x32_bf16 v[84:87], v[166:169], v[198:201], v[84:87]
	v_mfma_f32_16x16x32_bf16 v[80:83], v[174:177], v[198:201], v[80:83]
	v_mfma_f32_16x16x32_bf16 v[68:71], v[166:169], v[206:209], v[68:71]
	v_mfma_f32_16x16x32_bf16 v[64:67], v[174:177], v[206:209], v[64:67]
	v_mfma_f32_16x16x32_bf16 v[116:119], v[170:173], v[186:189], v[116:119]
	v_mfma_f32_16x16x32_bf16 v[112:115], v[178:181], v[186:189], v[112:115]
	v_mfma_f32_16x16x32_bf16 v[100:103], v[170:173], v[194:197], v[100:103]
	v_mfma_f32_16x16x32_bf16 v[96:99], v[178:181], v[194:197], v[96:99]
	v_mfma_f32_16x16x32_bf16 v[84:87], v[170:173], v[202:205], v[84:87]
	v_mfma_f32_16x16x32_bf16 v[80:83], v[178:181], v[202:205], v[80:83]
	v_mfma_f32_16x16x32_bf16 v[68:71], v[170:173], v[210:213], v[68:71]
	v_mfma_f32_16x16x32_bf16 v[64:67], v[178:181], v[210:213], v[64:67]
	s_setprio 0
	s_barrier
; #define PG8_STAGE(bufoff, gbase, voff) do { _Pragma("unroll") for (int _i = 0; _i < 2; ++_i) \
;         __builtin_amdgcn_global_load_lds((const unsigned*)((const char*)(gbase) + (voff)[_i]), (LAS unsigned*)(lds + (bufoff) + ldsw + _i * 8192), 16, 0, 0); } while (0)
; #define PG8_LDA(dst, b, h) do { _Pragma("unroll") for (int m = 0; m < 4; ++m) _Pragma("unroll") for (int k = 0; k < 2; ++k) dst[m][k] = *(const LAS bf16x8*)(lds + PG8_SA(b, h) + aoff + m * 2048 + k * 1024); } while (0)
; #define PG8_MMA(ai, bj, At, Bt) do { __builtin_amdgcn_s_setprio(1); _Pragma("unroll") for (int k = 0; k < 2; ++k) _Pragma("unroll") for (int m = 0; m < 4; ++m) _Pragma("unroll") for (int n = 0; n < 2; ++n) \
;         acc[ai][bj][m][n] = __builtin_amdgcn_mfma_f32_16x16x32_bf16(Bt[n][k], At[m][k], acc[ai][bj][m][n], 0, 0, 0); __builtin_amdgcn_s_setprio(0); } while (0)
; #define PG8_WAIT_V(n) asm volatile("s_waitcnt vmcnt(" #n ")" ::: "memory")
; #define PG8_WAIT_L(n) asm volatile("s_waitcnt lgkmcnt(" #n ")" ::: "memory")
; #define PG8_BAR __builtin_amdgcn_s_barrier()
; #define PG8_SCHED __builtin_amdgcn_sched_barrier(0)
; template <class Epi, bool ALIGN_EPI = PG8_ALIGN, bool SP2 = PG8_SP2>
; __device__ __forceinline__ void gemm_phase(LAS unsigned char* lds, const int tid, const int K, const Order& S, const Epi& E) {
;     ...
;             PG8_LDA(At, 1, 1); PG8_STAGE(PG8_SB(1, 0), b3, voffB); PG8_STAGE(PG8_SB(1, 1), b3 + hstep, voffB); PG8_STAGE(PG8_SA(1, 0), a3, voffA);
;             PG8_WAIT_V(8); PG8_WAIT_L(0); PG8_BAR; PG8_MMA(1, 0, At, B0); PG8_MMA(1, 1, At, B1); PG8_BAR; PG8_SCHED;
;     ...
;         }
;         if constexpr (ALIGN_EPI) { if (wr == 0) PG8_BAR; }
	s_add_i32 s44, s66, s49
	v_lshl_add_u64 v[214:215], v[214:215], 0, s[18:19]
	s_mov_b32 m0, s44
	ds_read_b128 v[182:185], v153 offset:49152
	ds_read_b128 v[186:189], v153 offset:50176
	ds_read_b128 v[190:193], v153 offset:51200
	ds_read_b128 v[194:197], v153 offset:52224
	ds_read_b128 v[198:201], v153 offset:53248
	ds_read_b128 v[202:205], v153 offset:54272
	ds_read_b128 v[206:209], v153 offset:55296
	ds_read_b128 v[210:213], v153 offset:56320
	global_load_lds_dwordx4 v[214:215], off
	s_add_i32 m0, s44, 0x2000
	s_add_u32 s42, s42, 0x80080
	v_lshl_add_u64 v[214:215], v[218:219], 0, s[18:19]
	s_addc_u32 s43, s43, 0
	s_add_i32 s44, s67, s49
	global_load_lds_dwordx4 v[214:215], off
	v_lshl_add_u64 v[214:215], s[42:43], 0, v[130:131]
	s_mov_b32 m0, s44
	s_nop 0
	global_load_lds_dwordx4 v[214:215], off
	v_lshl_add_u64 v[214:215], s[42:43], 0, v[134:135]
	s_add_i32 m0, s44, 0x2000
	s_nop 0
	global_load_lds_dwordx4 v[214:215], off
	v_lshl_add_u64 v[214:215], v[220:221], 0, s[18:19]
	s_mov_b32 m0, s54
	s_nop 0
	global_load_lds_dwordx4 v[214:215], off
	v_lshl_add_u64 v[214:215], v[222:223], 0, s[18:19]
	s_mov_b32 m0, s55
	s_nop 0
	global_load_lds_dwordx4 v[214:215], off
	s_waitcnt vmcnt(8)
	s_waitcnt lgkmcnt(0)
	s_barrier
	s_setprio 1
	s_waitcnt lgkmcnt(0)
	v_mfma_f32_16x16x32_bf16 v[60:63], v[142:145], v[182:185], v[60:63]
	v_mfma_f32_16x16x32_bf16 v[56:59], v[158:161], v[182:185], v[56:59]
	v_mfma_f32_16x16x32_bf16 v[44:47], v[142:145], v[190:193], v[44:47]
	v_mfma_f32_16x16x32_bf16 v[40:43], v[158:161], v[190:193], v[40:43]
	v_mfma_f32_16x16x32_bf16 v[28:31], v[142:145], v[198:201], v[28:31]
	v_mfma_f32_16x16x32_bf16 v[24:27], v[158:161], v[198:201], v[24:27]
	v_mfma_f32_16x16x32_bf16 v[12:15], v[142:145], v[206:209], v[12:15]
	v_mfma_f32_16x16x32_bf16 v[8:11], v[158:161], v[206:209], v[8:11]
	v_mfma_f32_16x16x32_bf16 v[60:63], v[154:157], v[186:189], v[60:63]
	v_mfma_f32_16x16x32_bf16 v[56:59], v[162:165], v[186:189], v[56:59]
	v_mfma_f32_16x16x32_bf16 v[44:47], v[154:157], v[194:197], v[44:47]
	v_mfma_f32_16x16x32_bf16 v[40:43], v[162:165], v[194:197], v[40:43]
	v_mfma_f32_16x16x32_bf16 v[28:31], v[154:157], v[202:205], v[28:31]
	v_mfma_f32_16x16x32_bf16 v[24:27], v[162:165], v[202:205], v[24:27]
	v_mfma_f32_16x16x32_bf16 v[12:15], v[154:157], v[210:213], v[12:15]
	v_mfma_f32_16x16x32_bf16 v[8:11], v[162:165], v[210:213], v[8:11]
	v_mfma_f32_16x16x32_bf16 v[52:55], v[166:169], v[182:185], v[52:55]
	v_mfma_f32_16x16x32_bf16 v[48:51], v[174:177], v[182:185], v[48:51]
	v_mfma_f32_16x16x32_bf16 v[36:39], v[166:169], v[190:193], v[36:39]
	v_mfma_f32_16x16x32_bf16 v[32:35], v[174:177], v[190:193], v[32:35]
	v_mfma_f32_16x16x32_bf16 v[20:23], v[166:169], v[198:201], v[20:23]
	v_mfma_f32_16x16x32_bf16 v[16:19], v[174:177], v[198:201], v[16:19]
	v_mfma_f32_16x16x32_bf16 v[4:7], v[166:169], v[206:209], v[4:7]
	v_mfma_f32_16x16x32_bf16 v[0:3], v[174:177], v[206:209], v[0:3]
	v_mfma_f32_16x16x32_bf16 v[52:55], v[170:173], v[186:189], v[52:55]
	v_mfma_f32_16x16x32_bf16 v[48:51], v[178:181], v[186:189], v[48:51]
	v_mfma_f32_16x16x32_bf16 v[36:39], v[170:173], v[194:197], v[36:39]
	v_mfma_f32_16x16x32_bf16 v[32:35], v[178:181], v[194:197], v[32:35]
	v_mfma_f32_16x16x32_bf16 v[20:23], v[170:173], v[202:205], v[20:23]
	v_mfma_f32_16x16x32_bf16 v[16:19], v[178:181], v[202:205], v[16:19]
	v_mfma_f32_16x16x32_bf16 v[4:7], v[170:173], v[210:213], v[4:7]
	v_mfma_f32_16x16x32_bf16 v[0:3], v[178:181], v[210:213], v[0:3]
	s_setprio 0
	s_barrier
	s_add_i32 s65, s65, 2
	s_add_u32 s63, s63, 0x100
	s_addc_u32 s64, s64, 0
	s_add_u32 s34, s34, 0x100
	s_addc_u32 s35, s35, 0
	s_cmp_gt_u32 s65, 29
	s_cbranch_scc0 .LBB0_265
	s_and_b64 vcc, exec, s[20:21]
	s_cbranch_vccz .LBB0_268
	s_barrier

;     __device__ __forceinline__ int nt(const Unit& u) const { return (u.ks < 0 || xsplit == 1) ? ntf : sbase + (u.ks >= sthr ? 2 : 0); }
; #define PG8_STAGE(bufoff, gbase, voff) do { _Pragma("unroll") for (int _i = 0; _i < 2; ++_i) \
;         __builtin_amdgcn_global_load_lds((const unsigned*)((const char*)(gbase) + (voff)[_i]), (LAS unsigned*)(lds + (bufoff) + ldsw + _i * 8192), 16, 0, 0); } while (0)
; #define PG8_LDA(dst, b, h) do { _Pragma("unroll") for (int m = 0; m < 4; ++m) _Pragma("unroll") for (int k = 0; k < 2; ++k) dst[m][k] = *(const LAS bf16x8*)(lds + PG8_SA(b, h) + aoff + m * 2048 + k * 1024); } while (0)
; #define PG8_LDB(dst, b, h) do { _Pragma("unroll") for (int n = 0; n < 2; ++n) _Pragma("unroll") for (int k = 0; k < 2; ++k) dst[n][k] = *(const LAS bf16x8*)(lds + PG8_SB(b, h) + boff + n * 2048 + k * 1024); } while (0)
; #define PG8_MMA(ai, bj, At, Bt) do { __builtin_amdgcn_s_setprio(1); _Pragma("unroll") for (int k = 0; k < 2; ++k) _Pragma("unroll") for (int m = 0; m < 4; ++m) _Pragma("unroll") for (int n = 0; n < 2; ++n) \
;         acc[ai][bj][m][n] = __builtin_amdgcn_mfma_f32_16x16x32_bf16(Bt[n][k], At[m][k], acc[ai][bj][m][n], 0, 0, 0); __builtin_amdgcn_s_setprio(0); } while (0)
; #define PG8_BAR __builtin_amdgcn_s_barrier()
; template <class Epi, bool ALIGN_EPI = PG8_ALIGN, bool SP2 = PG8_SP2>
; __device__ __forceinline__ void gemm_phase(LAS unsigned char* lds, const int tid, const int K, const Order& S, const Epi& E) {
;     ...
;             const bool last = (t == nt - 2);
;             const char* a1 = cA + (size_t)(t + 1) * kstep;
;             const char* a2 = last ? nA : cA + (size_t)(t + 2) * kstep; const char* b2 = last ? nB : cB + (size_t)(t + 2) * kstep;
;             const char* a3 = a2 + kstep; const char* b3 = b2 + kstep;
;             if (last && has_next) S.a_ready(nxt, tid);
;             if constexpr (SP2) {
;             PG8_LDB(B0, 0, 0); PG8_LDB(B1, 0, 1); PG8_SCHED; PG8_LDA(At, 0, 0); PG8_STAGE(PG8_SA(1, 1), a1 + hstep, voffA);
;             PG8_WAIT_V(8); PG8_WAIT_L(0); PG8_BAR; PG8_MMA(0, 0, At, B0); PG8_MMA(0, 1, At, B1); PG8_BAR; PG8_SCHED;
;             PG8_LDA(At, 0, 1); PG8_STAGE(PG8_SB(0, 0), b2, voffB); PG8_STAGE(PG8_SB(0, 1), b2 + hstep, voffB); PG8_STAGE(PG8_SA(0, 0), a2, voffA);
;             PG8_WAIT_V(8); PG8_WAIT_L(0); PG8_BAR; PG8_MMA(1, 0, At, B0); PG8_MMA(1, 1, At, B1); PG8_BAR; PG8_SCHED;
.LBB0_541:
	v_add_u32_e32 v140, s72, v220
	v_add_u32_e32 v156, s73, v220
	ds_read_b128 v[128:131], v140
	ds_read_b128 v[132:135], v140 offset:1024
	ds_read_b128 v[136:139], v140 offset:2048
	ds_read_b128 v[140:143], v140 offset:3072
	ds_read_b128 v[144:147], v156
	ds_read_b128 v[148:151], v156 offset:1024
	ds_read_b128 v[152:155], v156 offset:2048
	ds_read_b128 v[156:159], v156 offset:3072
	s_add_u32 s48, s46, 0xfffc0080
	s_addc_u32 s49, s47, -1
	s_cmp_eq_u32 s45, 12
	s_cselect_b32 s55, s31, s49
	s_cselect_b32 s54, s30, s48
	s_cselect_b32 s49, s23, s29
	s_cselect_b32 s48, s25, s27
	v_lshl_add_u64 v[206:207], s[46:47], 0, v[202:203]
	s_add_i32 m0, s61, 0xc000
	ds_read_b128 v[160:163], v222
	ds_read_b128 v[164:167], v222 offset:1024
	ds_read_b128 v[168:171], v222 offset:2048
	ds_read_b128 v[172:175], v222 offset:3072
	ds_read_b128 v[176:179], v222 offset:4096
	ds_read_b128 v[180:183], v222 offset:5120
	ds_read_b128 v[184:187], v222 offset:6144
	ds_read_b128 v[188:191], v222 offset:7168
	global_load_lds_dwordx4 v[206:207], off
	v_lshl_add_u64 v[206:207], s[46:47], 0, v[200:201]
	s_add_i32 m0, s61, 0xe000
	s_nop 0
	global_load_lds_dwordx4 v[206:207], off
	s_waitcnt vmcnt(8)
	s_waitcnt lgkmcnt(0)
	s_barrier
	s_setprio 1
	s_waitcnt lgkmcnt(0)
	v_mfma_f32_16x16x32_bf16 v[124:127], v[128:131], v[160:163], v[124:127]
	v_mfma_f32_16x16x32_bf16 v[120:123], v[136:139], v[160:163], v[120:123]
	v_mfma_f32_16x16x32_bf16 v[116:119], v[128:131], v[168:171], v[116:119]
	v_mfma_f32_16x16x32_bf16 v[112:115], v[136:139], v[168:171], v[112:115]
	v_mfma_f32_16x16x32_bf16 v[108:111], v[128:131], v[176:179], v[108:111]
	v_mfma_f32_16x16x32_bf16 v[104:107], v[136:139], v[176:179], v[104:107]
	v_mfma_f32_16x16x32_bf16 v[100:103], v[128:131], v[184:187], v[100:103]
	v_mfma_f32_16x16x32_bf16 v[96:99], v[136:139], v[184:187], v[96:99]
	v_mfma_f32_16x16x32_bf16 v[124:127], v[132:135], v[164:167], v[124:127]
	v_mfma_f32_16x16x32_bf16 v[120:123], v[140:143], v[164:167], v[120:123]
	v_mfma_f32_16x16x32_bf16 v[116:119], v[132:135], v[172:175], v[116:119]
	v_mfma_f32_16x16x32_bf16 v[112:115], v[140:143], v[172:175], v[112:115]
	v_mfma_f32_16x16x32_bf16 v[108:111], v[132:135], v[180:183], v[108:111]
	v_mfma_f32_16x16x32_bf16 v[104:107], v[140:143], v[180:183], v[104:107]
	v_mfma_f32_16x16x32_bf16 v[100:103], v[132:135], v[188:191], v[100:103]
	v_mfma_f32_16x16x32_bf16 v[96:99], v[140:143], v[188:191], v[96:99]
	v_mfma_f32_16x16x32_bf16 v[92:95], v[144:147], v[160:163], v[92:95]
	v_mfma_f32_16x16x32_bf16 v[88:91], v[152:155], v[160:163], v[88:91]
	v_mfma_f32_16x16x32_bf16 v[84:87], v[144:147], v[168:171], v[84:87]
	v_mfma_f32_16x16x32_bf16 v[80:83], v[152:155], v[168:171], v[80:83]
	v_mfma_f32_16x16x32_bf16 v[76:79], v[144:147], v[176:179], v[76:79]
	v_mfma_f32_16x16x32_bf16 v[72:75], v[152:155], v[176:179], v[72:75]
	v_mfma_f32_16x16x32_bf16 v[68:71], v[144:147], v[184:187], v[68:71]
	v_mfma_f32_16x16x32_bf16 v[64:67], v[152:155], v[184:187], v[64:67]
	v_mfma_f32_16x16x32_bf16 v[92:95], v[148:151], v[164:167], v[92:95]
	v_mfma_f32_16x16x32_bf16 v[88:91], v[156:159], v[164:167], v[88:91]
	v_mfma_f32_16x16x32_bf16 v[84:87], v[148:151], v[172:175], v[84:87]
	v_mfma_f32_16x16x32_bf16 v[80:83], v[156:159], v[172:175], v[80:83]
	v_mfma_f32_16x16x32_bf16 v[76:79], v[148:151], v[180:183], v[76:79]
	v_mfma_f32_16x16x32_bf16 v[72:75], v[156:159], v[180:183], v[72:75]
	v_mfma_f32_16x16x32_bf16 v[68:71], v[148:151], v[188:191], v[68:71]
	v_mfma_f32_16x16x32_bf16 v[64:67], v[156:159], v[188:191], v[64:67]
	s_setprio 0
	s_barrier
	s_add_i32 s51, s72, s60
	v_lshl_add_u64 v[206:207], s[48:49], 0, v[194:195]
	s_mov_b32 m0, s51
	ds_read_b128 v[160:163], v222 offset:16384
	ds_read_b128 v[164:167], v222 offset:17408
	ds_read_b128 v[168:171], v222 offset:18432
	ds_read_b128 v[172:175], v222 offset:19456
	ds_read_b128 v[176:179], v222 offset:20480
	ds_read_b128 v[180:183], v222 offset:21504
	ds_read_b128 v[184:187], v222 offset:22528
	ds_read_b128 v[188:191], v222 offset:23552
	global_load_lds_dwordx4 v[206:207], off
	s_add_i32 m0, s51, 0x2000
	s_add_u32 s92, s48, 0x40000
	v_lshl_add_u64 v[208:209], s[48:49], 0, v[198:199]
	s_addc_u32 s93, s49, 0
	s_add_i32 s51, s73, s60
	global_load_lds_dwordx4 v[208:209], off
	v_lshl_add_u64 v[212:213], s[92:93], 0, v[194:195]
	s_mov_b32 m0, s51
	v_lshl_add_u64 v[214:215], s[54:55], 0, v[196:197]
	global_load_lds_dwordx4 v[212:213], off
	v_lshl_add_u64 v[212:213], s[92:93], 0, v[198:199]
	s_add_i32 m0, s51, 0x2000
	s_nop 0
	global_load_lds_dwordx4 v[212:213], off
	v_lshl_add_u64 v[212:213], s[54:55], 0, v[192:193]
	s_mov_b32 m0, s61
	s_nop 0
	global_load_lds_dwordx4 v[212:213], off
	s_mov_b32 m0, s62
	s_nop 0
	global_load_lds_dwordx4 v[214:215], off
	s_waitcnt vmcnt(8)
	s_waitcnt lgkmcnt(0)
	s_barrier
; #define PG8_STAGE(bufoff, gbase, voff) do { _Pragma("unroll") for (int _i = 0; _i < 2; ++_i) \
;         __builtin_amdgcn_global_load_lds((const unsigned*)((const char*)(gbase) + (voff)[_i]), (LAS unsigned*)(lds + (bufoff) + ldsw + _i * 8192), 16, 0, 0); } while (0)
; #define PG8_LDA(dst, b, h) do { _Pragma("unroll") for (int m = 0; m < 4; ++m) _Pragma("unroll") for (int k = 0; k < 2; ++k) dst[m][k] = *(const LAS bf16x8*)(lds + PG8_SA(b, h) + aoff + m * 2048 + k * 1024); } while (0)
; #define PG8_LDB(dst, b, h) do { _Pragma("unroll") for (int n = 0; n < 2; ++n) _Pragma("unroll") for (int k = 0; k < 2; ++k) dst[n][k] = *(const LAS bf16x8*)(lds + PG8_SB(b, h) + boff + n * 2048 + k * 1024); } while (0)
; #define PG8_MMA(ai, bj, At, Bt) do { __builtin_amdgcn_s_setprio(1); _Pragma("unroll") for (int k = 0; k < 2; ++k) _Pragma("unroll") for (int m = 0; m < 4; ++m) _Pragma("unroll") for (int n = 0; n < 2; ++n) \
;         acc[ai][bj][m][n] = __builtin_amdgcn_mfma_f32_16x16x32_bf16(Bt[n][k], At[m][k], acc[ai][bj][m][n], 0, 0, 0); __builtin_amdgcn_s_setprio(0); } while (0)
; #define PG8_WAIT_V(n) asm volatile("s_waitcnt vmcnt(" #n ")" ::: "memory")
; #define PG8_WAIT_L(n) asm volatile("s_waitcnt lgkmcnt(" #n ")" ::: "memory")
; #define PG8_BAR __builtin_amdgcn_s_barrier()
; #define PG8_SCHED __builtin_amdgcn_sched_barrier(0)
; template <class Epi, bool ALIGN_EPI = PG8_ALIGN, bool SP2 = PG8_SP2>
; __device__ __forceinline__ void gemm_phase(LAS unsigned char* lds, const int tid, const int K, const Order& S, const Epi& E) {
;     ...
;             PG8_WAIT_V(8); PG8_WAIT_L(0); PG8_BAR; PG8_MMA(1, 0, At, B0); PG8_MMA(1, 1, At, B1); PG8_BAR; PG8_SCHED;
;             PG8_LDB(B0, 1, 0); PG8_LDB(B1, 1, 1); PG8_SCHED; PG8_LDA(At, 1, 0); PG8_STAGE(PG8_SA(0, 1), a2 + hstep, voffA);
;             PG8_WAIT_V(8); PG8_WAIT_L(0); PG8_BAR; PG8_MMA(0, 0, At, B0); PG8_MMA(0, 1, At, B1); PG8_BAR; PG8_SCHED;
	s_setprio 1
	s_waitcnt lgkmcnt(0)
	v_mfma_f32_16x16x32_bf16 v[60:63], v[128:131], v[160:163], v[60:63]
	v_mfma_f32_16x16x32_bf16 v[56:59], v[136:139], v[160:163], v[56:59]
	v_mfma_f32_16x16x32_bf16 v[52:55], v[128:131], v[168:171], v[52:55]
	v_mfma_f32_16x16x32_bf16 v[48:51], v[136:139], v[168:171], v[48:51]
	v_mfma_f32_16x16x32_bf16 v[44:47], v[128:131], v[176:179], v[44:47]
	v_mfma_f32_16x16x32_bf16 v[40:43], v[136:139], v[176:179], v[40:43]
	v_mfma_f32_16x16x32_bf16 v[36:39], v[128:131], v[184:187], v[36:39]
	v_mfma_f32_16x16x32_bf16 v[32:35], v[136:139], v[184:187], v[32:35]
	v_mfma_f32_16x16x32_bf16 v[60:63], v[132:135], v[164:167], v[60:63]
	v_mfma_f32_16x16x32_bf16 v[56:59], v[140:143], v[164:167], v[56:59]
	v_mfma_f32_16x16x32_bf16 v[52:55], v[132:135], v[172:175], v[52:55]
	v_mfma_f32_16x16x32_bf16 v[48:51], v[140:143], v[172:175], v[48:51]
	v_mfma_f32_16x16x32_bf16 v[44:47], v[132:135], v[180:183], v[44:47]
	v_mfma_f32_16x16x32_bf16 v[40:43], v[140:143], v[180:183], v[40:43]
	v_mfma_f32_16x16x32_bf16 v[36:39], v[132:135], v[188:191], v[36:39]
	v_mfma_f32_16x16x32_bf16 v[32:35], v[140:143], v[188:191], v[32:35]
	v_mfma_f32_16x16x32_bf16 v[28:31], v[144:147], v[160:163], v[28:31]
	v_mfma_f32_16x16x32_bf16 v[24:27], v[152:155], v[160:163], v[24:27]
	v_mfma_f32_16x16x32_bf16 v[20:23], v[144:147], v[168:171], v[20:23]
	v_mfma_f32_16x16x32_bf16 v[16:19], v[152:155], v[168:171], v[16:19]
	v_mfma_f32_16x16x32_bf16 v[12:15], v[144:147], v[176:179], v[12:15]
	v_mfma_f32_16x16x32_bf16 v[8:11], v[152:155], v[176:179], v[8:11]
	v_mfma_f32_16x16x32_bf16 v[4:7], v[144:147], v[184:187], v[4:7]
	v_mfma_f32_16x16x32_bf16 v[0:3], v[152:155], v[184:187], v[0:3]
	v_mfma_f32_16x16x32_bf16 v[28:31], v[148:151], v[164:167], v[28:31]
	v_mfma_f32_16x16x32_bf16 v[24:27], v[156:159], v[164:167], v[24:27]
	v_mfma_f32_16x16x32_bf16 v[20:23], v[148:151], v[172:175], v[20:23]
	v_mfma_f32_16x16x32_bf16 v[16:19], v[156:159], v[172:175], v[16:19]
	v_mfma_f32_16x16x32_bf16 v[12:15], v[148:151], v[180:183], v[12:15]
	v_mfma_f32_16x16x32_bf16 v[8:11], v[156:159], v[180:183], v[8:11]
	v_mfma_f32_16x16x32_bf16 v[4:7], v[148:151], v[188:191], v[4:7]
	v_mfma_f32_16x16x32_bf16 v[0:3], v[156:159], v[188:191], v[0:3]
	s_setprio 0
	s_barrier
	s_add_i32 s51, 0, 0x18000
	s_add_i32 s53, 0, 0x1c000
	v_add_u32_e32 v140, s51, v220
	v_add_u32_e32 v156, s53, v220
	ds_read_b128 v[128:131], v140
	ds_read_b128 v[132:135], v140 offset:1024
	ds_read_b128 v[136:139], v140 offset:2048
	ds_read_b128 v[140:143], v140 offset:3072
	ds_read_b128 v[144:147], v156
	ds_read_b128 v[148:151], v156 offset:1024
	ds_read_b128 v[152:155], v156 offset:2048
	ds_read_b128 v[156:159], v156 offset:3072
	s_add_u32 s54, s54, 0x40000
	s_addc_u32 s55, s55, 0
	s_mov_b32 m0, s63
	v_lshl_add_u64 v[224:225], s[54:55], 0, v[192:193]
	ds_read_b128 v[160:163], v222 offset:32768
	ds_read_b128 v[164:167], v222 offset:33792
	ds_read_b128 v[168:171], v222 offset:34816
	ds_read_b128 v[172:175], v222 offset:35840
	ds_read_b128 v[176:179], v222 offset:36864
	ds_read_b128 v[180:183], v222 offset:37888
	ds_read_b128 v[184:187], v222 offset:38912
	ds_read_b128 v[188:191], v222 offset:39936
	global_load_lds_dwordx4 v[224:225], off
	v_lshl_add_u64 v[224:225], s[54:55], 0, v[196:197]
	s_mov_b32 m0, s64
	s_nop 0
	global_load_lds_dwordx4 v[224:225], off
	s_waitcnt vmcnt(8)
	s_waitcnt lgkmcnt(0)
	s_barrier
	s_setprio 1
	s_waitcnt lgkmcnt(0)
	v_mfma_f32_16x16x32_bf16 v[124:127], v[128:131], v[160:163], v[124:127]
	v_mfma_f32_16x16x32_bf16 v[120:123], v[136:139], v[160:163], v[120:123]
	v_mfma_f32_16x16x32_bf16 v[116:119], v[128:131], v[168:171], v[116:119]
	v_mfma_f32_16x16x32_bf16 v[112:115], v[136:139], v[168:171], v[112:115]
	v_mfma_f32_16x16x32_bf16 v[108:111], v[128:131], v[176:179], v[108:111]
	v_mfma_f32_16x16x32_bf16 v[104:107], v[136:139], v[176:179], v[104:107]
	v_mfma_f32_16x16x32_bf16 v[100:103], v[128:131], v[184:187], v[100:103]
	v_mfma_f32_16x16x32_bf16 v[96:99], v[136:139], v[184:187], v[96:99]
	v_mfma_f32_16x16x32_bf16 v[124:127], v[132:135], v[164:167], v[124:127]
	v_mfma_f32_16x16x32_bf16 v[120:123], v[140:143], v[164:167], v[120:123]
	v_mfma_f32_16x16x32_bf16 v[116:119], v[132:135], v[172:175], v[116:119]
	v_mfma_f32_16x16x32_bf16 v[112:115], v[140:143], v[172:175], v[112:115]
	v_mfma_f32_16x16x32_bf16 v[108:111], v[132:135], v[180:183], v[108:111]
	v_mfma_f32_16x16x32_bf16 v[104:107], v[140:143], v[180:183], v[104:107]
	v_mfma_f32_16x16x32_bf16 v[100:103], v[132:135], v[188:191], v[100:103]
	v_mfma_f32_16x16x32_bf16 v[96:99], v[140:143], v[188:191], v[96:99]
	v_mfma_f32_16x16x32_bf16 v[92:95], v[144:147], v[160:163], v[92:95]
	v_mfma_f32_16x16x32_bf16 v[88:91], v[152:155], v[160:163], v[88:91]
	v_mfma_f32_16x16x32_bf16 v[84:87], v[144:147], v[168:171], v[84:87]
	v_mfma_f32_16x16x32_bf16 v[80:83], v[152:155], v[168:171], v[80:83]
	v_mfma_f32_16x16x32_bf16 v[76:79], v[144:147], v[176:179], v[76:79]
	v_mfma_f32_16x16x32_bf16 v[72:75], v[152:155], v[176:179], v[72:75]
	v_mfma_f32_16x16x32_bf16 v[68:71], v[144:147], v[184:187], v[68:71]
	v_mfma_f32_16x16x32_bf16 v[64:67], v[152:155], v[184:187], v[64:67]
	v_mfma_f32_16x16x32_bf16 v[92:95], v[148:151], v[164:167], v[92:95]
	v_mfma_f32_16x16x32_bf16 v[88:91], v[156:159], v[164:167], v[88:91]
	v_mfma_f32_16x16x32_bf16 v[84:87], v[148:151], v[172:175], v[84:87]
	v_mfma_f32_16x16x32_bf16 v[80:83], v[156:159], v[172:175], v[80:83]
	v_mfma_f32_16x16x32_bf16 v[76:79], v[148:151], v[180:183], v[76:79]
	v_mfma_f32_16x16x32_bf16 v[72:75], v[156:159], v[180:183], v[72:75]
	v_mfma_f32_16x16x32_bf16 v[68:71], v[148:151], v[188:191], v[68:71]
	v_mfma_f32_16x16x32_bf16 v[64:67], v[156:159], v[188:191], v[64:67]
	s_setprio 0
	s_barrier
; #define PG8_STAGE(bufoff, gbase, voff) do { _Pragma("unroll") for (int _i = 0; _i < 2; ++_i) \
;         __builtin_amdgcn_global_load_lds((const unsigned*)((const char*)(gbase) + (voff)[_i]), (LAS unsigned*)(lds + (bufoff) + ldsw + _i * 8192), 16, 0, 0); } while (0)
; #define PG8_LDA(dst, b, h) do { _Pragma("unroll") for (int m = 0; m < 4; ++m) _Pragma("unroll") for (int k = 0; k < 2; ++k) dst[m][k] = *(const LAS bf16x8*)(lds + PG8_SA(b, h) + aoff + m * 2048 + k * 1024); } while (0)
; #define PG8_MMA(ai, bj, At, Bt) do { __builtin_amdgcn_s_setprio(1); _Pragma("unroll") for (int k = 0; k < 2; ++k) _Pragma("unroll") for (int m = 0; m < 4; ++m) _Pragma("unroll") for (int n = 0; n < 2; ++n) \
;         acc[ai][bj][m][n] = __builtin_amdgcn_mfma_f32_16x16x32_bf16(Bt[n][k], At[m][k], acc[ai][bj][m][n], 0, 0, 0); __builtin_amdgcn_s_setprio(0); } while (0)
; #define PG8_WAIT_V(n) asm volatile("s_waitcnt vmcnt(" #n ")" ::: "memory")
; #define PG8_WAIT_L(n) asm volatile("s_waitcnt lgkmcnt(" #n ")" ::: "memory")
; #define PG8_BAR __builtin_amdgcn_s_barrier()
; #define PG8_SCHED __builtin_amdgcn_sched_barrier(0)
; template <class Epi, bool ALIGN_EPI = PG8_ALIGN, bool SP2 = PG8_SP2>
; __device__ __forceinline__ void gemm_phase(LAS unsigned char* lds, const int tid, const int K, const Order& S, const Epi& E) {
;     ...
;             PG8_LDA(At, 1, 1); PG8_STAGE(PG8_SB(1, 0), b3, voffB); PG8_STAGE(PG8_SB(1, 1), b3 + hstep, voffB); PG8_STAGE(PG8_SA(1, 0), a3, voffA);
;             PG8_WAIT_V(8); PG8_WAIT_L(0); PG8_BAR; PG8_MMA(1, 0, At, B0); PG8_MMA(1, 1, At, B1); PG8_BAR; PG8_SCHED;
;     ...
;         }
;         if constexpr (ALIGN_EPI) { if (wr == 0) PG8_BAR; }
	s_add_i32 s51, s51, s60
	v_lshl_add_u64 v[206:207], v[206:207], 0, s[14:15]
	s_mov_b32 m0, s51
	ds_read_b128 v[160:163], v222 offset:49152
	ds_read_b128 v[164:167], v222 offset:50176
	ds_read_b128 v[168:171], v222 offset:51200
	ds_read_b128 v[172:175], v222 offset:52224
	ds_read_b128 v[176:179], v222 offset:53248
	ds_read_b128 v[180:183], v222 offset:54272
	ds_read_b128 v[184:187], v222 offset:55296
	ds_read_b128 v[188:191], v222 offset:56320
	global_load_lds_dwordx4 v[206:207], off
	s_add_i32 m0, s51, 0x2000
	s_add_u32 s48, s48, 0x40080
	v_lshl_add_u64 v[206:207], v[208:209], 0, s[14:15]
	s_addc_u32 s49, s49, 0
	s_add_i32 s51, s53, s60
	global_load_lds_dwordx4 v[206:207], off
	v_lshl_add_u64 v[206:207], s[48:49], 0, v[194:195]
	s_mov_b32 m0, s51
	s_nop 0
	global_load_lds_dwordx4 v[206:207], off
	v_lshl_add_u64 v[206:207], s[48:49], 0, v[198:199]
	s_add_i32 m0, s51, 0x2000
	s_nop 0
	global_load_lds_dwordx4 v[206:207], off
	v_lshl_add_u64 v[206:207], v[212:213], 0, s[14:15]
	s_mov_b32 m0, s69
	s_nop 0
	global_load_lds_dwordx4 v[206:207], off
	v_lshl_add_u64 v[206:207], v[214:215], 0, s[14:15]
	s_mov_b32 m0, s70
	s_nop 0
	global_load_lds_dwordx4 v[206:207], off
	s_waitcnt vmcnt(8)
	s_waitcnt lgkmcnt(0)
	s_barrier
	s_setprio 1
	s_waitcnt lgkmcnt(0)
	v_mfma_f32_16x16x32_bf16 v[60:63], v[128:131], v[160:163], v[60:63]
	v_mfma_f32_16x16x32_bf16 v[56:59], v[136:139], v[160:163], v[56:59]
	v_mfma_f32_16x16x32_bf16 v[52:55], v[128:131], v[168:171], v[52:55]
	v_mfma_f32_16x16x32_bf16 v[48:51], v[136:139], v[168:171], v[48:51]
	v_mfma_f32_16x16x32_bf16 v[44:47], v[128:131], v[176:179], v[44:47]
	v_mfma_f32_16x16x32_bf16 v[40:43], v[136:139], v[176:179], v[40:43]
	v_mfma_f32_16x16x32_bf16 v[36:39], v[128:131], v[184:187], v[36:39]
	v_mfma_f32_16x16x32_bf16 v[32:35], v[136:139], v[184:187], v[32:35]
	v_mfma_f32_16x16x32_bf16 v[60:63], v[132:135], v[164:167], v[60:63]
	v_mfma_f32_16x16x32_bf16 v[56:59], v[140:143], v[164:167], v[56:59]
	v_mfma_f32_16x16x32_bf16 v[52:55], v[132:135], v[172:175], v[52:55]
	v_mfma_f32_16x16x32_bf16 v[48:51], v[140:143], v[172:175], v[48:51]
	v_mfma_f32_16x16x32_bf16 v[44:47], v[132:135], v[180:183], v[44:47]
	v_mfma_f32_16x16x32_bf16 v[40:43], v[140:143], v[180:183], v[40:43]
	v_mfma_f32_16x16x32_bf16 v[36:39], v[132:135], v[188:191], v[36:39]
	v_mfma_f32_16x16x32_bf16 v[32:35], v[140:143], v[188:191], v[32:35]
	v_mfma_f32_16x16x32_bf16 v[28:31], v[144:147], v[160:163], v[28:31]
	v_mfma_f32_16x16x32_bf16 v[24:27], v[152:155], v[160:163], v[24:27]
	v_mfma_f32_16x16x32_bf16 v[20:23], v[144:147], v[168:171], v[20:23]
	v_mfma_f32_16x16x32_bf16 v[16:19], v[152:155], v[168:171], v[16:19]
	v_mfma_f32_16x16x32_bf16 v[12:15], v[144:147], v[176:179], v[12:15]
	v_mfma_f32_16x16x32_bf16 v[8:11], v[152:155], v[176:179], v[8:11]
	v_mfma_f32_16x16x32_bf16 v[4:7], v[144:147], v[184:187], v[4:7]
	v_mfma_f32_16x16x32_bf16 v[0:3], v[152:155], v[184:187], v[0:3]
	v_mfma_f32_16x16x32_bf16 v[28:31], v[148:151], v[164:167], v[28:31]
	v_mfma_f32_16x16x32_bf16 v[24:27], v[156:159], v[164:167], v[24:27]
	v_mfma_f32_16x16x32_bf16 v[20:23], v[148:151], v[172:175], v[20:23]
	v_mfma_f32_16x16x32_bf16 v[16:19], v[156:159], v[172:175], v[16:19]
	v_mfma_f32_16x16x32_bf16 v[12:15], v[148:151], v[180:183], v[12:15]
	v_mfma_f32_16x16x32_bf16 v[8:11], v[156:159], v[180:183], v[8:11]
	v_mfma_f32_16x16x32_bf16 v[4:7], v[148:151], v[188:191], v[4:7]
	v_mfma_f32_16x16x32_bf16 v[0:3], v[156:159], v[188:191], v[0:3]
	s_setprio 0
	s_barrier
	s_add_i32 s45, s45, 2
	s_add_u32 s27, s27, 0x100
	s_addc_u32 s29, s29, 0
	s_add_u32 s46, s46, 0x100
	s_addc_u32 s47, s47, 0
	s_cmp_gt_u32 s45, 13
	s_cbranch_scc0 .LBB0_541
	s_and_b64 vcc, exec, s[16:17]
	s_cbranch_vccz .LBB0_544
	s_barrier

;     __device__ __forceinline__ int nt(const Unit& u) const { return (u.ks < 0 || xsplit == 1) ? ntf : sbase + (u.ks >= sthr ? 2 : 0); }
; #define PG8_STAGE(bufoff, gbase, voff) do { _Pragma("unroll") for (int _i = 0; _i < 2; ++_i) \
;         __builtin_amdgcn_global_load_lds((const unsigned*)((const char*)(gbase) + (voff)[_i]), (LAS unsigned*)(lds + (bufoff) + ldsw + _i * 8192), 16, 0, 0); } while (0)
; #define PG8_LDA(dst, b, h) do { _Pragma("unroll") for (int m = 0; m < 4; ++m) _Pragma("unroll") for (int k = 0; k < 2; ++k) dst[m][k] = *(const LAS bf16x8*)(lds + PG8_SA(b, h) + aoff + m * 2048 + k * 1024); } while (0)
; #define PG8_LDB(dst, b, h) do { _Pragma("unroll") for (int n = 0; n < 2; ++n) _Pragma("unroll") for (int k = 0; k < 2; ++k) dst[n][k] = *(const LAS bf16x8*)(lds + PG8_SB(b, h) + boff + n * 2048 + k * 1024); } while (0)
; #define PG8_MMA(ai, bj, At, Bt) do { __builtin_amdgcn_s_setprio(1); _Pragma("unroll") for (int k = 0; k < 2; ++k) _Pragma("unroll") for (int m = 0; m < 4; ++m) _Pragma("unroll") for (int n = 0; n < 2; ++n) \
;         acc[ai][bj][m][n] = __builtin_amdgcn_mfma_f32_16x16x32_bf16(Bt[n][k], At[m][k], acc[ai][bj][m][n], 0, 0, 0); __builtin_amdgcn_s_setprio(0); } while (0)
; #define PG8_BAR __builtin_amdgcn_s_barrier()
; template <class Epi, bool ALIGN_EPI = PG8_ALIGN, bool SP2 = PG8_SP2>
; __device__ __forceinline__ void gemm_phase(LAS unsigned char* lds, const int tid, const int K, const Order& S, const Epi& E) {
;     ...
;             const bool last = (t == nt - 2);
;             const char* a1 = cA + (size_t)(t + 1) * kstep;
;             const char* a2 = last ? nA : cA + (size_t)(t + 2) * kstep; const char* b2 = last ? nB : cB + (size_t)(t + 2) * kstep;
;             const char* a3 = a2 + kstep; const char* b3 = b2 + kstep;
;             if (last && has_next) S.a_ready(nxt, tid);
;             if constexpr (SP2) {
;             PG8_LDB(B0, 0, 0); PG8_LDB(B1, 0, 1); PG8_SCHED; PG8_LDA(At, 0, 0); PG8_STAGE(PG8_SA(1, 1), a1 + hstep, voffA);
;             PG8_WAIT_V(8); PG8_WAIT_L(0); PG8_BAR; PG8_MMA(0, 0, At, B0); PG8_MMA(0, 1, At, B1); PG8_BAR; PG8_SCHED;
;             PG8_LDA(At, 0, 1); PG8_STAGE(PG8_SB(0, 0), b2, voffB); PG8_STAGE(PG8_SB(0, 1), b2 + hstep, voffB); PG8_STAGE(PG8_SA(0, 0), a2, voffA);
;             PG8_WAIT_V(8); PG8_WAIT_L(0); PG8_BAR; PG8_MMA(1, 0, At, B0); PG8_MMA(1, 1, At, B1); PG8_BAR; PG8_SCHED;
.LBB0_660:
	s_or_b32 s16, s45, 1
	s_lshl_b64 s[64:65], s[16:17], 7
	s_add_i32 s16, s45, 2
	s_waitcnt vmcnt(0)
	v_add_u32_e32 v140, s82, v171
	v_add_u32_e32 v166, s83, v171
	s_lshl_b64 vcc, s[16:17], 7
	ds_read_b128 v[128:131], v140
	ds_read_b128 v[132:135], v140 offset:1024
	ds_read_b128 v[136:139], v140 offset:2048
	ds_read_b128 v[140:143], v140 offset:3072
	ds_read_b128 v[144:147], v166
	ds_read_b128 v[148:151], v166 offset:1024
	ds_read_b128 v[162:165], v166 offset:2048
	ds_read_b128 v[166:169], v166 offset:3072
	s_add_u32 s45, s52, vcc_lo
	s_addc_u32 s51, s53, vcc_hi
	s_and_b64 s[62:63], s[60:61], exec
	s_cselect_b32 s63, s51, s47
	s_cselect_b32 s62, s45, s46
	s_add_u32 s45, s54, vcc_lo
	s_addc_u32 s51, s55, vcc_hi
	s_and_b64 s[60:61], s[60:61], exec
	s_cselect_b32 s61, s51, s49
	s_cselect_b32 s60, s45, s48
	s_add_u32 s64, s29, s64
	s_addc_u32 s65, s31, s65
	v_lshl_add_u64 v[206:207], s[64:65], 0, v[152:153]
	s_add_i32 m0, s71, 0xc000
	ds_read_b128 v[174:177], v173
	ds_read_b128 v[178:181], v173 offset:1024
	ds_read_b128 v[182:185], v173 offset:2048
	ds_read_b128 v[186:189], v173 offset:3072
	ds_read_b128 v[190:193], v173 offset:4096
	ds_read_b128 v[194:197], v173 offset:5120
	ds_read_b128 v[198:201], v173 offset:6144
	ds_read_b128 v[202:205], v173 offset:7168
	global_load_lds_dwordx4 v[206:207], off
	v_lshl_add_u64 v[206:207], s[64:65], 0, v[156:157]
	s_add_i32 m0, s71, 0xe000
	s_nop 0
	global_load_lds_dwordx4 v[206:207], off
	s_waitcnt vmcnt(8)
	s_waitcnt lgkmcnt(0)
	s_barrier
	s_setprio 1
	s_waitcnt lgkmcnt(0)
	v_mfma_f32_16x16x32_bf16 v[124:127], v[128:131], v[174:177], v[124:127]
	v_mfma_f32_16x16x32_bf16 v[120:123], v[136:139], v[174:177], v[120:123]
	v_mfma_f32_16x16x32_bf16 v[116:119], v[128:131], v[182:185], v[116:119]
	v_mfma_f32_16x16x32_bf16 v[108:111], v[136:139], v[182:185], v[108:111]
	v_mfma_f32_16x16x32_bf16 v[100:103], v[128:131], v[190:193], v[100:103]
	v_mfma_f32_16x16x32_bf16 v[92:95], v[136:139], v[190:193], v[92:95]
	v_mfma_f32_16x16x32_bf16 v[84:87], v[128:131], v[198:201], v[84:87]
	v_mfma_f32_16x16x32_bf16 v[76:79], v[136:139], v[198:201], v[76:79]
	v_mfma_f32_16x16x32_bf16 v[124:127], v[132:135], v[178:181], v[124:127]
	v_mfma_f32_16x16x32_bf16 v[120:123], v[140:143], v[178:181], v[120:123]
	v_mfma_f32_16x16x32_bf16 v[116:119], v[132:135], v[186:189], v[116:119]
	v_mfma_f32_16x16x32_bf16 v[108:111], v[140:143], v[186:189], v[108:111]
	v_mfma_f32_16x16x32_bf16 v[100:103], v[132:135], v[194:197], v[100:103]
	v_mfma_f32_16x16x32_bf16 v[92:95], v[140:143], v[194:197], v[92:95]
	v_mfma_f32_16x16x32_bf16 v[84:87], v[132:135], v[202:205], v[84:87]
	v_mfma_f32_16x16x32_bf16 v[76:79], v[140:143], v[202:205], v[76:79]
	v_mfma_f32_16x16x32_bf16 v[112:115], v[144:147], v[174:177], v[112:115]
	v_mfma_f32_16x16x32_bf16 v[104:107], v[162:165], v[174:177], v[104:107]
	v_mfma_f32_16x16x32_bf16 v[96:99], v[144:147], v[182:185], v[96:99]
	v_mfma_f32_16x16x32_bf16 v[88:91], v[162:165], v[182:185], v[88:91]
	v_mfma_f32_16x16x32_bf16 v[80:83], v[144:147], v[190:193], v[80:83]
	v_mfma_f32_16x16x32_bf16 v[72:75], v[162:165], v[190:193], v[72:75]
	v_mfma_f32_16x16x32_bf16 v[68:71], v[144:147], v[198:201], v[68:71]
	v_mfma_f32_16x16x32_bf16 v[64:67], v[162:165], v[198:201], v[64:67]
	v_mfma_f32_16x16x32_bf16 v[112:115], v[148:151], v[178:181], v[112:115]
	v_mfma_f32_16x16x32_bf16 v[104:107], v[166:169], v[178:181], v[104:107]
	v_mfma_f32_16x16x32_bf16 v[96:99], v[148:151], v[186:189], v[96:99]
	v_mfma_f32_16x16x32_bf16 v[88:91], v[166:169], v[186:189], v[88:91]
	v_mfma_f32_16x16x32_bf16 v[80:83], v[148:151], v[194:197], v[80:83]
	v_mfma_f32_16x16x32_bf16 v[72:75], v[166:169], v[194:197], v[72:75]
	v_mfma_f32_16x16x32_bf16 v[68:71], v[148:151], v[202:205], v[68:71]
	v_mfma_f32_16x16x32_bf16 v[64:67], v[166:169], v[202:205], v[64:67]
	s_setprio 0
	s_barrier
	s_add_i32 s45, s82, s68
	v_lshl_add_u64 v[206:207], s[60:61], 0, v[154:155]
	s_mov_b32 m0, s45
	ds_read_b128 v[174:177], v173 offset:16384
	ds_read_b128 v[178:181], v173 offset:17408
	ds_read_b128 v[182:185], v173 offset:18432
	ds_read_b128 v[186:189], v173 offset:19456
	ds_read_b128 v[190:193], v173 offset:20480
	ds_read_b128 v[194:197], v173 offset:21504
	ds_read_b128 v[198:201], v173 offset:22528
	ds_read_b128 v[202:205], v173 offset:23552
	global_load_lds_dwordx4 v[206:207], off
	s_add_i32 m0, s45, 0x2000
	s_add_u32 s64, s60, 0x80000
	v_lshl_add_u64 v[208:209], s[60:61], 0, v[158:159]
	s_addc_u32 s65, s61, 0
	s_add_i32 s45, s83, s68
	global_load_lds_dwordx4 v[208:209], off
	v_lshl_add_u64 v[210:211], s[64:65], 0, v[154:155]
	s_mov_b32 m0, s45
	v_lshl_add_u64 v[212:213], s[62:63], 0, v[156:157]
	global_load_lds_dwordx4 v[210:211], off
	v_lshl_add_u64 v[210:211], s[64:65], 0, v[158:159]
	s_add_i32 m0, s45, 0x2000
	s_nop 0
	global_load_lds_dwordx4 v[210:211], off
	v_lshl_add_u64 v[210:211], s[62:63], 0, v[152:153]
	s_mov_b32 m0, s71
	s_nop 0
	global_load_lds_dwordx4 v[210:211], off
	s_mov_b32 m0, s72
	s_nop 0
	global_load_lds_dwordx4 v[212:213], off
	s_waitcnt vmcnt(8)
	s_waitcnt lgkmcnt(0)
	s_barrier
; #define PG8_STAGE(bufoff, gbase, voff) do { _Pragma("unroll") for (int _i = 0; _i < 2; ++_i) \
;         __builtin_amdgcn_global_load_lds((const unsigned*)((const char*)(gbase) + (voff)[_i]), (LAS unsigned*)(lds + (bufoff) + ldsw + _i * 8192), 16, 0, 0); } while (0)
; #define PG8_LDA(dst, b, h) do { _Pragma("unroll") for (int m = 0; m < 4; ++m) _Pragma("unroll") for (int k = 0; k < 2; ++k) dst[m][k] = *(const LAS bf16x8*)(lds + PG8_SA(b, h) + aoff + m * 2048 + k * 1024); } while (0)
; #define PG8_LDB(dst, b, h) do { _Pragma("unroll") for (int n = 0; n < 2; ++n) _Pragma("unroll") for (int k = 0; k < 2; ++k) dst[n][k] = *(const LAS bf16x8*)(lds + PG8_SB(b, h) + boff + n * 2048 + k * 1024); } while (0)
; #define PG8_MMA(ai, bj, At, Bt) do { __builtin_amdgcn_s_setprio(1); _Pragma("unroll") for (int k = 0; k < 2; ++k) _Pragma("unroll") for (int m = 0; m < 4; ++m) _Pragma("unroll") for (int n = 0; n < 2; ++n) \
;         acc[ai][bj][m][n] = __builtin_amdgcn_mfma_f32_16x16x32_bf16(Bt[n][k], At[m][k], acc[ai][bj][m][n], 0, 0, 0); __builtin_amdgcn_s_setprio(0); } while (0)
; #define PG8_WAIT_V(n) asm volatile("s_waitcnt vmcnt(" #n ")" ::: "memory")
; #define PG8_WAIT_L(n) asm volatile("s_waitcnt lgkmcnt(" #n ")" ::: "memory")
; #define PG8_BAR __builtin_amdgcn_s_barrier()
; #define PG8_SCHED __builtin_amdgcn_sched_barrier(0)
; template <class Epi, bool ALIGN_EPI = PG8_ALIGN, bool SP2 = PG8_SP2>
; __device__ __forceinline__ void gemm_phase(LAS unsigned char* lds, const int tid, const int K, const Order& S, const Epi& E) {
;     ...
;             PG8_WAIT_V(8); PG8_WAIT_L(0); PG8_BAR; PG8_MMA(1, 0, At, B0); PG8_MMA(1, 1, At, B1); PG8_BAR; PG8_SCHED;
;             PG8_LDB(B0, 1, 0); PG8_LDB(B1, 1, 1); PG8_SCHED; PG8_LDA(At, 1, 0); PG8_STAGE(PG8_SA(0, 1), a2 + hstep, voffA);
;             PG8_WAIT_V(8); PG8_WAIT_L(0); PG8_BAR; PG8_MMA(0, 0, At, B0); PG8_MMA(0, 1, At, B1); PG8_BAR; PG8_SCHED;
	s_setprio 1
	s_waitcnt lgkmcnt(0)
	v_mfma_f32_16x16x32_bf16 v[60:63], v[128:131], v[174:177], v[60:63]
	v_mfma_f32_16x16x32_bf16 v[56:59], v[136:139], v[174:177], v[56:59]
	v_mfma_f32_16x16x32_bf16 v[52:55], v[128:131], v[182:185], v[52:55]
	v_mfma_f32_16x16x32_bf16 v[44:47], v[136:139], v[182:185], v[44:47]
	v_mfma_f32_16x16x32_bf16 v[36:39], v[128:131], v[190:193], v[36:39]
	v_mfma_f32_16x16x32_bf16 v[28:31], v[136:139], v[190:193], v[28:31]
	v_mfma_f32_16x16x32_bf16 v[20:23], v[128:131], v[198:201], v[20:23]
	v_mfma_f32_16x16x32_bf16 v[12:15], v[136:139], v[198:201], v[12:15]
	v_mfma_f32_16x16x32_bf16 v[60:63], v[132:135], v[178:181], v[60:63]
	v_mfma_f32_16x16x32_bf16 v[56:59], v[140:143], v[178:181], v[56:59]
	v_mfma_f32_16x16x32_bf16 v[52:55], v[132:135], v[186:189], v[52:55]
	v_mfma_f32_16x16x32_bf16 v[44:47], v[140:143], v[186:189], v[44:47]
	v_mfma_f32_16x16x32_bf16 v[36:39], v[132:135], v[194:197], v[36:39]
	v_mfma_f32_16x16x32_bf16 v[28:31], v[140:143], v[194:197], v[28:31]
	v_mfma_f32_16x16x32_bf16 v[20:23], v[132:135], v[202:205], v[20:23]
	v_mfma_f32_16x16x32_bf16 v[12:15], v[140:143], v[202:205], v[12:15]
	v_mfma_f32_16x16x32_bf16 v[48:51], v[144:147], v[174:177], v[48:51]
	v_mfma_f32_16x16x32_bf16 v[40:43], v[162:165], v[174:177], v[40:43]
	v_mfma_f32_16x16x32_bf16 v[32:35], v[144:147], v[182:185], v[32:35]
	v_mfma_f32_16x16x32_bf16 v[24:27], v[162:165], v[182:185], v[24:27]
	v_mfma_f32_16x16x32_bf16 v[16:19], v[144:147], v[190:193], v[16:19]
	v_mfma_f32_16x16x32_bf16 v[8:11], v[162:165], v[190:193], v[8:11]
	v_mfma_f32_16x16x32_bf16 v[4:7], v[144:147], v[198:201], v[4:7]
	v_mfma_f32_16x16x32_bf16 v[0:3], v[162:165], v[198:201], v[0:3]
	v_mfma_f32_16x16x32_bf16 v[48:51], v[148:151], v[178:181], v[48:51]
	v_mfma_f32_16x16x32_bf16 v[40:43], v[166:169], v[178:181], v[40:43]
	v_mfma_f32_16x16x32_bf16 v[32:35], v[148:151], v[186:189], v[32:35]
	v_mfma_f32_16x16x32_bf16 v[24:27], v[166:169], v[186:189], v[24:27]
	v_mfma_f32_16x16x32_bf16 v[16:19], v[148:151], v[194:197], v[16:19]
	v_mfma_f32_16x16x32_bf16 v[8:11], v[166:169], v[194:197], v[8:11]
	v_mfma_f32_16x16x32_bf16 v[4:7], v[148:151], v[202:205], v[4:7]
	v_mfma_f32_16x16x32_bf16 v[0:3], v[166:169], v[202:205], v[0:3]
	s_setprio 0
	s_barrier
	s_add_i32 s45, 0, 0x18000
	s_add_i32 s51, 0, 0x1c000
	v_add_u32_e32 v140, s45, v171
	v_add_u32_e32 v166, s51, v171
	ds_read_b128 v[128:131], v140
	ds_read_b128 v[132:135], v140 offset:1024
	ds_read_b128 v[136:139], v140 offset:2048
	ds_read_b128 v[140:143], v140 offset:3072
	ds_read_b128 v[144:147], v166
	ds_read_b128 v[148:151], v166 offset:1024
	ds_read_b128 v[162:165], v166 offset:2048
	ds_read_b128 v[166:169], v166 offset:3072
	s_add_u32 s62, s62, 0x80000
	s_addc_u32 s63, s63, 0
	s_mov_b32 m0, s73
	v_lshl_add_u64 v[214:215], s[62:63], 0, v[152:153]
	ds_read_b128 v[174:177], v173 offset:32768
	ds_read_b128 v[178:181], v173 offset:33792
	ds_read_b128 v[182:185], v173 offset:34816
	ds_read_b128 v[186:189], v173 offset:35840
	ds_read_b128 v[190:193], v173 offset:36864
	ds_read_b128 v[194:197], v173 offset:37888
	ds_read_b128 v[198:201], v173 offset:38912
	ds_read_b128 v[202:205], v173 offset:39936
	global_load_lds_dwordx4 v[214:215], off
	v_lshl_add_u64 v[214:215], s[62:63], 0, v[156:157]
	s_mov_b32 m0, s74
	s_nop 0
	global_load_lds_dwordx4 v[214:215], off
	s_waitcnt vmcnt(8)
	s_waitcnt lgkmcnt(0)
	s_barrier
	s_setprio 1
	s_waitcnt lgkmcnt(0)
	v_mfma_f32_16x16x32_bf16 v[124:127], v[128:131], v[174:177], v[124:127]
	v_mfma_f32_16x16x32_bf16 v[120:123], v[136:139], v[174:177], v[120:123]
	v_mfma_f32_16x16x32_bf16 v[116:119], v[128:131], v[182:185], v[116:119]
	v_mfma_f32_16x16x32_bf16 v[108:111], v[136:139], v[182:185], v[108:111]
	v_mfma_f32_16x16x32_bf16 v[100:103], v[128:131], v[190:193], v[100:103]
	v_mfma_f32_16x16x32_bf16 v[92:95], v[136:139], v[190:193], v[92:95]
	v_mfma_f32_16x16x32_bf16 v[84:87], v[128:131], v[198:201], v[84:87]
	v_mfma_f32_16x16x32_bf16 v[76:79], v[136:139], v[198:201], v[76:79]
	v_mfma_f32_16x16x32_bf16 v[124:127], v[132:135], v[178:181], v[124:127]
	v_mfma_f32_16x16x32_bf16 v[120:123], v[140:143], v[178:181], v[120:123]
	v_mfma_f32_16x16x32_bf16 v[116:119], v[132:135], v[186:189], v[116:119]
	v_mfma_f32_16x16x32_bf16 v[108:111], v[140:143], v[186:189], v[108:111]
	v_mfma_f32_16x16x32_bf16 v[100:103], v[132:135], v[194:197], v[100:103]
	v_mfma_f32_16x16x32_bf16 v[92:95], v[140:143], v[194:197], v[92:95]
	v_mfma_f32_16x16x32_bf16 v[84:87], v[132:135], v[202:205], v[84:87]
	v_mfma_f32_16x16x32_bf16 v[76:79], v[140:143], v[202:205], v[76:79]
	v_mfma_f32_16x16x32_bf16 v[112:115], v[144:147], v[174:177], v[112:115]
	v_mfma_f32_16x16x32_bf16 v[104:107], v[162:165], v[174:177], v[104:107]
	v_mfma_f32_16x16x32_bf16 v[96:99], v[144:147], v[182:185], v[96:99]
	v_mfma_f32_16x16x32_bf16 v[88:91], v[162:165], v[182:185], v[88:91]
	v_mfma_f32_16x16x32_bf16 v[80:83], v[144:147], v[190:193], v[80:83]
	v_mfma_f32_16x16x32_bf16 v[72:75], v[162:165], v[190:193], v[72:75]
	v_mfma_f32_16x16x32_bf16 v[68:71], v[144:147], v[198:201], v[68:71]
	v_mfma_f32_16x16x32_bf16 v[64:67], v[162:165], v[198:201], v[64:67]
	v_mfma_f32_16x16x32_bf16 v[112:115], v[148:151], v[178:181], v[112:115]
	v_mfma_f32_16x16x32_bf16 v[104:107], v[166:169], v[178:181], v[104:107]
	v_mfma_f32_16x16x32_bf16 v[96:99], v[148:151], v[186:189], v[96:99]
	v_mfma_f32_16x16x32_bf16 v[88:91], v[166:169], v[186:189], v[88:91]
	v_mfma_f32_16x16x32_bf16 v[80:83], v[148:151], v[194:197], v[80:83]
	v_mfma_f32_16x16x32_bf16 v[72:75], v[166:169], v[194:197], v[72:75]
	v_mfma_f32_16x16x32_bf16 v[68:71], v[148:151], v[202:205], v[68:71]
	v_mfma_f32_16x16x32_bf16 v[64:67], v[166:169], v[202:205], v[64:67]
	s_setprio 0
	s_barrier
;     __device__ __forceinline__ int nt(const Unit& u) const { return (u.ks < 0 || xsplit == 1) ? ntf : sbase + (u.ks >= sthr ? 2 : 0); }
; #define PG8_STAGE(bufoff, gbase, voff) do { _Pragma("unroll") for (int _i = 0; _i < 2; ++_i) \
;         __builtin_amdgcn_global_load_lds((const unsigned*)((const char*)(gbase) + (voff)[_i]), (LAS unsigned*)(lds + (bufoff) + ldsw + _i * 8192), 16, 0, 0); } while (0)
; #define PG8_LDA(dst, b, h) do { _Pragma("unroll") for (int m = 0; m < 4; ++m) _Pragma("unroll") for (int k = 0; k < 2; ++k) dst[m][k] = *(const LAS bf16x8*)(lds + PG8_SA(b, h) + aoff + m * 2048 + k * 1024); } while (0)
; #define PG8_MMA(ai, bj, At, Bt) do { __builtin_amdgcn_s_setprio(1); _Pragma("unroll") for (int k = 0; k < 2; ++k) _Pragma("unroll") for (int m = 0; m < 4; ++m) _Pragma("unroll") for (int n = 0; n < 2; ++n) \
;         acc[ai][bj][m][n] = __builtin_amdgcn_mfma_f32_16x16x32_bf16(Bt[n][k], At[m][k], acc[ai][bj][m][n], 0, 0, 0); __builtin_amdgcn_s_setprio(0); } while (0)
; #define PG8_WAIT_V(n) asm volatile("s_waitcnt vmcnt(" #n ")" ::: "memory")
; #define PG8_WAIT_L(n) asm volatile("s_waitcnt lgkmcnt(" #n ")" ::: "memory")
; #define PG8_BAR __builtin_amdgcn_s_barrier()
; #define PG8_SCHED __builtin_amdgcn_sched_barrier(0)
; template <class Epi, bool ALIGN_EPI = PG8_ALIGN, bool SP2 = PG8_SP2>
; __device__ __forceinline__ void gemm_phase(LAS unsigned char* lds, const int tid, const int K, const Order& S, const Epi& E) {
;     ...
;         for (int t = 0; t < nt; t += 2) {
;     ...
;             PG8_LDA(At, 1, 1); PG8_STAGE(PG8_SB(1, 0), b3, voffB); PG8_STAGE(PG8_SB(1, 1), b3 + hstep, voffB); PG8_STAGE(PG8_SA(1, 0), a3, voffA);
;             PG8_WAIT_V(8); PG8_WAIT_L(0); PG8_BAR; PG8_MMA(1, 0, At, B0); PG8_MMA(1, 1, At, B1); PG8_BAR; PG8_SCHED;
	s_add_i32 s45, s45, s68
	v_lshl_add_u64 v[206:207], v[206:207], 0, s[22:23]
	s_mov_b32 m0, s45
	ds_read_b128 v[174:177], v173 offset:49152
	ds_read_b128 v[178:181], v173 offset:50176
	ds_read_b128 v[182:185], v173 offset:51200
	ds_read_b128 v[186:189], v173 offset:52224
	ds_read_b128 v[190:193], v173 offset:53248
	ds_read_b128 v[194:197], v173 offset:54272
	ds_read_b128 v[198:201], v173 offset:55296
	ds_read_b128 v[202:205], v173 offset:56320
	global_load_lds_dwordx4 v[206:207], off
	s_add_i32 m0, s45, 0x2000
	s_add_u32 s60, s60, 0x80080
	v_lshl_add_u64 v[206:207], v[208:209], 0, s[22:23]
	s_addc_u32 s61, s61, 0
	s_add_i32 s45, s51, s68
	global_load_lds_dwordx4 v[206:207], off
	v_lshl_add_u64 v[206:207], s[60:61], 0, v[154:155]
	s_mov_b32 m0, s45
	s_nop 0
	global_load_lds_dwordx4 v[206:207], off
	v_lshl_add_u64 v[206:207], s[60:61], 0, v[158:159]
	s_add_i32 m0, s45, 0x2000
	s_nop 0
	global_load_lds_dwordx4 v[206:207], off
	v_lshl_add_u64 v[206:207], v[210:211], 0, s[22:23]
	s_mov_b32 m0, s77
	s_nop 0
	global_load_lds_dwordx4 v[206:207], off
	v_lshl_add_u64 v[206:207], v[212:213], 0, s[22:23]
	s_mov_b32 m0, s78
	s_nop 0
	global_load_lds_dwordx4 v[206:207], off
	s_waitcnt vmcnt(8)
	s_waitcnt lgkmcnt(0)
	s_barrier
	s_setprio 1
	s_waitcnt lgkmcnt(0)
	v_mfma_f32_16x16x32_bf16 v[60:63], v[128:131], v[174:177], v[60:63]
	v_mfma_f32_16x16x32_bf16 v[56:59], v[136:139], v[174:177], v[56:59]
	v_mfma_f32_16x16x32_bf16 v[52:55], v[128:131], v[182:185], v[52:55]
	v_mfma_f32_16x16x32_bf16 v[44:47], v[136:139], v[182:185], v[44:47]
	v_mfma_f32_16x16x32_bf16 v[36:39], v[128:131], v[190:193], v[36:39]
	v_mfma_f32_16x16x32_bf16 v[28:31], v[136:139], v[190:193], v[28:31]
	v_mfma_f32_16x16x32_bf16 v[20:23], v[128:131], v[198:201], v[20:23]
	v_mfma_f32_16x16x32_bf16 v[12:15], v[136:139], v[198:201], v[12:15]
	v_mfma_f32_16x16x32_bf16 v[60:63], v[132:135], v[178:181], v[60:63]
	v_mfma_f32_16x16x32_bf16 v[56:59], v[140:143], v[178:181], v[56:59]
	v_mfma_f32_16x16x32_bf16 v[52:55], v[132:135], v[186:189], v[52:55]
	v_mfma_f32_16x16x32_bf16 v[44:47], v[140:143], v[186:189], v[44:47]
	v_mfma_f32_16x16x32_bf16 v[36:39], v[132:135], v[194:197], v[36:39]
	v_mfma_f32_16x16x32_bf16 v[28:31], v[140:143], v[194:197], v[28:31]
	v_mfma_f32_16x16x32_bf16 v[20:23], v[132:135], v[202:205], v[20:23]
	v_mfma_f32_16x16x32_bf16 v[12:15], v[140:143], v[202:205], v[12:15]
	v_mfma_f32_16x16x32_bf16 v[48:51], v[144:147], v[174:177], v[48:51]
	v_mfma_f32_16x16x32_bf16 v[40:43], v[162:165], v[174:177], v[40:43]
	v_mfma_f32_16x16x32_bf16 v[32:35], v[144:147], v[182:185], v[32:35]
	v_mfma_f32_16x16x32_bf16 v[24:27], v[162:165], v[182:185], v[24:27]
	v_mfma_f32_16x16x32_bf16 v[16:19], v[144:147], v[190:193], v[16:19]
	v_mfma_f32_16x16x32_bf16 v[8:11], v[162:165], v[190:193], v[8:11]
	v_mfma_f32_16x16x32_bf16 v[4:7], v[144:147], v[198:201], v[4:7]
	v_mfma_f32_16x16x32_bf16 v[0:3], v[162:165], v[198:201], v[0:3]
	v_mfma_f32_16x16x32_bf16 v[48:51], v[148:151], v[178:181], v[48:51]
	v_mfma_f32_16x16x32_bf16 v[40:43], v[166:169], v[178:181], v[40:43]
	v_mfma_f32_16x16x32_bf16 v[32:35], v[148:151], v[186:189], v[32:35]
	v_mfma_f32_16x16x32_bf16 v[24:27], v[166:169], v[186:189], v[24:27]
	v_mfma_f32_16x16x32_bf16 v[16:19], v[148:151], v[194:197], v[16:19]
	v_mfma_f32_16x16x32_bf16 v[8:11], v[166:169], v[194:197], v[8:11]
	v_mfma_f32_16x16x32_bf16 v[4:7], v[148:151], v[202:205], v[4:7]
	v_mfma_f32_16x16x32_bf16 v[0:3], v[166:169], v[202:205], v[0:3]
	s_setprio 0
	s_barrier
	s_cmp_ge_u32 s16, s9
	s_mov_b32 s45, s16
	s_cbranch_scc1 .LBB0_667

;     __device__ __forceinline__ int nt(const Unit& u) const { return (u.ks < 0 || xsplit == 1) ? ntf : sbase + (u.ks >= sthr ? 2 : 0); }
; #define PG8_STAGE(bufoff, gbase, voff) do { _Pragma("unroll") for (int _i = 0; _i < 2; ++_i) \
;         __builtin_amdgcn_global_load_lds((const unsigned*)((const char*)(gbase) + (voff)[_i]), (LAS unsigned*)(lds + (bufoff) + ldsw + _i * 8192), 16, 0, 0); } while (0)
; #define PG8_LDA(dst, b, h) do { _Pragma("unroll") for (int m = 0; m < 4; ++m) _Pragma("unroll") for (int k = 0; k < 2; ++k) dst[m][k] = *(const LAS bf16x8*)(lds + PG8_SA(b, h) + aoff + m * 2048 + k * 1024); } while (0)
; #define PG8_LDB(dst, b, h) do { _Pragma("unroll") for (int n = 0; n < 2; ++n) _Pragma("unroll") for (int k = 0; k < 2; ++k) dst[n][k] = *(const LAS bf16x8*)(lds + PG8_SB(b, h) + boff + n * 2048 + k * 1024); } while (0)
; #define PG8_MMA(ai, bj, At, Bt) do { __builtin_amdgcn_s_setprio(1); _Pragma("unroll") for (int k = 0; k < 2; ++k) _Pragma("unroll") for (int m = 0; m < 4; ++m) _Pragma("unroll") for (int n = 0; n < 2; ++n) \
;         acc[ai][bj][m][n] = __builtin_amdgcn_mfma_f32_16x16x32_bf16(Bt[n][k], At[m][k], acc[ai][bj][m][n], 0, 0, 0); __builtin_amdgcn_s_setprio(0); } while (0)
; #define PG8_BAR __builtin_amdgcn_s_barrier()
; template <class Epi, bool ALIGN_EPI = PG8_ALIGN, bool SP2 = PG8_SP2>
; __device__ __forceinline__ void gemm_phase(LAS unsigned char* lds, const int tid, const int K, const Order& S, const Epi& E) {
;     ...
;             const bool last = (t == nt - 2);
;             const char* a1 = cA + (size_t)(t + 1) * kstep;
;             const char* a2 = last ? nA : cA + (size_t)(t + 2) * kstep; const char* b2 = last ? nB : cB + (size_t)(t + 2) * kstep;
;             const char* a3 = a2 + kstep; const char* b3 = b2 + kstep;
;             if (last && has_next) S.a_ready(nxt, tid);
;             if constexpr (SP2) {
;             PG8_LDB(B0, 0, 0); PG8_LDB(B1, 0, 1); PG8_SCHED; PG8_LDA(At, 0, 0); PG8_STAGE(PG8_SA(1, 1), a1 + hstep, voffA);
;             PG8_WAIT_V(8); PG8_WAIT_L(0); PG8_BAR; PG8_MMA(0, 0, At, B0); PG8_MMA(0, 1, At, B1); PG8_BAR; PG8_SCHED;
;             PG8_LDA(At, 0, 1); PG8_STAGE(PG8_SB(0, 0), b2, voffB); PG8_STAGE(PG8_SB(0, 1), b2 + hstep, voffB); PG8_STAGE(PG8_SA(0, 0), a2, voffA);
;             PG8_WAIT_V(8); PG8_WAIT_L(0); PG8_BAR; PG8_MMA(1, 0, At, B0); PG8_MMA(1, 1, At, B1); PG8_BAR; PG8_SCHED;
.LBB0_865:
	ds_read_b128 v[48:51], v222
	ds_read_b128 v[52:55], v222 offset:1024
	ds_read_b128 v[56:59], v222 offset:2048
	ds_read_b128 v[60:63], v222 offset:3072
	ds_read_b128 v[72:75], v223
	ds_read_b128 v[76:79], v223 offset:1024
	ds_read_b128 v[136:139], v223 offset:2048
	ds_read_b128 v[140:143], v223 offset:3072
	s_add_u32 s60, s58, 0xfff80080
	s_addc_u32 s61, s59, -1
	s_cmp_eq_u32 s86, 28
	s_cselect_b32 s63, s44, s61
	s_cselect_b32 s62, s45, s60
	s_cselect_b32 s61, s35, s85
	s_cselect_b32 s60, s47, s55
	v_lshl_add_u64 v[206:207], s[58:59], 0, v[194:195]
	s_add_i32 m0, s57, 0xc000
	ds_read_b128 v[144:147], v224
	ds_read_b128 v[148:151], v224 offset:1024
	ds_read_b128 v[152:155], v224 offset:2048
	ds_read_b128 v[160:163], v224 offset:3072
	ds_read_b128 v[176:179], v224 offset:4096
	ds_read_b128 v[180:183], v224 offset:5120
	ds_read_b128 v[198:201], v224 offset:6144
	ds_read_b128 v[202:205], v224 offset:7168
	global_load_lds_dwordx4 v[206:207], off
	v_lshl_add_u64 v[206:207], s[58:59], 0, v[192:193]
	s_add_i32 m0, s57, 0xe000
	s_nop 0
	global_load_lds_dwordx4 v[206:207], off
	s_waitcnt vmcnt(8)
	s_waitcnt lgkmcnt(0)
	s_barrier
	s_setprio 1
	s_waitcnt lgkmcnt(0)
	v_mfma_f32_16x16x32_bf16 v[172:175], v[48:51], v[144:147], v[172:175]
	v_mfma_f32_16x16x32_bf16 v[84:87], v[56:59], v[144:147], v[84:87]
	v_mfma_f32_16x16x32_bf16 v[164:167], v[48:51], v[152:155], v[164:167]
	v_mfma_f32_16x16x32_bf16 v[68:71], v[56:59], v[152:155], v[68:71]
	v_mfma_f32_16x16x32_bf16 v[132:135], v[48:51], v[176:179], v[132:135]
	v_mfma_f32_16x16x32_bf16 v[44:47], v[56:59], v[176:179], v[44:47]
	v_mfma_f32_16x16x32_bf16 v[124:127], v[48:51], v[198:201], v[124:127]
	v_mfma_f32_16x16x32_bf16 v[36:39], v[56:59], v[198:201], v[36:39]
	v_mfma_f32_16x16x32_bf16 v[172:175], v[52:55], v[148:151], v[172:175]
	v_mfma_f32_16x16x32_bf16 v[84:87], v[60:63], v[148:151], v[84:87]
	v_mfma_f32_16x16x32_bf16 v[164:167], v[52:55], v[160:163], v[164:167]
	v_mfma_f32_16x16x32_bf16 v[68:71], v[60:63], v[160:163], v[68:71]
	v_mfma_f32_16x16x32_bf16 v[132:135], v[52:55], v[180:183], v[132:135]
	v_mfma_f32_16x16x32_bf16 v[44:47], v[60:63], v[180:183], v[44:47]
	v_mfma_f32_16x16x32_bf16 v[124:127], v[52:55], v[202:205], v[124:127]
	v_mfma_f32_16x16x32_bf16 v[36:39], v[60:63], v[202:205], v[36:39]
	v_mfma_f32_16x16x32_bf16 v[80:83], v[136:139], v[144:147], v[80:83]
	v_mfma_f32_16x16x32_bf16 v[64:67], v[136:139], v[152:155], v[64:67]
	v_mfma_f32_16x16x32_bf16 v[128:131], v[72:75], v[176:179], v[128:131]
	v_mfma_f32_16x16x32_bf16 v[40:43], v[136:139], v[176:179], v[40:43]
	v_mfma_f32_16x16x32_bf16 v[120:123], v[72:75], v[198:201], v[120:123]
	v_mfma_f32_16x16x32_bf16 v[32:35], v[136:139], v[198:201], v[32:35]
	v_mfma_f32_16x16x32_bf16 v[168:171], v[72:75], v[144:147], v[168:171]
	v_mfma_f32_16x16x32_bf16 v[144:147], v[72:75], v[152:155], v[156:159]
	v_mfma_f32_16x16x32_bf16 v[80:83], v[140:143], v[148:151], v[80:83]
	v_mfma_f32_16x16x32_bf16 v[64:67], v[140:143], v[160:163], v[64:67]
	v_mfma_f32_16x16x32_bf16 v[128:131], v[76:79], v[180:183], v[128:131]
	v_mfma_f32_16x16x32_bf16 v[40:43], v[140:143], v[180:183], v[40:43]
	v_mfma_f32_16x16x32_bf16 v[120:123], v[76:79], v[202:205], v[120:123]
	v_mfma_f32_16x16x32_bf16 v[32:35], v[140:143], v[202:205], v[32:35]
	v_mfma_f32_16x16x32_bf16 v[152:155], v[76:79], v[148:151], v[168:171]
	v_mfma_f32_16x16x32_bf16 v[144:147], v[76:79], v[160:163], v[144:147]
	s_setprio 0
	s_barrier
	s_add_i32 s87, s81, s68
	v_lshl_add_u64 v[214:215], s[60:61], 0, v[186:187]
	s_mov_b32 m0, s87
	ds_read_b128 v[148:151], v224 offset:16384
	ds_read_b128 v[156:159], v224 offset:17408
	ds_read_b128 v[160:163], v224 offset:18432
	ds_read_b128 v[168:171], v224 offset:19456
	ds_read_b128 v[176:179], v224 offset:20480
	ds_read_b128 v[180:183], v224 offset:21504
	ds_read_b128 v[198:201], v224 offset:22528
	ds_read_b128 v[202:205], v224 offset:23552
	global_load_lds_dwordx4 v[214:215], off
	s_add_i32 m0, s87, 0x2000
	s_add_u32 s88, s60, 0x80000
	v_lshl_add_u64 v[226:227], s[60:61], 0, v[190:191]
	s_addc_u32 s89, s61, 0
	s_add_i32 s87, s82, s68
	global_load_lds_dwordx4 v[226:227], off
	v_lshl_add_u64 v[206:207], s[88:89], 0, v[186:187]
	s_mov_b32 m0, s87
	v_lshl_add_u64 v[228:229], s[62:63], 0, v[184:185]
	global_load_lds_dwordx4 v[206:207], off
	v_lshl_add_u64 v[206:207], s[88:89], 0, v[190:191]
	s_add_i32 m0, s87, 0x2000
	v_lshl_add_u64 v[230:231], s[62:63], 0, v[188:189]
	global_load_lds_dwordx4 v[206:207], off
	s_mov_b32 m0, s57
	s_nop 0
	global_load_lds_dwordx4 v[228:229], off
	s_mov_b32 m0, s69
	s_nop 0
	global_load_lds_dwordx4 v[230:231], off
	s_waitcnt vmcnt(8)
	s_waitcnt lgkmcnt(0)
	s_barrier
; #define PG8_STAGE(bufoff, gbase, voff) do { _Pragma("unroll") for (int _i = 0; _i < 2; ++_i) \
;         __builtin_amdgcn_global_load_lds((const unsigned*)((const char*)(gbase) + (voff)[_i]), (LAS unsigned*)(lds + (bufoff) + ldsw + _i * 8192), 16, 0, 0); } while (0)
; #define PG8_LDA(dst, b, h) do { _Pragma("unroll") for (int m = 0; m < 4; ++m) _Pragma("unroll") for (int k = 0; k < 2; ++k) dst[m][k] = *(const LAS bf16x8*)(lds + PG8_SA(b, h) + aoff + m * 2048 + k * 1024); } while (0)
; #define PG8_LDB(dst, b, h) do { _Pragma("unroll") for (int n = 0; n < 2; ++n) _Pragma("unroll") for (int k = 0; k < 2; ++k) dst[n][k] = *(const LAS bf16x8*)(lds + PG8_SB(b, h) + boff + n * 2048 + k * 1024); } while (0)
; #define PG8_MMA(ai, bj, At, Bt) do { __builtin_amdgcn_s_setprio(1); _Pragma("unroll") for (int k = 0; k < 2; ++k) _Pragma("unroll") for (int m = 0; m < 4; ++m) _Pragma("unroll") for (int n = 0; n < 2; ++n) \
;         acc[ai][bj][m][n] = __builtin_amdgcn_mfma_f32_16x16x32_bf16(Bt[n][k], At[m][k], acc[ai][bj][m][n], 0, 0, 0); __builtin_amdgcn_s_setprio(0); } while (0)
; #define PG8_WAIT_V(n) asm volatile("s_waitcnt vmcnt(" #n ")" ::: "memory")
; #define PG8_WAIT_L(n) asm volatile("s_waitcnt lgkmcnt(" #n ")" ::: "memory")
; #define PG8_BAR __builtin_amdgcn_s_barrier()
; #define PG8_SCHED __builtin_amdgcn_sched_barrier(0)
; template <class Epi, bool ALIGN_EPI = PG8_ALIGN, bool SP2 = PG8_SP2>
; __device__ __forceinline__ void gemm_phase(LAS unsigned char* lds, const int tid, const int K, const Order& S, const Epi& E) {
;     ...
;             PG8_WAIT_V(8); PG8_WAIT_L(0); PG8_BAR; PG8_MMA(1, 0, At, B0); PG8_MMA(1, 1, At, B1); PG8_BAR; PG8_SCHED;
;             PG8_LDB(B0, 1, 0); PG8_LDB(B1, 1, 1); PG8_SCHED; PG8_LDA(At, 1, 0); PG8_STAGE(PG8_SA(0, 1), a2 + hstep, voffA);
;             PG8_WAIT_V(8); PG8_WAIT_L(0); PG8_BAR; PG8_MMA(0, 0, At, B0); PG8_MMA(0, 1, At, B1); PG8_BAR; PG8_SCHED;
	s_setprio 1
	s_waitcnt lgkmcnt(0)
	v_mfma_f32_16x16x32_bf16 v[28:31], v[56:59], v[148:151], v[28:31]
	v_mfma_f32_16x16x32_bf16 v[108:111], v[48:51], v[160:163], v[108:111]
	v_mfma_f32_16x16x32_bf16 v[20:23], v[56:59], v[160:163], v[20:23]
	v_mfma_f32_16x16x32_bf16 v[100:103], v[48:51], v[176:179], v[100:103]
	v_mfma_f32_16x16x32_bf16 v[12:15], v[56:59], v[176:179], v[12:15]
	v_mfma_f32_16x16x32_bf16 v[4:7], v[56:59], v[198:201], v[4:7]
	v_mfma_f32_16x16x32_bf16 v[116:119], v[48:51], v[148:151], v[116:119]
	v_mfma_f32_16x16x32_bf16 v[48:51], v[48:51], v[198:201], v[92:95]
	v_mfma_f32_16x16x32_bf16 v[28:31], v[60:63], v[156:159], v[28:31]
	v_mfma_f32_16x16x32_bf16 v[92:95], v[52:55], v[168:171], v[108:111]
	v_mfma_f32_16x16x32_bf16 v[20:23], v[60:63], v[168:171], v[20:23]
	v_mfma_f32_16x16x32_bf16 v[100:103], v[52:55], v[180:183], v[100:103]
	v_mfma_f32_16x16x32_bf16 v[12:15], v[60:63], v[180:183], v[12:15]
	v_mfma_f32_16x16x32_bf16 v[4:7], v[60:63], v[202:205], v[4:7]
	v_mfma_f32_16x16x32_bf16 v[56:59], v[52:55], v[156:159], v[116:119]
	v_mfma_f32_16x16x32_bf16 v[48:51], v[52:55], v[202:205], v[48:51]
	v_mfma_f32_16x16x32_bf16 v[24:27], v[136:139], v[148:151], v[24:27]
	v_mfma_f32_16x16x32_bf16 v[16:19], v[136:139], v[160:163], v[16:19]
	v_mfma_f32_16x16x32_bf16 v[96:99], v[72:75], v[176:179], v[96:99]
	v_mfma_f32_16x16x32_bf16 v[8:11], v[136:139], v[176:179], v[8:11]
	v_mfma_f32_16x16x32_bf16 v[0:3], v[136:139], v[198:201], v[0:3]
	v_mfma_f32_16x16x32_bf16 v[52:55], v[72:75], v[148:151], v[112:115]
	v_mfma_f32_16x16x32_bf16 v[60:63], v[72:75], v[160:163], v[104:107]
	v_mfma_f32_16x16x32_bf16 v[72:75], v[72:75], v[198:201], v[88:91]
	v_mfma_f32_16x16x32_bf16 v[24:27], v[140:143], v[156:159], v[24:27]
	v_mfma_f32_16x16x32_bf16 v[16:19], v[140:143], v[168:171], v[16:19]
	v_mfma_f32_16x16x32_bf16 v[88:91], v[76:79], v[180:183], v[96:99]
	v_mfma_f32_16x16x32_bf16 v[8:11], v[140:143], v[180:183], v[8:11]
	v_mfma_f32_16x16x32_bf16 v[0:3], v[140:143], v[202:205], v[0:3]
	v_mfma_f32_16x16x32_bf16 v[52:55], v[76:79], v[156:159], v[52:55]
	v_mfma_f32_16x16x32_bf16 v[60:63], v[76:79], v[168:171], v[60:63]
	v_mfma_f32_16x16x32_bf16 v[72:75], v[76:79], v[202:205], v[72:75]
	s_setprio 0
	s_barrier
	s_add_i32 s87, 0, 0x18000
	v_add_u32_e32 v108, s87, v220
	s_add_i32 s88, 0, 0x1c000
	ds_read_b128 v[76:79], v108
	ds_read_b128 v[96:99], v108 offset:1024
	ds_read_b128 v[104:107], v108 offset:2048
	ds_read_b128 v[112:115], v108 offset:3072
	v_add_u32_e32 v108, s88, v220
	ds_read_b128 v[136:139], v108
	ds_read_b128 v[140:143], v108 offset:1024
	ds_read_b128 v[148:151], v108 offset:2048
	ds_read_b128 v[160:163], v108 offset:3072
	s_add_u32 s62, s62, 0x80000
	s_addc_u32 s63, s63, 0
	s_mov_b32 m0, s70
	v_lshl_add_u64 v[206:207], s[62:63], 0, v[184:185]
	ds_read_b128 v[108:111], v224 offset:32768
	ds_read_b128 v[116:119], v224 offset:33792
	ds_read_b128 v[156:159], v224 offset:34816
	ds_read_b128 v[176:179], v224 offset:35840
	ds_read_b128 v[168:171], v224 offset:36864
	ds_read_b128 v[180:183], v224 offset:37888
	ds_read_b128 v[198:201], v224 offset:38912
	ds_read_b128 v[202:205], v224 offset:39936
	global_load_lds_dwordx4 v[206:207], off
	v_lshl_add_u64 v[206:207], s[62:63], 0, v[188:189]
	s_mov_b32 m0, s71
	s_nop 0
	global_load_lds_dwordx4 v[206:207], off
	s_waitcnt vmcnt(8)
	s_waitcnt lgkmcnt(0)
	s_barrier
	s_setprio 1
	s_waitcnt lgkmcnt(0)
	v_mfma_f32_16x16x32_bf16 v[172:175], v[76:79], v[108:111], v[172:175]
	v_mfma_f32_16x16x32_bf16 v[84:87], v[104:107], v[108:111], v[84:87]
	v_mfma_f32_16x16x32_bf16 v[164:167], v[76:79], v[156:159], v[164:167]
	v_mfma_f32_16x16x32_bf16 v[68:71], v[104:107], v[156:159], v[68:71]
	v_mfma_f32_16x16x32_bf16 v[132:135], v[76:79], v[168:171], v[132:135]
	v_mfma_f32_16x16x32_bf16 v[44:47], v[104:107], v[168:171], v[44:47]
	v_mfma_f32_16x16x32_bf16 v[124:127], v[76:79], v[198:201], v[124:127]
	v_mfma_f32_16x16x32_bf16 v[36:39], v[104:107], v[198:201], v[36:39]
	v_mfma_f32_16x16x32_bf16 v[172:175], v[96:99], v[116:119], v[172:175]
	v_mfma_f32_16x16x32_bf16 v[84:87], v[112:115], v[116:119], v[84:87]
	v_mfma_f32_16x16x32_bf16 v[164:167], v[96:99], v[176:179], v[164:167]
	v_mfma_f32_16x16x32_bf16 v[68:71], v[112:115], v[176:179], v[68:71]
	v_mfma_f32_16x16x32_bf16 v[132:135], v[96:99], v[180:183], v[132:135]
	v_mfma_f32_16x16x32_bf16 v[44:47], v[112:115], v[180:183], v[44:47]
	v_mfma_f32_16x16x32_bf16 v[124:127], v[96:99], v[202:205], v[124:127]
	v_mfma_f32_16x16x32_bf16 v[36:39], v[112:115], v[202:205], v[36:39]
	v_mfma_f32_16x16x32_bf16 v[152:155], v[136:139], v[108:111], v[152:155]
	v_mfma_f32_16x16x32_bf16 v[80:83], v[148:151], v[108:111], v[80:83]
	v_mfma_f32_16x16x32_bf16 v[108:111], v[136:139], v[156:159], v[144:147]
	v_mfma_f32_16x16x32_bf16 v[64:67], v[148:151], v[156:159], v[64:67]
	v_mfma_f32_16x16x32_bf16 v[128:131], v[136:139], v[168:171], v[128:131]
	v_mfma_f32_16x16x32_bf16 v[40:43], v[148:151], v[168:171], v[40:43]
	v_mfma_f32_16x16x32_bf16 v[120:123], v[136:139], v[198:201], v[120:123]
	v_mfma_f32_16x16x32_bf16 v[32:35], v[148:151], v[198:201], v[32:35]
	v_mfma_f32_16x16x32_bf16 v[168:171], v[140:143], v[116:119], v[152:155]
	v_mfma_f32_16x16x32_bf16 v[80:83], v[160:163], v[116:119], v[80:83]
	v_mfma_f32_16x16x32_bf16 v[156:159], v[140:143], v[176:179], v[108:111]
	v_mfma_f32_16x16x32_bf16 v[64:67], v[160:163], v[176:179], v[64:67]
	v_mfma_f32_16x16x32_bf16 v[128:131], v[140:143], v[180:183], v[128:131]
	v_mfma_f32_16x16x32_bf16 v[40:43], v[160:163], v[180:183], v[40:43]
	v_mfma_f32_16x16x32_bf16 v[120:123], v[140:143], v[202:205], v[120:123]
	v_mfma_f32_16x16x32_bf16 v[32:35], v[160:163], v[202:205], v[32:35]
	s_setprio 0
	s_barrier
; #define PG8_STAGE(bufoff, gbase, voff) do { _Pragma("unroll") for (int _i = 0; _i < 2; ++_i) \
;         __builtin_amdgcn_global_load_lds((const unsigned*)((const char*)(gbase) + (voff)[_i]), (LAS unsigned*)(lds + (bufoff) + ldsw + _i * 8192), 16, 0, 0); } while (0)
; #define PG8_LDA(dst, b, h) do { _Pragma("unroll") for (int m = 0; m < 4; ++m) _Pragma("unroll") for (int k = 0; k < 2; ++k) dst[m][k] = *(const LAS bf16x8*)(lds + PG8_SA(b, h) + aoff + m * 2048 + k * 1024); } while (0)
; #define PG8_MMA(ai, bj, At, Bt) do { __builtin_amdgcn_s_setprio(1); _Pragma("unroll") for (int k = 0; k < 2; ++k) _Pragma("unroll") for (int m = 0; m < 4; ++m) _Pragma("unroll") for (int n = 0; n < 2; ++n) \
;         acc[ai][bj][m][n] = __builtin_amdgcn_mfma_f32_16x16x32_bf16(Bt[n][k], At[m][k], acc[ai][bj][m][n], 0, 0, 0); __builtin_amdgcn_s_setprio(0); } while (0)
; #define PG8_WAIT_V(n) asm volatile("s_waitcnt vmcnt(" #n ")" ::: "memory")
; #define PG8_WAIT_L(n) asm volatile("s_waitcnt lgkmcnt(" #n ")" ::: "memory")
; #define PG8_BAR __builtin_amdgcn_s_barrier()
; #define PG8_SCHED __builtin_amdgcn_sched_barrier(0)
; template <class Epi, bool ALIGN_EPI = PG8_ALIGN, bool SP2 = PG8_SP2>
; __device__ __forceinline__ void gemm_phase(LAS unsigned char* lds, const int tid, const int K, const Order& S, const Epi& E) {
;     ...
;             PG8_LDA(At, 1, 1); PG8_STAGE(PG8_SB(1, 0), b3, voffB); PG8_STAGE(PG8_SB(1, 1), b3 + hstep, voffB); PG8_STAGE(PG8_SA(1, 0), a3, voffA);
;             PG8_WAIT_V(8); PG8_WAIT_L(0); PG8_BAR; PG8_MMA(1, 0, At, B0); PG8_MMA(1, 1, At, B1); PG8_BAR; PG8_SCHED;
;     ...
;         }
;         if constexpr (ALIGN_EPI) { if (wr == 0) PG8_BAR; }
	s_add_i32 s62, s87, s68
	v_lshl_add_u64 v[108:109], v[214:215], 0, s[18:19]
	s_mov_b32 m0, s62
	ds_read_b128 v[144:147], v224 offset:49152
	ds_read_b128 v[152:155], v224 offset:50176
	ds_read_b128 v[176:179], v224 offset:51200
	ds_read_b128 v[180:183], v224 offset:52224
	ds_read_b128 v[198:201], v224 offset:53248
	ds_read_b128 v[202:205], v224 offset:54272
	ds_read_b128 v[206:209], v224 offset:55296
	ds_read_b128 v[210:213], v224 offset:56320
	global_load_lds_dwordx4 v[108:109], off
	s_add_i32 m0, s62, 0x2000
	s_add_u32 s60, s60, 0x80080
	v_lshl_add_u64 v[108:109], v[226:227], 0, s[18:19]
	s_addc_u32 s61, s61, 0
	s_add_i32 s62, s88, s68
	global_load_lds_dwordx4 v[108:109], off
	v_lshl_add_u64 v[108:109], s[60:61], 0, v[186:187]
	s_mov_b32 m0, s62
	s_nop 0
	global_load_lds_dwordx4 v[108:109], off
	v_lshl_add_u64 v[108:109], s[60:61], 0, v[190:191]
	s_add_i32 m0, s62, 0x2000
	s_nop 0
	global_load_lds_dwordx4 v[108:109], off
	v_lshl_add_u64 v[108:109], v[228:229], 0, s[18:19]
	s_mov_b32 m0, s76
	s_nop 0
	global_load_lds_dwordx4 v[108:109], off
	v_lshl_add_u64 v[108:109], v[230:231], 0, s[18:19]
	s_mov_b32 m0, s77
	s_nop 0
	global_load_lds_dwordx4 v[108:109], off
	s_waitcnt vmcnt(8)
	s_waitcnt lgkmcnt(0)
	s_barrier
	s_setprio 1
	s_waitcnt lgkmcnt(0)
	v_mfma_f32_16x16x32_bf16 v[56:59], v[76:79], v[144:147], v[56:59]
	v_mfma_f32_16x16x32_bf16 v[28:31], v[104:107], v[144:147], v[28:31]
	v_mfma_f32_16x16x32_bf16 v[92:95], v[76:79], v[176:179], v[92:95]
	v_mfma_f32_16x16x32_bf16 v[20:23], v[104:107], v[176:179], v[20:23]
	v_mfma_f32_16x16x32_bf16 v[100:103], v[76:79], v[198:201], v[100:103]
	v_mfma_f32_16x16x32_bf16 v[12:15], v[104:107], v[198:201], v[12:15]
	v_mfma_f32_16x16x32_bf16 v[48:51], v[76:79], v[206:209], v[48:51]
	v_mfma_f32_16x16x32_bf16 v[4:7], v[104:107], v[206:209], v[4:7]
	v_mfma_f32_16x16x32_bf16 v[116:119], v[96:99], v[152:155], v[56:59]
	v_mfma_f32_16x16x32_bf16 v[28:31], v[112:115], v[152:155], v[28:31]
	v_mfma_f32_16x16x32_bf16 v[108:111], v[96:99], v[180:183], v[92:95]
	v_mfma_f32_16x16x32_bf16 v[20:23], v[112:115], v[180:183], v[20:23]
	v_mfma_f32_16x16x32_bf16 v[100:103], v[96:99], v[202:205], v[100:103]
	v_mfma_f32_16x16x32_bf16 v[12:15], v[112:115], v[202:205], v[12:15]
	v_mfma_f32_16x16x32_bf16 v[92:95], v[96:99], v[210:213], v[48:51]
	v_mfma_f32_16x16x32_bf16 v[4:7], v[112:115], v[210:213], v[4:7]
	v_mfma_f32_16x16x32_bf16 v[48:51], v[136:139], v[144:147], v[52:55]
	v_mfma_f32_16x16x32_bf16 v[24:27], v[148:151], v[144:147], v[24:27]
	v_mfma_f32_16x16x32_bf16 v[52:55], v[136:139], v[176:179], v[60:63]
	v_mfma_f32_16x16x32_bf16 v[16:19], v[148:151], v[176:179], v[16:19]
	v_mfma_f32_16x16x32_bf16 v[56:59], v[136:139], v[198:201], v[88:91]
	v_mfma_f32_16x16x32_bf16 v[8:11], v[148:151], v[198:201], v[8:11]
	v_mfma_f32_16x16x32_bf16 v[60:63], v[136:139], v[206:209], v[72:75]
	v_mfma_f32_16x16x32_bf16 v[0:3], v[148:151], v[206:209], v[0:3]
	v_mfma_f32_16x16x32_bf16 v[112:115], v[140:143], v[152:155], v[48:51]
	v_mfma_f32_16x16x32_bf16 v[24:27], v[160:163], v[152:155], v[24:27]
	v_mfma_f32_16x16x32_bf16 v[104:107], v[140:143], v[180:183], v[52:55]
	v_mfma_f32_16x16x32_bf16 v[16:19], v[160:163], v[180:183], v[16:19]
	v_mfma_f32_16x16x32_bf16 v[96:99], v[140:143], v[202:205], v[56:59]
	v_mfma_f32_16x16x32_bf16 v[8:11], v[160:163], v[202:205], v[8:11]
	v_mfma_f32_16x16x32_bf16 v[88:91], v[140:143], v[210:213], v[60:63]
	v_mfma_f32_16x16x32_bf16 v[0:3], v[160:163], v[210:213], v[0:3]
	s_setprio 0
	s_barrier
	s_add_i32 s86, s86, 2
	s_add_u32 s55, s55, 0x100
	s_addc_u32 s85, s85, 0
	s_add_u32 s58, s58, 0x100
	s_addc_u32 s59, s59, 0
	s_cmp_gt_u32 s86, 29
	s_cbranch_scc0 .LBB0_865
	s_and_b64 vcc, exec, s[20:21]
	s_cbranch_vccz .LBB0_868
	s_barrier

;     __device__ __forceinline__ int nt(const Unit& u) const { return (u.ks < 0 || xsplit == 1) ? ntf : sbase + (u.ks >= sthr ? 2 : 0); }
; #define PG8_STAGE(bufoff, gbase, voff) do { _Pragma("unroll") for (int _i = 0; _i < 2; ++_i) \
;         __builtin_amdgcn_global_load_lds((const unsigned*)((const char*)(gbase) + (voff)[_i]), (LAS unsigned*)(lds + (bufoff) + ldsw + _i * 8192), 16, 0, 0); } while (0)
; #define PG8_LDA(dst, b, h) do { _Pragma("unroll") for (int m = 0; m < 4; ++m) _Pragma("unroll") for (int k = 0; k < 2; ++k) dst[m][k] = *(const LAS bf16x8*)(lds + PG8_SA(b, h) + aoff + m * 2048 + k * 1024); } while (0)
; #define PG8_LDB(dst, b, h) do { _Pragma("unroll") for (int n = 0; n < 2; ++n) _Pragma("unroll") for (int k = 0; k < 2; ++k) dst[n][k] = *(const LAS bf16x8*)(lds + PG8_SB(b, h) + boff + n * 2048 + k * 1024); } while (0)
; #define PG8_MMA(ai, bj, At, Bt) do { __builtin_amdgcn_s_setprio(1); _Pragma("unroll") for (int k = 0; k < 2; ++k) _Pragma("unroll") for (int m = 0; m < 4; ++m) _Pragma("unroll") for (int n = 0; n < 2; ++n) \
;         acc[ai][bj][m][n] = __builtin_amdgcn_mfma_f32_16x16x32_bf16(Bt[n][k], At[m][k], acc[ai][bj][m][n], 0, 0, 0); __builtin_amdgcn_s_setprio(0); } while (0)
; #define PG8_BAR __builtin_amdgcn_s_barrier()
; template <class Epi, bool ALIGN_EPI = PG8_ALIGN, bool SP2 = PG8_SP2>
; __device__ __forceinline__ void gemm_phase(LAS unsigned char* lds, const int tid, const int K, const Order& S, const Epi& E) {
;     ...
;             const bool last = (t == nt - 2);
;             const char* a1 = cA + (size_t)(t + 1) * kstep;
;             const char* a2 = last ? nA : cA + (size_t)(t + 2) * kstep; const char* b2 = last ? nB : cB + (size_t)(t + 2) * kstep;
;             const char* a3 = a2 + kstep; const char* b3 = b2 + kstep;
;             if (last && has_next) S.a_ready(nxt, tid);
;             if constexpr (SP2) {
;             PG8_LDB(B0, 0, 0); PG8_LDB(B1, 0, 1); PG8_SCHED; PG8_LDA(At, 0, 0); PG8_STAGE(PG8_SA(1, 1), a1 + hstep, voffA);
;             PG8_WAIT_V(8); PG8_WAIT_L(0); PG8_BAR; PG8_MMA(0, 0, At, B0); PG8_MMA(0, 1, At, B1); PG8_BAR; PG8_SCHED;
;             PG8_LDA(At, 0, 1); PG8_STAGE(PG8_SB(0, 0), b2, voffB); PG8_STAGE(PG8_SB(0, 1), b2 + hstep, voffB); PG8_STAGE(PG8_SA(0, 0), a2, voffA);
;             PG8_WAIT_V(8); PG8_WAIT_L(0); PG8_BAR; PG8_MMA(1, 0, At, B0); PG8_MMA(1, 1, At, B1); PG8_BAR; PG8_SCHED;
.LBB0_1118:
	s_waitcnt vmcnt(0)
	ds_read_b128 v[128:131], v169
	ds_read_b128 v[132:135], v169 offset:1024
	ds_read_b128 v[136:139], v169 offset:2048
	ds_read_b128 v[140:143], v169 offset:3072
	ds_read_b128 v[158:161], v170
	ds_read_b128 v[162:165], v170 offset:1024
	ds_read_b128 v[172:175], v170 offset:2048
	ds_read_b128 v[176:179], v170 offset:3072
	s_add_i32 vcc_lo, s48, 2
	s_add_u32 s46, s34, 0x100
	s_addc_u32 s47, s35, 0
	s_cmp_eq_u32 s95, s48
	s_cselect_b32 s48, s30, s96
	s_cselect_b32 s51, s29, s47
	s_cselect_b32 s50, s28, s46
	s_cselect_b32 s49, s31, s97
	v_lshl_add_u64 v[212:213], s[34:35], 0, v[154:155]
	s_add_i32 m0, s55, 0xc000
	ds_read_b128 v[180:183], v171
	ds_read_b128 v[184:187], v171 offset:1024
	ds_read_b128 v[188:191], v171 offset:2048
	ds_read_b128 v[192:195], v171 offset:3072
	ds_read_b128 v[196:199], v171 offset:4096
	ds_read_b128 v[200:203], v171 offset:5120
	ds_read_b128 v[204:207], v171 offset:6144
	ds_read_b128 v[208:211], v171 offset:7168
	global_load_lds_dwordx4 v[212:213], off
	v_lshl_add_u64 v[212:213], s[34:35], 0, v[152:153]
	s_add_i32 m0, s55, 0xe000
	s_nop 0
	global_load_lds_dwordx4 v[212:213], off
	s_waitcnt vmcnt(8)
	s_waitcnt lgkmcnt(0)
	s_barrier
	s_setprio 1
	s_waitcnt lgkmcnt(0)
	v_mfma_f32_16x16x32_bf16 v[124:127], v[128:131], v[180:183], v[124:127]
	v_mfma_f32_16x16x32_bf16 v[120:123], v[136:139], v[180:183], v[120:123]
	v_mfma_f32_16x16x32_bf16 v[116:119], v[128:131], v[188:191], v[116:119]
	v_mfma_f32_16x16x32_bf16 v[108:111], v[136:139], v[188:191], v[108:111]
	v_mfma_f32_16x16x32_bf16 v[100:103], v[128:131], v[196:199], v[100:103]
	v_mfma_f32_16x16x32_bf16 v[92:95], v[136:139], v[196:199], v[92:95]
	v_mfma_f32_16x16x32_bf16 v[84:87], v[128:131], v[204:207], v[84:87]
	v_mfma_f32_16x16x32_bf16 v[76:79], v[136:139], v[204:207], v[76:79]
	v_mfma_f32_16x16x32_bf16 v[124:127], v[132:135], v[184:187], v[124:127]
	v_mfma_f32_16x16x32_bf16 v[120:123], v[140:143], v[184:187], v[120:123]
	v_mfma_f32_16x16x32_bf16 v[116:119], v[132:135], v[192:195], v[116:119]
	v_mfma_f32_16x16x32_bf16 v[108:111], v[140:143], v[192:195], v[108:111]
	v_mfma_f32_16x16x32_bf16 v[100:103], v[132:135], v[200:203], v[100:103]
	v_mfma_f32_16x16x32_bf16 v[92:95], v[140:143], v[200:203], v[92:95]
	v_mfma_f32_16x16x32_bf16 v[84:87], v[132:135], v[208:211], v[84:87]
	v_mfma_f32_16x16x32_bf16 v[76:79], v[140:143], v[208:211], v[76:79]
	v_mfma_f32_16x16x32_bf16 v[112:115], v[158:161], v[180:183], v[112:115]
	v_mfma_f32_16x16x32_bf16 v[104:107], v[172:175], v[180:183], v[104:107]
	v_mfma_f32_16x16x32_bf16 v[96:99], v[158:161], v[188:191], v[96:99]
	v_mfma_f32_16x16x32_bf16 v[88:91], v[172:175], v[188:191], v[88:91]
	v_mfma_f32_16x16x32_bf16 v[80:83], v[158:161], v[196:199], v[80:83]
	v_mfma_f32_16x16x32_bf16 v[72:75], v[172:175], v[196:199], v[72:75]
	v_mfma_f32_16x16x32_bf16 v[68:71], v[158:161], v[204:207], v[68:71]
	v_mfma_f32_16x16x32_bf16 v[64:67], v[172:175], v[204:207], v[64:67]
	v_mfma_f32_16x16x32_bf16 v[112:115], v[162:165], v[184:187], v[112:115]
	v_mfma_f32_16x16x32_bf16 v[104:107], v[176:179], v[184:187], v[104:107]
	v_mfma_f32_16x16x32_bf16 v[96:99], v[162:165], v[192:195], v[96:99]
	v_mfma_f32_16x16x32_bf16 v[88:91], v[176:179], v[192:195], v[88:91]
	v_mfma_f32_16x16x32_bf16 v[80:83], v[162:165], v[200:203], v[80:83]
	v_mfma_f32_16x16x32_bf16 v[72:75], v[176:179], v[200:203], v[72:75]
	v_mfma_f32_16x16x32_bf16 v[68:71], v[162:165], v[208:211], v[68:71]
	v_mfma_f32_16x16x32_bf16 v[64:67], v[176:179], v[208:211], v[64:67]
	s_setprio 0
	s_barrier
	s_add_i32 s34, s66, s54
	v_lshl_add_u64 v[212:213], s[48:49], 0, v[146:147]
	s_mov_b32 m0, s34
	ds_read_b128 v[180:183], v171 offset:16384
	ds_read_b128 v[184:187], v171 offset:17408
	ds_read_b128 v[188:191], v171 offset:18432
	ds_read_b128 v[192:195], v171 offset:19456
	ds_read_b128 v[196:199], v171 offset:20480
	ds_read_b128 v[200:203], v171 offset:21504
	ds_read_b128 v[204:207], v171 offset:22528
	ds_read_b128 v[208:211], v171 offset:23552
	global_load_lds_dwordx4 v[212:213], off
	s_add_i32 m0, s34, 0x2000
	s_add_u32 s34, s48, 0x158000
	v_lshl_add_u64 v[214:215], s[48:49], 0, v[150:151]
	s_addc_u32 s35, s49, 0
	s_add_i32 vcc_hi, s67, s54
	global_load_lds_dwordx4 v[214:215], off
	v_lshl_add_u64 v[218:219], s[34:35], 0, v[146:147]
	s_mov_b32 m0, vcc_hi
	v_lshl_add_u64 v[220:221], s[50:51], 0, v[148:149]
	global_load_lds_dwordx4 v[218:219], off
	v_lshl_add_u64 v[218:219], s[34:35], 0, v[150:151]
	s_add_i32 m0, vcc_hi, 0x2000
	s_nop 0
	global_load_lds_dwordx4 v[218:219], off
	v_lshl_add_u64 v[218:219], s[50:51], 0, v[144:145]
	s_mov_b32 m0, s55
	s_nop 0
	global_load_lds_dwordx4 v[218:219], off
	s_mov_b32 m0, s56
	s_nop 0
	global_load_lds_dwordx4 v[220:221], off
	s_waitcnt vmcnt(8)
	s_waitcnt lgkmcnt(0)
	s_barrier
; #define PG8_STAGE(bufoff, gbase, voff) do { _Pragma("unroll") for (int _i = 0; _i < 2; ++_i) \
;         __builtin_amdgcn_global_load_lds((const unsigned*)((const char*)(gbase) + (voff)[_i]), (LAS unsigned*)(lds + (bufoff) + ldsw + _i * 8192), 16, 0, 0); } while (0)
; #define PG8_LDA(dst, b, h) do { _Pragma("unroll") for (int m = 0; m < 4; ++m) _Pragma("unroll") for (int k = 0; k < 2; ++k) dst[m][k] = *(const LAS bf16x8*)(lds + PG8_SA(b, h) + aoff + m * 2048 + k * 1024); } while (0)
; #define PG8_LDB(dst, b, h) do { _Pragma("unroll") for (int n = 0; n < 2; ++n) _Pragma("unroll") for (int k = 0; k < 2; ++k) dst[n][k] = *(const LAS bf16x8*)(lds + PG8_SB(b, h) + boff + n * 2048 + k * 1024); } while (0)
; #define PG8_MMA(ai, bj, At, Bt) do { __builtin_amdgcn_s_setprio(1); _Pragma("unroll") for (int k = 0; k < 2; ++k) _Pragma("unroll") for (int m = 0; m < 4; ++m) _Pragma("unroll") for (int n = 0; n < 2; ++n) \
;         acc[ai][bj][m][n] = __builtin_amdgcn_mfma_f32_16x16x32_bf16(Bt[n][k], At[m][k], acc[ai][bj][m][n], 0, 0, 0); __builtin_amdgcn_s_setprio(0); } while (0)
; #define PG8_WAIT_V(n) asm volatile("s_waitcnt vmcnt(" #n ")" ::: "memory")
; #define PG8_WAIT_L(n) asm volatile("s_waitcnt lgkmcnt(" #n ")" ::: "memory")
; #define PG8_BAR __builtin_amdgcn_s_barrier()
; #define PG8_SCHED __builtin_amdgcn_sched_barrier(0)
; template <class Epi, bool ALIGN_EPI = PG8_ALIGN, bool SP2 = PG8_SP2>
; __device__ __forceinline__ void gemm_phase(LAS unsigned char* lds, const int tid, const int K, const Order& S, const Epi& E) {
;     ...
;             PG8_WAIT_V(8); PG8_WAIT_L(0); PG8_BAR; PG8_MMA(1, 0, At, B0); PG8_MMA(1, 1, At, B1); PG8_BAR; PG8_SCHED;
;             PG8_LDB(B0, 1, 0); PG8_LDB(B1, 1, 1); PG8_SCHED; PG8_LDA(At, 1, 0); PG8_STAGE(PG8_SA(0, 1), a2 + hstep, voffA);
;             PG8_WAIT_V(8); PG8_WAIT_L(0); PG8_BAR; PG8_MMA(0, 0, At, B0); PG8_MMA(0, 1, At, B1); PG8_BAR; PG8_SCHED;
	s_setprio 1
	s_waitcnt lgkmcnt(0)
	v_mfma_f32_16x16x32_bf16 v[60:63], v[128:131], v[180:183], v[60:63]
	v_mfma_f32_16x16x32_bf16 v[56:59], v[136:139], v[180:183], v[56:59]
	v_mfma_f32_16x16x32_bf16 v[52:55], v[128:131], v[188:191], v[52:55]
	v_mfma_f32_16x16x32_bf16 v[44:47], v[136:139], v[188:191], v[44:47]
	v_mfma_f32_16x16x32_bf16 v[36:39], v[128:131], v[196:199], v[36:39]
	v_mfma_f32_16x16x32_bf16 v[28:31], v[136:139], v[196:199], v[28:31]
	v_mfma_f32_16x16x32_bf16 v[20:23], v[128:131], v[204:207], v[20:23]
	v_mfma_f32_16x16x32_bf16 v[12:15], v[136:139], v[204:207], v[12:15]
	v_mfma_f32_16x16x32_bf16 v[60:63], v[132:135], v[184:187], v[60:63]
	v_mfma_f32_16x16x32_bf16 v[56:59], v[140:143], v[184:187], v[56:59]
	v_mfma_f32_16x16x32_bf16 v[52:55], v[132:135], v[192:195], v[52:55]
	v_mfma_f32_16x16x32_bf16 v[44:47], v[140:143], v[192:195], v[44:47]
	v_mfma_f32_16x16x32_bf16 v[36:39], v[132:135], v[200:203], v[36:39]
	v_mfma_f32_16x16x32_bf16 v[28:31], v[140:143], v[200:203], v[28:31]
	v_mfma_f32_16x16x32_bf16 v[20:23], v[132:135], v[208:211], v[20:23]
	v_mfma_f32_16x16x32_bf16 v[12:15], v[140:143], v[208:211], v[12:15]
	v_mfma_f32_16x16x32_bf16 v[48:51], v[158:161], v[180:183], v[48:51]
	v_mfma_f32_16x16x32_bf16 v[40:43], v[172:175], v[180:183], v[40:43]
	v_mfma_f32_16x16x32_bf16 v[32:35], v[158:161], v[188:191], v[32:35]
	v_mfma_f32_16x16x32_bf16 v[24:27], v[172:175], v[188:191], v[24:27]
	v_mfma_f32_16x16x32_bf16 v[16:19], v[158:161], v[196:199], v[16:19]
	v_mfma_f32_16x16x32_bf16 v[8:11], v[172:175], v[196:199], v[8:11]
	v_mfma_f32_16x16x32_bf16 v[4:7], v[158:161], v[204:207], v[4:7]
	v_mfma_f32_16x16x32_bf16 v[0:3], v[172:175], v[204:207], v[0:3]
	v_mfma_f32_16x16x32_bf16 v[48:51], v[162:165], v[184:187], v[48:51]
	v_mfma_f32_16x16x32_bf16 v[40:43], v[176:179], v[184:187], v[40:43]
	v_mfma_f32_16x16x32_bf16 v[32:35], v[162:165], v[192:195], v[32:35]
	v_mfma_f32_16x16x32_bf16 v[24:27], v[176:179], v[192:195], v[24:27]
	v_mfma_f32_16x16x32_bf16 v[16:19], v[162:165], v[200:203], v[16:19]
	v_mfma_f32_16x16x32_bf16 v[8:11], v[176:179], v[200:203], v[8:11]
	v_mfma_f32_16x16x32_bf16 v[4:7], v[162:165], v[208:211], v[4:7]
	v_mfma_f32_16x16x32_bf16 v[0:3], v[176:179], v[208:211], v[0:3]
	s_setprio 0
	s_barrier
	s_add_i32 vcc_hi, 0, 0x18000
	s_add_i32 s40, 0, 0x1c000
	v_add_u32_e32 v140, vcc_hi, v167
	v_add_u32_e32 v176, s40, v167
	ds_read_b128 v[128:131], v140
	ds_read_b128 v[132:135], v140 offset:1024
	ds_read_b128 v[136:139], v140 offset:2048
	ds_read_b128 v[140:143], v140 offset:3072
	ds_read_b128 v[158:161], v176
	ds_read_b128 v[162:165], v176 offset:1024
	ds_read_b128 v[172:175], v176 offset:2048
	ds_read_b128 v[176:179], v176 offset:3072
	s_add_u32 s34, s50, 0x158000
	s_addc_u32 s35, s51, 0
	s_mov_b32 m0, s57
	v_lshl_add_u64 v[222:223], s[34:35], 0, v[144:145]
	ds_read_b128 v[180:183], v171 offset:32768
	ds_read_b128 v[184:187], v171 offset:33792
	ds_read_b128 v[188:191], v171 offset:34816
	ds_read_b128 v[192:195], v171 offset:35840
	ds_read_b128 v[196:199], v171 offset:36864
	ds_read_b128 v[200:203], v171 offset:37888
	ds_read_b128 v[204:207], v171 offset:38912
	ds_read_b128 v[208:211], v171 offset:39936
	global_load_lds_dwordx4 v[222:223], off
	v_lshl_add_u64 v[222:223], s[34:35], 0, v[148:149]
	s_mov_b32 m0, s58
	s_nop 0
	global_load_lds_dwordx4 v[222:223], off
	s_waitcnt vmcnt(8)
	s_waitcnt lgkmcnt(0)
	s_barrier
	s_setprio 1
	s_waitcnt lgkmcnt(0)
	v_mfma_f32_16x16x32_bf16 v[124:127], v[128:131], v[180:183], v[124:127]
	v_mfma_f32_16x16x32_bf16 v[120:123], v[136:139], v[180:183], v[120:123]
	v_mfma_f32_16x16x32_bf16 v[116:119], v[128:131], v[188:191], v[116:119]
	v_mfma_f32_16x16x32_bf16 v[108:111], v[136:139], v[188:191], v[108:111]
	v_mfma_f32_16x16x32_bf16 v[100:103], v[128:131], v[196:199], v[100:103]
	v_mfma_f32_16x16x32_bf16 v[92:95], v[136:139], v[196:199], v[92:95]
	v_mfma_f32_16x16x32_bf16 v[84:87], v[128:131], v[204:207], v[84:87]
	v_mfma_f32_16x16x32_bf16 v[76:79], v[136:139], v[204:207], v[76:79]
	v_mfma_f32_16x16x32_bf16 v[124:127], v[132:135], v[184:187], v[124:127]
	v_mfma_f32_16x16x32_bf16 v[120:123], v[140:143], v[184:187], v[120:123]
	v_mfma_f32_16x16x32_bf16 v[116:119], v[132:135], v[192:195], v[116:119]
	v_mfma_f32_16x16x32_bf16 v[108:111], v[140:143], v[192:195], v[108:111]
	v_mfma_f32_16x16x32_bf16 v[100:103], v[132:135], v[200:203], v[100:103]
	v_mfma_f32_16x16x32_bf16 v[92:95], v[140:143], v[200:203], v[92:95]
	v_mfma_f32_16x16x32_bf16 v[84:87], v[132:135], v[208:211], v[84:87]
	v_mfma_f32_16x16x32_bf16 v[76:79], v[140:143], v[208:211], v[76:79]
	v_mfma_f32_16x16x32_bf16 v[112:115], v[158:161], v[180:183], v[112:115]
	v_mfma_f32_16x16x32_bf16 v[104:107], v[172:175], v[180:183], v[104:107]
	v_mfma_f32_16x16x32_bf16 v[96:99], v[158:161], v[188:191], v[96:99]
	v_mfma_f32_16x16x32_bf16 v[88:91], v[172:175], v[188:191], v[88:91]
	v_mfma_f32_16x16x32_bf16 v[80:83], v[158:161], v[196:199], v[80:83]
	v_mfma_f32_16x16x32_bf16 v[72:75], v[172:175], v[196:199], v[72:75]
	v_mfma_f32_16x16x32_bf16 v[68:71], v[158:161], v[204:207], v[68:71]
	v_mfma_f32_16x16x32_bf16 v[64:67], v[172:175], v[204:207], v[64:67]
	v_mfma_f32_16x16x32_bf16 v[112:115], v[162:165], v[184:187], v[112:115]
	v_mfma_f32_16x16x32_bf16 v[104:107], v[176:179], v[184:187], v[104:107]
	v_mfma_f32_16x16x32_bf16 v[96:99], v[162:165], v[192:195], v[96:99]
	v_mfma_f32_16x16x32_bf16 v[88:91], v[176:179], v[192:195], v[88:91]
	v_mfma_f32_16x16x32_bf16 v[80:83], v[162:165], v[200:203], v[80:83]
	v_mfma_f32_16x16x32_bf16 v[72:75], v[176:179], v[200:203], v[72:75]
	v_mfma_f32_16x16x32_bf16 v[68:71], v[162:165], v[208:211], v[68:71]
	v_mfma_f32_16x16x32_bf16 v[64:67], v[176:179], v[208:211], v[64:67]
	s_setprio 0
	s_barrier
;     __device__ __forceinline__ int nt(const Unit& u) const { return (u.ks < 0 || xsplit == 1) ? ntf : sbase + (u.ks >= sthr ? 2 : 0); }
; #define PG8_STAGE(bufoff, gbase, voff) do { _Pragma("unroll") for (int _i = 0; _i < 2; ++_i) \
;         __builtin_amdgcn_global_load_lds((const unsigned*)((const char*)(gbase) + (voff)[_i]), (LAS unsigned*)(lds + (bufoff) + ldsw + _i * 8192), 16, 0, 0); } while (0)
; #define PG8_LDA(dst, b, h) do { _Pragma("unroll") for (int m = 0; m < 4; ++m) _Pragma("unroll") for (int k = 0; k < 2; ++k) dst[m][k] = *(const LAS bf16x8*)(lds + PG8_SA(b, h) + aoff + m * 2048 + k * 1024); } while (0)
; #define PG8_MMA(ai, bj, At, Bt) do { __builtin_amdgcn_s_setprio(1); _Pragma("unroll") for (int k = 0; k < 2; ++k) _Pragma("unroll") for (int m = 0; m < 4; ++m) _Pragma("unroll") for (int n = 0; n < 2; ++n) \
;         acc[ai][bj][m][n] = __builtin_amdgcn_mfma_f32_16x16x32_bf16(Bt[n][k], At[m][k], acc[ai][bj][m][n], 0, 0, 0); __builtin_amdgcn_s_setprio(0); } while (0)
; #define PG8_WAIT_V(n) asm volatile("s_waitcnt vmcnt(" #n ")" ::: "memory")
; #define PG8_WAIT_L(n) asm volatile("s_waitcnt lgkmcnt(" #n ")" ::: "memory")
; #define PG8_BAR __builtin_amdgcn_s_barrier()
; #define PG8_SCHED __builtin_amdgcn_sched_barrier(0)
; template <class Epi, bool ALIGN_EPI = PG8_ALIGN, bool SP2 = PG8_SP2>
; __device__ __forceinline__ void gemm_phase(LAS unsigned char* lds, const int tid, const int K, const Order& S, const Epi& E) {
;     ...
;         for (int t = 0; t < nt; t += 2) {
;     ...
;             PG8_LDA(At, 1, 1); PG8_STAGE(PG8_SB(1, 0), b3, voffB); PG8_STAGE(PG8_SB(1, 1), b3 + hstep, voffB); PG8_STAGE(PG8_SA(1, 0), a3, voffA);
;             PG8_WAIT_V(8); PG8_WAIT_L(0); PG8_BAR; PG8_MMA(1, 0, At, B0); PG8_MMA(1, 1, At, B1); PG8_BAR; PG8_SCHED;
	s_add_i32 s34, vcc_hi, s54
	v_lshl_add_u64 v[212:213], v[212:213], 0, s[14:15]
	s_mov_b32 m0, s34
	ds_read_b128 v[180:183], v171 offset:49152
	ds_read_b128 v[184:187], v171 offset:50176
	ds_read_b128 v[188:191], v171 offset:51200
	ds_read_b128 v[192:195], v171 offset:52224
	ds_read_b128 v[196:199], v171 offset:53248
	ds_read_b128 v[200:203], v171 offset:54272
	ds_read_b128 v[204:207], v171 offset:55296
	ds_read_b128 v[208:211], v171 offset:56320
	global_load_lds_dwordx4 v[212:213], off
	s_add_i32 m0, s34, 0x2000
	s_add_u32 s34, s48, 0x158080
	v_lshl_add_u64 v[212:213], v[214:215], 0, s[14:15]
	s_addc_u32 s35, s49, 0
	s_add_i32 s40, s40, s54
	global_load_lds_dwordx4 v[212:213], off
	v_lshl_add_u64 v[212:213], s[34:35], 0, v[146:147]
	s_mov_b32 m0, s40
	s_nop 0
	global_load_lds_dwordx4 v[212:213], off
	v_lshl_add_u64 v[212:213], s[34:35], 0, v[150:151]
	s_add_i32 m0, s40, 0x2000
	s_nop 0
	global_load_lds_dwordx4 v[212:213], off
	v_lshl_add_u64 v[212:213], v[218:219], 0, s[14:15]
	s_mov_b32 m0, s61
	s_nop 0
	global_load_lds_dwordx4 v[212:213], off
	v_lshl_add_u64 v[212:213], v[220:221], 0, s[14:15]
	s_mov_b32 m0, s62
	s_nop 0
	global_load_lds_dwordx4 v[212:213], off
	s_waitcnt vmcnt(8)
	s_waitcnt lgkmcnt(0)
	s_barrier
	s_setprio 1
	s_waitcnt lgkmcnt(0)
	v_mfma_f32_16x16x32_bf16 v[60:63], v[128:131], v[180:183], v[60:63]
	v_mfma_f32_16x16x32_bf16 v[56:59], v[136:139], v[180:183], v[56:59]
	v_mfma_f32_16x16x32_bf16 v[52:55], v[128:131], v[188:191], v[52:55]
	v_mfma_f32_16x16x32_bf16 v[44:47], v[136:139], v[188:191], v[44:47]
	v_mfma_f32_16x16x32_bf16 v[36:39], v[128:131], v[196:199], v[36:39]
	v_mfma_f32_16x16x32_bf16 v[28:31], v[136:139], v[196:199], v[28:31]
	v_mfma_f32_16x16x32_bf16 v[20:23], v[128:131], v[204:207], v[20:23]
	v_mfma_f32_16x16x32_bf16 v[12:15], v[136:139], v[204:207], v[12:15]
	v_mfma_f32_16x16x32_bf16 v[60:63], v[132:135], v[184:187], v[60:63]
	v_mfma_f32_16x16x32_bf16 v[56:59], v[140:143], v[184:187], v[56:59]
	v_mfma_f32_16x16x32_bf16 v[52:55], v[132:135], v[192:195], v[52:55]
	v_mfma_f32_16x16x32_bf16 v[44:47], v[140:143], v[192:195], v[44:47]
	v_mfma_f32_16x16x32_bf16 v[36:39], v[132:135], v[200:203], v[36:39]
	v_mfma_f32_16x16x32_bf16 v[28:31], v[140:143], v[200:203], v[28:31]
	v_mfma_f32_16x16x32_bf16 v[20:23], v[132:135], v[208:211], v[20:23]
	v_mfma_f32_16x16x32_bf16 v[12:15], v[140:143], v[208:211], v[12:15]
	v_mfma_f32_16x16x32_bf16 v[48:51], v[158:161], v[180:183], v[48:51]
	v_mfma_f32_16x16x32_bf16 v[40:43], v[172:175], v[180:183], v[40:43]
	v_mfma_f32_16x16x32_bf16 v[32:35], v[158:161], v[188:191], v[32:35]
	v_mfma_f32_16x16x32_bf16 v[24:27], v[172:175], v[188:191], v[24:27]
	v_mfma_f32_16x16x32_bf16 v[16:19], v[158:161], v[196:199], v[16:19]
	v_mfma_f32_16x16x32_bf16 v[8:11], v[172:175], v[196:199], v[8:11]
	v_mfma_f32_16x16x32_bf16 v[4:7], v[158:161], v[204:207], v[4:7]
	v_mfma_f32_16x16x32_bf16 v[0:3], v[172:175], v[204:207], v[0:3]
	v_mfma_f32_16x16x32_bf16 v[48:51], v[162:165], v[184:187], v[48:51]
	v_mfma_f32_16x16x32_bf16 v[40:43], v[176:179], v[184:187], v[40:43]
	v_mfma_f32_16x16x32_bf16 v[32:35], v[162:165], v[192:195], v[32:35]
	v_mfma_f32_16x16x32_bf16 v[24:27], v[176:179], v[192:195], v[24:27]
	v_mfma_f32_16x16x32_bf16 v[16:19], v[162:165], v[200:203], v[16:19]
	v_mfma_f32_16x16x32_bf16 v[8:11], v[176:179], v[200:203], v[8:11]
	v_mfma_f32_16x16x32_bf16 v[4:7], v[162:165], v[208:211], v[4:7]
	v_mfma_f32_16x16x32_bf16 v[0:3], v[176:179], v[208:211], v[0:3]
	s_setprio 0
	s_barrier
	s_add_u32 s96, s96, 0x100
	s_addc_u32 s97, s97, 0
	s_cmp_ge_u32 vcc_lo, s94
	s_mov_b64 s[34:35], s[46:47]
	s_mov_b32 s48, vcc_lo
	s_cbranch_scc0 .LBB0_1118
	s_and_b64 vcc, exec, s[16:17]
	s_cbranch_vccz .LBB0_1121
	s_barrier

;     __device__ __forceinline__ int nt(const Unit& u) const { return (u.ks < 0 || xsplit == 1) ? ntf : sbase + (u.ks >= sthr ? 2 : 0); }
; #define PG8_STAGE(bufoff, gbase, voff) do { _Pragma("unroll") for (int _i = 0; _i < 2; ++_i) \
;         __builtin_amdgcn_global_load_lds((const unsigned*)((const char*)(gbase) + (voff)[_i]), (LAS unsigned*)(lds + (bufoff) + ldsw + _i * 8192), 16, 0, 0); } while (0)
; #define PG8_LDA(dst, b, h) do { _Pragma("unroll") for (int m = 0; m < 4; ++m) _Pragma("unroll") for (int k = 0; k < 2; ++k) dst[m][k] = *(const LAS bf16x8*)(lds + PG8_SA(b, h) + aoff + m * 2048 + k * 1024); } while (0)
; #define PG8_LDB(dst, b, h) do { _Pragma("unroll") for (int n = 0; n < 2; ++n) _Pragma("unroll") for (int k = 0; k < 2; ++k) dst[n][k] = *(const LAS bf16x8*)(lds + PG8_SB(b, h) + boff + n * 2048 + k * 1024); } while (0)
; #define PG8_MMA(ai, bj, At, Bt) do { __builtin_amdgcn_s_setprio(1); _Pragma("unroll") for (int k = 0; k < 2; ++k) _Pragma("unroll") for (int m = 0; m < 4; ++m) _Pragma("unroll") for (int n = 0; n < 2; ++n) \
;         acc[ai][bj][m][n] = __builtin_amdgcn_mfma_f32_16x16x32_bf16(Bt[n][k], At[m][k], acc[ai][bj][m][n], 0, 0, 0); __builtin_amdgcn_s_setprio(0); } while (0)
; #define PG8_BAR __builtin_amdgcn_s_barrier()
; template <class Epi, bool ALIGN_EPI = PG8_ALIGN, bool SP2 = PG8_SP2>
; __device__ __forceinline__ void gemm_phase(LAS unsigned char* lds, const int tid, const int K, const Order& S, const Epi& E) {
;     ...
;             const bool last = (t == nt - 2);
;             const char* a1 = cA + (size_t)(t + 1) * kstep;
;             const char* a2 = last ? nA : cA + (size_t)(t + 2) * kstep; const char* b2 = last ? nB : cB + (size_t)(t + 2) * kstep;
;             const char* a3 = a2 + kstep; const char* b3 = b2 + kstep;
;             if (last && has_next) S.a_ready(nxt, tid);
;             if constexpr (SP2) {
;             PG8_LDB(B0, 0, 0); PG8_LDB(B1, 0, 1); PG8_SCHED; PG8_LDA(At, 0, 0); PG8_STAGE(PG8_SA(1, 1), a1 + hstep, voffA);
;             PG8_WAIT_V(8); PG8_WAIT_L(0); PG8_BAR; PG8_MMA(0, 0, At, B0); PG8_MMA(0, 1, At, B1); PG8_BAR; PG8_SCHED;
;             PG8_LDA(At, 0, 1); PG8_STAGE(PG8_SB(0, 0), b2, voffB); PG8_STAGE(PG8_SB(0, 1), b2 + hstep, voffB); PG8_STAGE(PG8_SA(0, 0), a2, voffA);
;             PG8_WAIT_V(8); PG8_WAIT_L(0); PG8_BAR; PG8_MMA(1, 0, At, B0); PG8_MMA(1, 1, At, B1); PG8_BAR; PG8_SCHED;
.LBB0_1348:
	ds_read_b128 v[142:145], v161
	ds_read_b128 v[146:149], v161 offset:1024
	ds_read_b128 v[150:153], v161 offset:2048
	ds_read_b128 v[154:157], v161 offset:3072
	ds_read_b128 v[164:167], v162
	ds_read_b128 v[168:171], v162 offset:1024
	ds_read_b128 v[172:175], v162 offset:2048
	ds_read_b128 v[176:179], v162 offset:3072
	s_add_i32 s83, s44, 2
	s_add_u32 s40, s34, 0xfff80080
	s_addc_u32 s41, s35, -1
	s_cmp_eq_u32 s23, s44
	s_cselect_b32 s44, s28, s25
	s_cselect_b32 s47, s27, s41
	s_cselect_b32 s46, s26, s40
	s_cselect_b32 s45, s29, s31
	v_lshl_add_u64 v[212:213], s[34:35], 0, v[138:139]
	s_add_i32 m0, s53, 0xc000
	ds_read_b128 v[180:183], v163
	ds_read_b128 v[184:187], v163 offset:1024
	ds_read_b128 v[188:191], v163 offset:2048
	ds_read_b128 v[192:195], v163 offset:3072
	ds_read_b128 v[196:199], v163 offset:4096
	ds_read_b128 v[200:203], v163 offset:5120
	ds_read_b128 v[204:207], v163 offset:6144
	ds_read_b128 v[208:211], v163 offset:7168
	global_load_lds_dwordx4 v[212:213], off
	v_lshl_add_u64 v[212:213], s[34:35], 0, v[136:137]
	s_add_i32 m0, s53, 0xe000
	s_nop 0
	global_load_lds_dwordx4 v[212:213], off
	s_waitcnt vmcnt(8)
	s_waitcnt lgkmcnt(0)
	s_barrier
	s_setprio 1
	s_waitcnt lgkmcnt(0)
	v_mfma_f32_16x16x32_bf16 v[124:127], v[142:145], v[180:183], v[124:127]
	v_mfma_f32_16x16x32_bf16 v[120:123], v[150:153], v[180:183], v[120:123]
	v_mfma_f32_16x16x32_bf16 v[116:119], v[142:145], v[188:191], v[116:119]
	v_mfma_f32_16x16x32_bf16 v[112:115], v[150:153], v[188:191], v[112:115]
	v_mfma_f32_16x16x32_bf16 v[104:107], v[142:145], v[196:199], v[104:107]
	v_mfma_f32_16x16x32_bf16 v[96:99], v[150:153], v[196:199], v[96:99]
	v_mfma_f32_16x16x32_bf16 v[88:91], v[142:145], v[204:207], v[88:91]
	v_mfma_f32_16x16x32_bf16 v[80:83], v[150:153], v[204:207], v[80:83]
	v_mfma_f32_16x16x32_bf16 v[124:127], v[146:149], v[184:187], v[124:127]
	v_mfma_f32_16x16x32_bf16 v[120:123], v[154:157], v[184:187], v[120:123]
	v_mfma_f32_16x16x32_bf16 v[116:119], v[146:149], v[192:195], v[116:119]
	v_mfma_f32_16x16x32_bf16 v[112:115], v[154:157], v[192:195], v[112:115]
	v_mfma_f32_16x16x32_bf16 v[104:107], v[146:149], v[200:203], v[104:107]
	v_mfma_f32_16x16x32_bf16 v[96:99], v[154:157], v[200:203], v[96:99]
	v_mfma_f32_16x16x32_bf16 v[88:91], v[146:149], v[208:211], v[88:91]
	v_mfma_f32_16x16x32_bf16 v[80:83], v[154:157], v[208:211], v[80:83]
	v_mfma_f32_16x16x32_bf16 v[108:111], v[164:167], v[180:183], v[108:111]
	v_mfma_f32_16x16x32_bf16 v[100:103], v[172:175], v[180:183], v[100:103]
	v_mfma_f32_16x16x32_bf16 v[92:95], v[164:167], v[188:191], v[92:95]
	v_mfma_f32_16x16x32_bf16 v[84:87], v[172:175], v[188:191], v[84:87]
	v_mfma_f32_16x16x32_bf16 v[76:79], v[164:167], v[196:199], v[76:79]
	v_mfma_f32_16x16x32_bf16 v[72:75], v[172:175], v[196:199], v[72:75]
	v_mfma_f32_16x16x32_bf16 v[68:71], v[164:167], v[204:207], v[68:71]
	v_mfma_f32_16x16x32_bf16 v[64:67], v[172:175], v[204:207], v[64:67]
	v_mfma_f32_16x16x32_bf16 v[108:111], v[168:171], v[184:187], v[108:111]
	v_mfma_f32_16x16x32_bf16 v[100:103], v[176:179], v[184:187], v[100:103]
	v_mfma_f32_16x16x32_bf16 v[92:95], v[168:171], v[192:195], v[92:95]
	v_mfma_f32_16x16x32_bf16 v[84:87], v[176:179], v[192:195], v[84:87]
	v_mfma_f32_16x16x32_bf16 v[76:79], v[168:171], v[200:203], v[76:79]
	v_mfma_f32_16x16x32_bf16 v[72:75], v[176:179], v[200:203], v[72:75]
	v_mfma_f32_16x16x32_bf16 v[68:71], v[168:171], v[208:211], v[68:71]
	v_mfma_f32_16x16x32_bf16 v[64:67], v[176:179], v[208:211], v[64:67]
	s_setprio 0
	s_barrier
	s_add_i32 s40, s65, s52
	v_lshl_add_u64 v[212:213], s[44:45], 0, v[130:131]
	s_mov_b32 m0, s40
	ds_read_b128 v[180:183], v163 offset:16384
	ds_read_b128 v[184:187], v163 offset:17408
	ds_read_b128 v[188:191], v163 offset:18432
	ds_read_b128 v[192:195], v163 offset:19456
	ds_read_b128 v[196:199], v163 offset:20480
	ds_read_b128 v[200:203], v163 offset:21504
	ds_read_b128 v[204:207], v163 offset:22528
	ds_read_b128 v[208:211], v163 offset:23552
	global_load_lds_dwordx4 v[212:213], off
	s_add_i32 m0, s40, 0x2000
	s_add_u32 s86, s44, 0x80000
	v_lshl_add_u64 v[214:215], s[44:45], 0, v[134:135]
	s_addc_u32 s87, s45, 0
	s_add_i32 s40, s66, s52
	global_load_lds_dwordx4 v[214:215], off
	v_lshl_add_u64 v[218:219], s[86:87], 0, v[130:131]
	s_mov_b32 m0, s40
	v_lshl_add_u64 v[220:221], s[46:47], 0, v[132:133]
	global_load_lds_dwordx4 v[218:219], off
	v_lshl_add_u64 v[218:219], s[86:87], 0, v[134:135]
	s_add_i32 m0, s40, 0x2000
	s_nop 0
	global_load_lds_dwordx4 v[218:219], off
	v_lshl_add_u64 v[218:219], s[46:47], 0, v[128:129]
	s_mov_b32 m0, s53
	s_nop 0
	global_load_lds_dwordx4 v[218:219], off
	s_mov_b32 m0, s54
	s_nop 0
	global_load_lds_dwordx4 v[220:221], off
	s_waitcnt vmcnt(8)
	s_waitcnt lgkmcnt(0)
	s_barrier
; #define PG8_STAGE(bufoff, gbase, voff) do { _Pragma("unroll") for (int _i = 0; _i < 2; ++_i) \
;         __builtin_amdgcn_global_load_lds((const unsigned*)((const char*)(gbase) + (voff)[_i]), (LAS unsigned*)(lds + (bufoff) + ldsw + _i * 8192), 16, 0, 0); } while (0)
; #define PG8_LDA(dst, b, h) do { _Pragma("unroll") for (int m = 0; m < 4; ++m) _Pragma("unroll") for (int k = 0; k < 2; ++k) dst[m][k] = *(const LAS bf16x8*)(lds + PG8_SA(b, h) + aoff + m * 2048 + k * 1024); } while (0)
; #define PG8_LDB(dst, b, h) do { _Pragma("unroll") for (int n = 0; n < 2; ++n) _Pragma("unroll") for (int k = 0; k < 2; ++k) dst[n][k] = *(const LAS bf16x8*)(lds + PG8_SB(b, h) + boff + n * 2048 + k * 1024); } while (0)
; #define PG8_MMA(ai, bj, At, Bt) do { __builtin_amdgcn_s_setprio(1); _Pragma("unroll") for (int k = 0; k < 2; ++k) _Pragma("unroll") for (int m = 0; m < 4; ++m) _Pragma("unroll") for (int n = 0; n < 2; ++n) \
;         acc[ai][bj][m][n] = __builtin_amdgcn_mfma_f32_16x16x32_bf16(Bt[n][k], At[m][k], acc[ai][bj][m][n], 0, 0, 0); __builtin_amdgcn_s_setprio(0); } while (0)
; #define PG8_WAIT_V(n) asm volatile("s_waitcnt vmcnt(" #n ")" ::: "memory")
; #define PG8_WAIT_L(n) asm volatile("s_waitcnt lgkmcnt(" #n ")" ::: "memory")
; #define PG8_BAR __builtin_amdgcn_s_barrier()
; #define PG8_SCHED __builtin_amdgcn_sched_barrier(0)
; template <class Epi, bool ALIGN_EPI = PG8_ALIGN, bool SP2 = PG8_SP2>
; __device__ __forceinline__ void gemm_phase(LAS unsigned char* lds, const int tid, const int K, const Order& S, const Epi& E) {
;     ...
;             PG8_WAIT_V(8); PG8_WAIT_L(0); PG8_BAR; PG8_MMA(1, 0, At, B0); PG8_MMA(1, 1, At, B1); PG8_BAR; PG8_SCHED;
;             PG8_LDB(B0, 1, 0); PG8_LDB(B1, 1, 1); PG8_SCHED; PG8_LDA(At, 1, 0); PG8_STAGE(PG8_SA(0, 1), a2 + hstep, voffA);
;             PG8_WAIT_V(8); PG8_WAIT_L(0); PG8_BAR; PG8_MMA(0, 0, At, B0); PG8_MMA(0, 1, At, B1); PG8_BAR; PG8_SCHED;
	s_setprio 1
	s_waitcnt lgkmcnt(0)
	v_mfma_f32_16x16x32_bf16 v[60:63], v[142:145], v[180:183], v[60:63]
	v_mfma_f32_16x16x32_bf16 v[56:59], v[150:153], v[180:183], v[56:59]
	v_mfma_f32_16x16x32_bf16 v[52:55], v[142:145], v[188:191], v[52:55]
	v_mfma_f32_16x16x32_bf16 v[48:51], v[150:153], v[188:191], v[48:51]
	v_mfma_f32_16x16x32_bf16 v[40:43], v[142:145], v[196:199], v[40:43]
	v_mfma_f32_16x16x32_bf16 v[32:35], v[150:153], v[196:199], v[32:35]
	v_mfma_f32_16x16x32_bf16 v[24:27], v[142:145], v[204:207], v[24:27]
	v_mfma_f32_16x16x32_bf16 v[16:19], v[150:153], v[204:207], v[16:19]
	v_mfma_f32_16x16x32_bf16 v[60:63], v[146:149], v[184:187], v[60:63]
	v_mfma_f32_16x16x32_bf16 v[56:59], v[154:157], v[184:187], v[56:59]
	v_mfma_f32_16x16x32_bf16 v[52:55], v[146:149], v[192:195], v[52:55]
	v_mfma_f32_16x16x32_bf16 v[48:51], v[154:157], v[192:195], v[48:51]
	v_mfma_f32_16x16x32_bf16 v[40:43], v[146:149], v[200:203], v[40:43]
	v_mfma_f32_16x16x32_bf16 v[32:35], v[154:157], v[200:203], v[32:35]
	v_mfma_f32_16x16x32_bf16 v[24:27], v[146:149], v[208:211], v[24:27]
	v_mfma_f32_16x16x32_bf16 v[16:19], v[154:157], v[208:211], v[16:19]
	v_mfma_f32_16x16x32_bf16 v[44:47], v[164:167], v[180:183], v[44:47]
	v_mfma_f32_16x16x32_bf16 v[36:39], v[172:175], v[180:183], v[36:39]
	v_mfma_f32_16x16x32_bf16 v[28:31], v[164:167], v[188:191], v[28:31]
	v_mfma_f32_16x16x32_bf16 v[20:23], v[172:175], v[188:191], v[20:23]
	v_mfma_f32_16x16x32_bf16 v[12:15], v[164:167], v[196:199], v[12:15]
	v_mfma_f32_16x16x32_bf16 v[8:11], v[172:175], v[196:199], v[8:11]
	v_mfma_f32_16x16x32_bf16 v[4:7], v[164:167], v[204:207], v[4:7]
	v_mfma_f32_16x16x32_bf16 v[0:3], v[172:175], v[204:207], v[0:3]
	v_mfma_f32_16x16x32_bf16 v[44:47], v[168:171], v[184:187], v[44:47]
	v_mfma_f32_16x16x32_bf16 v[36:39], v[176:179], v[184:187], v[36:39]
	v_mfma_f32_16x16x32_bf16 v[28:31], v[168:171], v[192:195], v[28:31]
	v_mfma_f32_16x16x32_bf16 v[20:23], v[176:179], v[192:195], v[20:23]
	v_mfma_f32_16x16x32_bf16 v[12:15], v[168:171], v[200:203], v[12:15]
	v_mfma_f32_16x16x32_bf16 v[8:11], v[176:179], v[200:203], v[8:11]
	v_mfma_f32_16x16x32_bf16 v[4:7], v[168:171], v[208:211], v[4:7]
	v_mfma_f32_16x16x32_bf16 v[0:3], v[176:179], v[208:211], v[0:3]
	s_setprio 0
	s_barrier
	s_add_i32 s40, 0, 0x18000
	s_add_i32 s41, 0, 0x1c000
	v_add_u32_e32 v154, s40, v159
	v_add_u32_e32 v176, s41, v159
	ds_read_b128 v[142:145], v154
	ds_read_b128 v[146:149], v154 offset:1024
	ds_read_b128 v[150:153], v154 offset:2048
	ds_read_b128 v[154:157], v154 offset:3072
	ds_read_b128 v[164:167], v176
	ds_read_b128 v[168:171], v176 offset:1024
	ds_read_b128 v[172:175], v176 offset:2048
	ds_read_b128 v[176:179], v176 offset:3072
	s_add_u32 s46, s46, 0x80000
	s_addc_u32 s47, s47, 0
	s_mov_b32 m0, s55
	v_lshl_add_u64 v[222:223], s[46:47], 0, v[128:129]
	ds_read_b128 v[180:183], v163 offset:32768
	ds_read_b128 v[184:187], v163 offset:33792
	ds_read_b128 v[188:191], v163 offset:34816
	ds_read_b128 v[192:195], v163 offset:35840
	ds_read_b128 v[196:199], v163 offset:36864
	ds_read_b128 v[200:203], v163 offset:37888
	ds_read_b128 v[204:207], v163 offset:38912
	ds_read_b128 v[208:211], v163 offset:39936
	global_load_lds_dwordx4 v[222:223], off
	v_lshl_add_u64 v[222:223], s[46:47], 0, v[132:133]
	s_mov_b32 m0, s56
	s_nop 0
	global_load_lds_dwordx4 v[222:223], off
	s_waitcnt vmcnt(8)
	s_waitcnt lgkmcnt(0)
	s_barrier
	s_setprio 1
	s_waitcnt lgkmcnt(0)
	v_mfma_f32_16x16x32_bf16 v[124:127], v[142:145], v[180:183], v[124:127]
	v_mfma_f32_16x16x32_bf16 v[120:123], v[150:153], v[180:183], v[120:123]
	v_mfma_f32_16x16x32_bf16 v[116:119], v[142:145], v[188:191], v[116:119]
	v_mfma_f32_16x16x32_bf16 v[112:115], v[150:153], v[188:191], v[112:115]
	v_mfma_f32_16x16x32_bf16 v[104:107], v[142:145], v[196:199], v[104:107]
	v_mfma_f32_16x16x32_bf16 v[96:99], v[150:153], v[196:199], v[96:99]
	v_mfma_f32_16x16x32_bf16 v[88:91], v[142:145], v[204:207], v[88:91]
	v_mfma_f32_16x16x32_bf16 v[80:83], v[150:153], v[204:207], v[80:83]
	v_mfma_f32_16x16x32_bf16 v[124:127], v[146:149], v[184:187], v[124:127]
	v_mfma_f32_16x16x32_bf16 v[120:123], v[154:157], v[184:187], v[120:123]
	v_mfma_f32_16x16x32_bf16 v[116:119], v[146:149], v[192:195], v[116:119]
	v_mfma_f32_16x16x32_bf16 v[112:115], v[154:157], v[192:195], v[112:115]
	v_mfma_f32_16x16x32_bf16 v[104:107], v[146:149], v[200:203], v[104:107]
	v_mfma_f32_16x16x32_bf16 v[96:99], v[154:157], v[200:203], v[96:99]
	v_mfma_f32_16x16x32_bf16 v[88:91], v[146:149], v[208:211], v[88:91]
	v_mfma_f32_16x16x32_bf16 v[80:83], v[154:157], v[208:211], v[80:83]
	v_mfma_f32_16x16x32_bf16 v[108:111], v[164:167], v[180:183], v[108:111]
	v_mfma_f32_16x16x32_bf16 v[100:103], v[172:175], v[180:183], v[100:103]
	v_mfma_f32_16x16x32_bf16 v[92:95], v[164:167], v[188:191], v[92:95]
	v_mfma_f32_16x16x32_bf16 v[84:87], v[172:175], v[188:191], v[84:87]
	v_mfma_f32_16x16x32_bf16 v[76:79], v[164:167], v[196:199], v[76:79]
	v_mfma_f32_16x16x32_bf16 v[72:75], v[172:175], v[196:199], v[72:75]
	v_mfma_f32_16x16x32_bf16 v[68:71], v[164:167], v[204:207], v[68:71]
	v_mfma_f32_16x16x32_bf16 v[64:67], v[172:175], v[204:207], v[64:67]
	v_mfma_f32_16x16x32_bf16 v[108:111], v[168:171], v[184:187], v[108:111]
	v_mfma_f32_16x16x32_bf16 v[100:103], v[176:179], v[184:187], v[100:103]
	v_mfma_f32_16x16x32_bf16 v[92:95], v[168:171], v[192:195], v[92:95]
	v_mfma_f32_16x16x32_bf16 v[84:87], v[176:179], v[192:195], v[84:87]
	v_mfma_f32_16x16x32_bf16 v[76:79], v[168:171], v[200:203], v[76:79]
	v_mfma_f32_16x16x32_bf16 v[72:75], v[176:179], v[200:203], v[72:75]
	v_mfma_f32_16x16x32_bf16 v[68:71], v[168:171], v[208:211], v[68:71]
	v_mfma_f32_16x16x32_bf16 v[64:67], v[176:179], v[208:211], v[64:67]
	s_setprio 0
	s_barrier
; #define PG8_STAGE(bufoff, gbase, voff) do { _Pragma("unroll") for (int _i = 0; _i < 2; ++_i) \
;         __builtin_amdgcn_global_load_lds((const unsigned*)((const char*)(gbase) + (voff)[_i]), (LAS unsigned*)(lds + (bufoff) + ldsw + _i * 8192), 16, 0, 0); } while (0)
; #define PG8_LDA(dst, b, h) do { _Pragma("unroll") for (int m = 0; m < 4; ++m) _Pragma("unroll") for (int k = 0; k < 2; ++k) dst[m][k] = *(const LAS bf16x8*)(lds + PG8_SA(b, h) + aoff + m * 2048 + k * 1024); } while (0)
; #define PG8_MMA(ai, bj, At, Bt) do { __builtin_amdgcn_s_setprio(1); _Pragma("unroll") for (int k = 0; k < 2; ++k) _Pragma("unroll") for (int m = 0; m < 4; ++m) _Pragma("unroll") for (int n = 0; n < 2; ++n) \
;         acc[ai][bj][m][n] = __builtin_amdgcn_mfma_f32_16x16x32_bf16(Bt[n][k], At[m][k], acc[ai][bj][m][n], 0, 0, 0); __builtin_amdgcn_s_setprio(0); } while (0)
; #define PG8_WAIT_V(n) asm volatile("s_waitcnt vmcnt(" #n ")" ::: "memory")
; #define PG8_WAIT_L(n) asm volatile("s_waitcnt lgkmcnt(" #n ")" ::: "memory")
; #define PG8_BAR __builtin_amdgcn_s_barrier()
; #define PG8_SCHED __builtin_amdgcn_sched_barrier(0)
; template <class Epi, bool ALIGN_EPI = PG8_ALIGN, bool SP2 = PG8_SP2>
; __device__ __forceinline__ void gemm_phase(LAS unsigned char* lds, const int tid, const int K, const Order& S, const Epi& E) {
;     ...
;             PG8_LDA(At, 1, 1); PG8_STAGE(PG8_SB(1, 0), b3, voffB); PG8_STAGE(PG8_SB(1, 1), b3 + hstep, voffB); PG8_STAGE(PG8_SA(1, 0), a3, voffA);
;             PG8_WAIT_V(8); PG8_WAIT_L(0); PG8_BAR; PG8_MMA(1, 0, At, B0); PG8_MMA(1, 1, At, B1); PG8_BAR; PG8_SCHED;
;     ...
;         }
;         if constexpr (ALIGN_EPI) { if (wr == 0) PG8_BAR; }
	s_add_i32 s40, s40, s52
	v_lshl_add_u64 v[212:213], v[212:213], 0, s[18:19]
	s_mov_b32 m0, s40
	ds_read_b128 v[180:183], v163 offset:49152
	ds_read_b128 v[184:187], v163 offset:50176
	ds_read_b128 v[188:191], v163 offset:51200
	ds_read_b128 v[192:195], v163 offset:52224
	ds_read_b128 v[196:199], v163 offset:53248
	ds_read_b128 v[200:203], v163 offset:54272
	ds_read_b128 v[204:207], v163 offset:55296
	ds_read_b128 v[208:211], v163 offset:56320
	global_load_lds_dwordx4 v[212:213], off
	s_add_i32 m0, s40, 0x2000
	s_add_u32 s44, s44, 0x80080
	v_lshl_add_u64 v[212:213], v[214:215], 0, s[18:19]
	s_addc_u32 s45, s45, 0
	s_add_i32 s40, s41, s52
	global_load_lds_dwordx4 v[212:213], off
	v_lshl_add_u64 v[212:213], s[44:45], 0, v[130:131]
	s_mov_b32 m0, s40
	s_nop 0
	global_load_lds_dwordx4 v[212:213], off
	v_lshl_add_u64 v[212:213], s[44:45], 0, v[134:135]
	s_add_i32 m0, s40, 0x2000
	s_nop 0
	global_load_lds_dwordx4 v[212:213], off
	v_lshl_add_u64 v[212:213], v[218:219], 0, s[18:19]
	s_mov_b32 m0, s59
	s_nop 0
	global_load_lds_dwordx4 v[212:213], off
	v_lshl_add_u64 v[212:213], v[220:221], 0, s[18:19]
	s_mov_b32 m0, s60
	s_nop 0
	global_load_lds_dwordx4 v[212:213], off
	s_waitcnt vmcnt(8)
	s_waitcnt lgkmcnt(0)
	s_barrier
	s_setprio 1
	s_waitcnt lgkmcnt(0)
	v_mfma_f32_16x16x32_bf16 v[60:63], v[142:145], v[180:183], v[60:63]
	v_mfma_f32_16x16x32_bf16 v[56:59], v[150:153], v[180:183], v[56:59]
	v_mfma_f32_16x16x32_bf16 v[52:55], v[142:145], v[188:191], v[52:55]
	v_mfma_f32_16x16x32_bf16 v[48:51], v[150:153], v[188:191], v[48:51]
	v_mfma_f32_16x16x32_bf16 v[40:43], v[142:145], v[196:199], v[40:43]
	v_mfma_f32_16x16x32_bf16 v[32:35], v[150:153], v[196:199], v[32:35]
	v_mfma_f32_16x16x32_bf16 v[24:27], v[142:145], v[204:207], v[24:27]
	v_mfma_f32_16x16x32_bf16 v[16:19], v[150:153], v[204:207], v[16:19]
	v_mfma_f32_16x16x32_bf16 v[60:63], v[146:149], v[184:187], v[60:63]
	v_mfma_f32_16x16x32_bf16 v[56:59], v[154:157], v[184:187], v[56:59]
	v_mfma_f32_16x16x32_bf16 v[52:55], v[146:149], v[192:195], v[52:55]
	v_mfma_f32_16x16x32_bf16 v[48:51], v[154:157], v[192:195], v[48:51]
	v_mfma_f32_16x16x32_bf16 v[40:43], v[146:149], v[200:203], v[40:43]
	v_mfma_f32_16x16x32_bf16 v[32:35], v[154:157], v[200:203], v[32:35]
	v_mfma_f32_16x16x32_bf16 v[24:27], v[146:149], v[208:211], v[24:27]
	v_mfma_f32_16x16x32_bf16 v[16:19], v[154:157], v[208:211], v[16:19]
	v_mfma_f32_16x16x32_bf16 v[44:47], v[164:167], v[180:183], v[44:47]
	v_mfma_f32_16x16x32_bf16 v[36:39], v[172:175], v[180:183], v[36:39]
	v_mfma_f32_16x16x32_bf16 v[28:31], v[164:167], v[188:191], v[28:31]
	v_mfma_f32_16x16x32_bf16 v[20:23], v[172:175], v[188:191], v[20:23]
	v_mfma_f32_16x16x32_bf16 v[12:15], v[164:167], v[196:199], v[12:15]
	v_mfma_f32_16x16x32_bf16 v[8:11], v[172:175], v[196:199], v[8:11]
	v_mfma_f32_16x16x32_bf16 v[4:7], v[164:167], v[204:207], v[4:7]
	v_mfma_f32_16x16x32_bf16 v[0:3], v[172:175], v[204:207], v[0:3]
	v_mfma_f32_16x16x32_bf16 v[44:47], v[168:171], v[184:187], v[44:47]
	v_mfma_f32_16x16x32_bf16 v[36:39], v[176:179], v[184:187], v[36:39]
	v_mfma_f32_16x16x32_bf16 v[28:31], v[168:171], v[192:195], v[28:31]
	v_mfma_f32_16x16x32_bf16 v[20:23], v[176:179], v[192:195], v[20:23]
	v_mfma_f32_16x16x32_bf16 v[12:15], v[168:171], v[200:203], v[12:15]
	v_mfma_f32_16x16x32_bf16 v[8:11], v[176:179], v[200:203], v[8:11]
	v_mfma_f32_16x16x32_bf16 v[4:7], v[168:171], v[208:211], v[4:7]
	v_mfma_f32_16x16x32_bf16 v[0:3], v[176:179], v[208:211], v[0:3]
	s_setprio 0
	s_barrier
	s_add_u32 s25, s25, 0x100
	s_addc_u32 s31, s31, 0
	s_add_u32 s34, s34, 0x100
	s_addc_u32 s35, s35, 0
	s_cmp_ge_u32 s83, s7
	s_mov_b32 s44, s83
	s_cbranch_scc0 .LBB0_1348
	s_and_b64 vcc, exec, s[20:21]
	s_cbranch_vccz .LBB0_1351
	s_barrier

;     __device__ __forceinline__ int nt(const Unit& u) const { return (u.ks < 0 || xsplit == 1) ? ntf : sbase + (u.ks >= sthr ? 2 : 0); }
; #define PG8_STAGE(bufoff, gbase, voff) do { _Pragma("unroll") for (int _i = 0; _i < 2; ++_i) \
;         __builtin_amdgcn_global_load_lds((const unsigned*)((const char*)(gbase) + (voff)[_i]), (LAS unsigned*)(lds + (bufoff) + ldsw + _i * 8192), 16, 0, 0); } while (0)
; #define PG8_LDA(dst, b, h) do { _Pragma("unroll") for (int m = 0; m < 4; ++m) _Pragma("unroll") for (int k = 0; k < 2; ++k) dst[m][k] = *(const LAS bf16x8*)(lds + PG8_SA(b, h) + aoff + m * 2048 + k * 1024); } while (0)
; #define PG8_LDB(dst, b, h) do { _Pragma("unroll") for (int n = 0; n < 2; ++n) _Pragma("unroll") for (int k = 0; k < 2; ++k) dst[n][k] = *(const LAS bf16x8*)(lds + PG8_SB(b, h) + boff + n * 2048 + k * 1024); } while (0)
; #define PG8_MMA(ai, bj, At, Bt) do { __builtin_amdgcn_s_setprio(1); _Pragma("unroll") for (int k = 0; k < 2; ++k) _Pragma("unroll") for (int m = 0; m < 4; ++m) _Pragma("unroll") for (int n = 0; n < 2; ++n) \
;         acc[ai][bj][m][n] = __builtin_amdgcn_mfma_f32_16x16x32_bf16(Bt[n][k], At[m][k], acc[ai][bj][m][n], 0, 0, 0); __builtin_amdgcn_s_setprio(0); } while (0)
; #define PG8_BAR __builtin_amdgcn_s_barrier()
; template <class Epi, bool ALIGN_EPI = PG8_ALIGN, bool SP2 = PG8_SP2>
; __device__ __forceinline__ void gemm_phase(LAS unsigned char* lds, const int tid, const int K, const Order& S, const Epi& E) {
;     ...
;             const bool last = (t == nt - 2);
;             const char* a1 = cA + (size_t)(t + 1) * kstep;
;             const char* a2 = last ? nA : cA + (size_t)(t + 2) * kstep; const char* b2 = last ? nB : cB + (size_t)(t + 2) * kstep;
;             const char* a3 = a2 + kstep; const char* b3 = b2 + kstep;
;             if (last && has_next) S.a_ready(nxt, tid);
;             if constexpr (SP2) {
;             PG8_LDB(B0, 0, 0); PG8_LDB(B1, 0, 1); PG8_SCHED; PG8_LDA(At, 0, 0); PG8_STAGE(PG8_SA(1, 1), a1 + hstep, voffA);
;             PG8_WAIT_V(8); PG8_WAIT_L(0); PG8_BAR; PG8_MMA(0, 0, At, B0); PG8_MMA(0, 1, At, B1); PG8_BAR; PG8_SCHED;
;             PG8_LDA(At, 0, 1); PG8_STAGE(PG8_SB(0, 0), b2, voffB); PG8_STAGE(PG8_SB(0, 1), b2 + hstep, voffB); PG8_STAGE(PG8_SA(0, 0), a2, voffA);
;             PG8_WAIT_V(8); PG8_WAIT_L(0); PG8_BAR; PG8_MMA(1, 0, At, B0); PG8_MMA(1, 1, At, B1); PG8_BAR; PG8_SCHED;
.LBB0_1612:
	v_add_u32_e32 v140, s54, v218
	v_add_u32_e32 v156, s55, v218
	ds_read_b128 v[128:131], v140
	ds_read_b128 v[132:135], v140 offset:1024
	ds_read_b128 v[136:139], v140 offset:2048
	ds_read_b128 v[140:143], v140 offset:3072
	ds_read_b128 v[144:147], v156
	ds_read_b128 v[148:151], v156 offset:1024
	ds_read_b128 v[152:155], v156 offset:2048
	ds_read_b128 v[156:159], v156 offset:3072
	s_add_u32 s30, s28, 0xfffc0080
	s_addc_u32 s31, s29, -1
	s_cmp_eq_u32 s76, 12
	s_cselect_b32 s35, s25, s31
	s_cselect_b32 s34, s24, s30
	s_cselect_b32 s31, s21, s75
	s_cselect_b32 s30, s23, s74
	v_lshl_add_u64 v[206:207], s[28:29], 0, v[202:203]
	s_add_i32 m0, s47, 0xc000
	ds_read_b128 v[160:163], v220
	ds_read_b128 v[164:167], v220 offset:1024
	ds_read_b128 v[168:171], v220 offset:2048
	ds_read_b128 v[172:175], v220 offset:3072
	ds_read_b128 v[176:179], v220 offset:4096
	ds_read_b128 v[180:183], v220 offset:5120
	ds_read_b128 v[184:187], v220 offset:6144
	ds_read_b128 v[188:191], v220 offset:7168
	global_load_lds_dwordx4 v[206:207], off
	v_lshl_add_u64 v[206:207], s[28:29], 0, v[200:201]
	s_add_i32 m0, s47, 0xe000
	s_nop 0
	global_load_lds_dwordx4 v[206:207], off
	s_waitcnt vmcnt(8)
	s_waitcnt lgkmcnt(0)
	s_barrier
	s_setprio 1
	s_waitcnt lgkmcnt(0)
	v_mfma_f32_16x16x32_bf16 v[124:127], v[128:131], v[160:163], v[124:127]
	v_mfma_f32_16x16x32_bf16 v[120:123], v[136:139], v[160:163], v[120:123]
	v_mfma_f32_16x16x32_bf16 v[116:119], v[128:131], v[168:171], v[116:119]
	v_mfma_f32_16x16x32_bf16 v[112:115], v[136:139], v[168:171], v[112:115]
	v_mfma_f32_16x16x32_bf16 v[108:111], v[128:131], v[176:179], v[108:111]
	v_mfma_f32_16x16x32_bf16 v[104:107], v[136:139], v[176:179], v[104:107]
	v_mfma_f32_16x16x32_bf16 v[100:103], v[128:131], v[184:187], v[100:103]
	v_mfma_f32_16x16x32_bf16 v[96:99], v[136:139], v[184:187], v[96:99]
	v_mfma_f32_16x16x32_bf16 v[124:127], v[132:135], v[164:167], v[124:127]
	v_mfma_f32_16x16x32_bf16 v[120:123], v[140:143], v[164:167], v[120:123]
	v_mfma_f32_16x16x32_bf16 v[116:119], v[132:135], v[172:175], v[116:119]
	v_mfma_f32_16x16x32_bf16 v[112:115], v[140:143], v[172:175], v[112:115]
	v_mfma_f32_16x16x32_bf16 v[108:111], v[132:135], v[180:183], v[108:111]
	v_mfma_f32_16x16x32_bf16 v[104:107], v[140:143], v[180:183], v[104:107]
	v_mfma_f32_16x16x32_bf16 v[100:103], v[132:135], v[188:191], v[100:103]
	v_mfma_f32_16x16x32_bf16 v[96:99], v[140:143], v[188:191], v[96:99]
	v_mfma_f32_16x16x32_bf16 v[92:95], v[144:147], v[160:163], v[92:95]
	v_mfma_f32_16x16x32_bf16 v[88:91], v[152:155], v[160:163], v[88:91]
	v_mfma_f32_16x16x32_bf16 v[84:87], v[144:147], v[168:171], v[84:87]
	v_mfma_f32_16x16x32_bf16 v[80:83], v[152:155], v[168:171], v[80:83]
	v_mfma_f32_16x16x32_bf16 v[76:79], v[144:147], v[176:179], v[76:79]
	v_mfma_f32_16x16x32_bf16 v[72:75], v[152:155], v[176:179], v[72:75]
	v_mfma_f32_16x16x32_bf16 v[68:71], v[144:147], v[184:187], v[68:71]
	v_mfma_f32_16x16x32_bf16 v[64:67], v[152:155], v[184:187], v[64:67]
	v_mfma_f32_16x16x32_bf16 v[92:95], v[148:151], v[164:167], v[92:95]
	v_mfma_f32_16x16x32_bf16 v[88:91], v[156:159], v[164:167], v[88:91]
	v_mfma_f32_16x16x32_bf16 v[84:87], v[148:151], v[172:175], v[84:87]
	v_mfma_f32_16x16x32_bf16 v[80:83], v[156:159], v[172:175], v[80:83]
	v_mfma_f32_16x16x32_bf16 v[76:79], v[148:151], v[180:183], v[76:79]
	v_mfma_f32_16x16x32_bf16 v[72:75], v[156:159], v[180:183], v[72:75]
	v_mfma_f32_16x16x32_bf16 v[68:71], v[148:151], v[188:191], v[68:71]
	v_mfma_f32_16x16x32_bf16 v[64:67], v[156:159], v[188:191], v[64:67]
	s_setprio 0
	s_barrier
	s_add_i32 s40, s54, s46
	v_lshl_add_u64 v[206:207], s[30:31], 0, v[194:195]
	s_mov_b32 m0, s40
	ds_read_b128 v[160:163], v220 offset:16384
	ds_read_b128 v[164:167], v220 offset:17408
	ds_read_b128 v[168:171], v220 offset:18432
	ds_read_b128 v[172:175], v220 offset:19456
	ds_read_b128 v[176:179], v220 offset:20480
	ds_read_b128 v[180:183], v220 offset:21504
	ds_read_b128 v[184:187], v220 offset:22528
	ds_read_b128 v[188:191], v220 offset:23552
	global_load_lds_dwordx4 v[206:207], off
	s_add_i32 m0, s40, 0x2000
	s_add_u32 s78, s30, 0x40000
	v_lshl_add_u64 v[208:209], s[30:31], 0, v[198:199]
	s_addc_u32 s79, s31, 0
	s_add_i32 s40, s55, s46
	global_load_lds_dwordx4 v[208:209], off
	v_lshl_add_u64 v[212:213], s[78:79], 0, v[194:195]
	s_mov_b32 m0, s40
	v_lshl_add_u64 v[214:215], s[34:35], 0, v[196:197]
	global_load_lds_dwordx4 v[212:213], off
	v_lshl_add_u64 v[212:213], s[78:79], 0, v[198:199]
	s_add_i32 m0, s40, 0x2000
	s_nop 0
	global_load_lds_dwordx4 v[212:213], off
	v_lshl_add_u64 v[212:213], s[34:35], 0, v[192:193]
	s_mov_b32 m0, s47
	s_nop 0
	global_load_lds_dwordx4 v[212:213], off
	s_mov_b32 m0, s48
	s_nop 0
	global_load_lds_dwordx4 v[214:215], off
	s_waitcnt vmcnt(8)
	s_waitcnt lgkmcnt(0)
	s_barrier
; #define PG8_STAGE(bufoff, gbase, voff) do { _Pragma("unroll") for (int _i = 0; _i < 2; ++_i) \
;         __builtin_amdgcn_global_load_lds((const unsigned*)((const char*)(gbase) + (voff)[_i]), (LAS unsigned*)(lds + (bufoff) + ldsw + _i * 8192), 16, 0, 0); } while (0)
; #define PG8_LDA(dst, b, h) do { _Pragma("unroll") for (int m = 0; m < 4; ++m) _Pragma("unroll") for (int k = 0; k < 2; ++k) dst[m][k] = *(const LAS bf16x8*)(lds + PG8_SA(b, h) + aoff + m * 2048 + k * 1024); } while (0)
; #define PG8_LDB(dst, b, h) do { _Pragma("unroll") for (int n = 0; n < 2; ++n) _Pragma("unroll") for (int k = 0; k < 2; ++k) dst[n][k] = *(const LAS bf16x8*)(lds + PG8_SB(b, h) + boff + n * 2048 + k * 1024); } while (0)
; #define PG8_MMA(ai, bj, At, Bt) do { __builtin_amdgcn_s_setprio(1); _Pragma("unroll") for (int k = 0; k < 2; ++k) _Pragma("unroll") for (int m = 0; m < 4; ++m) _Pragma("unroll") for (int n = 0; n < 2; ++n) \
;         acc[ai][bj][m][n] = __builtin_amdgcn_mfma_f32_16x16x32_bf16(Bt[n][k], At[m][k], acc[ai][bj][m][n], 0, 0, 0); __builtin_amdgcn_s_setprio(0); } while (0)
; #define PG8_WAIT_V(n) asm volatile("s_waitcnt vmcnt(" #n ")" ::: "memory")
; #define PG8_WAIT_L(n) asm volatile("s_waitcnt lgkmcnt(" #n ")" ::: "memory")
; #define PG8_BAR __builtin_amdgcn_s_barrier()
; #define PG8_SCHED __builtin_amdgcn_sched_barrier(0)
; template <class Epi, bool ALIGN_EPI = PG8_ALIGN, bool SP2 = PG8_SP2>
; __device__ __forceinline__ void gemm_phase(LAS unsigned char* lds, const int tid, const int K, const Order& S, const Epi& E) {
;     ...
;             PG8_WAIT_V(8); PG8_WAIT_L(0); PG8_BAR; PG8_MMA(1, 0, At, B0); PG8_MMA(1, 1, At, B1); PG8_BAR; PG8_SCHED;
;             PG8_LDB(B0, 1, 0); PG8_LDB(B1, 1, 1); PG8_SCHED; PG8_LDA(At, 1, 0); PG8_STAGE(PG8_SA(0, 1), a2 + hstep, voffA);
;             PG8_WAIT_V(8); PG8_WAIT_L(0); PG8_BAR; PG8_MMA(0, 0, At, B0); PG8_MMA(0, 1, At, B1); PG8_BAR; PG8_SCHED;
	s_setprio 1
	s_waitcnt lgkmcnt(0)
	v_mfma_f32_16x16x32_bf16 v[60:63], v[128:131], v[160:163], v[60:63]
	v_mfma_f32_16x16x32_bf16 v[56:59], v[136:139], v[160:163], v[56:59]
	v_mfma_f32_16x16x32_bf16 v[52:55], v[128:131], v[168:171], v[52:55]
	v_mfma_f32_16x16x32_bf16 v[48:51], v[136:139], v[168:171], v[48:51]
	v_mfma_f32_16x16x32_bf16 v[44:47], v[128:131], v[176:179], v[44:47]
	v_mfma_f32_16x16x32_bf16 v[40:43], v[136:139], v[176:179], v[40:43]
	v_mfma_f32_16x16x32_bf16 v[36:39], v[128:131], v[184:187], v[36:39]
	v_mfma_f32_16x16x32_bf16 v[32:35], v[136:139], v[184:187], v[32:35]
	v_mfma_f32_16x16x32_bf16 v[60:63], v[132:135], v[164:167], v[60:63]
	v_mfma_f32_16x16x32_bf16 v[56:59], v[140:143], v[164:167], v[56:59]
	v_mfma_f32_16x16x32_bf16 v[52:55], v[132:135], v[172:175], v[52:55]
	v_mfma_f32_16x16x32_bf16 v[48:51], v[140:143], v[172:175], v[48:51]
	v_mfma_f32_16x16x32_bf16 v[44:47], v[132:135], v[180:183], v[44:47]
	v_mfma_f32_16x16x32_bf16 v[40:43], v[140:143], v[180:183], v[40:43]
	v_mfma_f32_16x16x32_bf16 v[36:39], v[132:135], v[188:191], v[36:39]
	v_mfma_f32_16x16x32_bf16 v[32:35], v[140:143], v[188:191], v[32:35]
	v_mfma_f32_16x16x32_bf16 v[28:31], v[144:147], v[160:163], v[28:31]
	v_mfma_f32_16x16x32_bf16 v[24:27], v[152:155], v[160:163], v[24:27]
	v_mfma_f32_16x16x32_bf16 v[20:23], v[144:147], v[168:171], v[20:23]
	v_mfma_f32_16x16x32_bf16 v[16:19], v[152:155], v[168:171], v[16:19]
	v_mfma_f32_16x16x32_bf16 v[12:15], v[144:147], v[176:179], v[12:15]
	v_mfma_f32_16x16x32_bf16 v[8:11], v[152:155], v[176:179], v[8:11]
	v_mfma_f32_16x16x32_bf16 v[4:7], v[144:147], v[184:187], v[4:7]
	v_mfma_f32_16x16x32_bf16 v[0:3], v[152:155], v[184:187], v[0:3]
	v_mfma_f32_16x16x32_bf16 v[28:31], v[148:151], v[164:167], v[28:31]
	v_mfma_f32_16x16x32_bf16 v[24:27], v[156:159], v[164:167], v[24:27]
	v_mfma_f32_16x16x32_bf16 v[20:23], v[148:151], v[172:175], v[20:23]
	v_mfma_f32_16x16x32_bf16 v[16:19], v[156:159], v[172:175], v[16:19]
	v_mfma_f32_16x16x32_bf16 v[12:15], v[148:151], v[180:183], v[12:15]
	v_mfma_f32_16x16x32_bf16 v[8:11], v[156:159], v[180:183], v[8:11]
	v_mfma_f32_16x16x32_bf16 v[4:7], v[148:151], v[188:191], v[4:7]
	v_mfma_f32_16x16x32_bf16 v[0:3], v[156:159], v[188:191], v[0:3]
	s_setprio 0
	s_barrier
	s_add_i32 s40, 0, 0x18000
	s_add_i32 s41, 0, 0x1c000
	v_add_u32_e32 v140, s40, v218
	v_add_u32_e32 v156, s41, v218
	ds_read_b128 v[128:131], v140
	ds_read_b128 v[132:135], v140 offset:1024
	ds_read_b128 v[136:139], v140 offset:2048
	ds_read_b128 v[140:143], v140 offset:3072
	ds_read_b128 v[144:147], v156
	ds_read_b128 v[148:151], v156 offset:1024
	ds_read_b128 v[152:155], v156 offset:2048
	ds_read_b128 v[156:159], v156 offset:3072
	s_add_u32 s34, s34, 0x40000
	s_addc_u32 s35, s35, 0
	s_mov_b32 m0, s49
	v_lshl_add_u64 v[222:223], s[34:35], 0, v[192:193]
	ds_read_b128 v[160:163], v220 offset:32768
	ds_read_b128 v[164:167], v220 offset:33792
	ds_read_b128 v[168:171], v220 offset:34816
	ds_read_b128 v[172:175], v220 offset:35840
	ds_read_b128 v[176:179], v220 offset:36864
	ds_read_b128 v[180:183], v220 offset:37888
	ds_read_b128 v[184:187], v220 offset:38912
	ds_read_b128 v[188:191], v220 offset:39936
	global_load_lds_dwordx4 v[222:223], off
	v_lshl_add_u64 v[222:223], s[34:35], 0, v[196:197]
	s_mov_b32 m0, s50
	s_nop 0
	global_load_lds_dwordx4 v[222:223], off
	s_waitcnt vmcnt(8)
	s_waitcnt lgkmcnt(0)
	s_barrier
	s_setprio 1
	s_waitcnt lgkmcnt(0)
	v_mfma_f32_16x16x32_bf16 v[124:127], v[128:131], v[160:163], v[124:127]
	v_mfma_f32_16x16x32_bf16 v[120:123], v[136:139], v[160:163], v[120:123]
	v_mfma_f32_16x16x32_bf16 v[116:119], v[128:131], v[168:171], v[116:119]
	v_mfma_f32_16x16x32_bf16 v[112:115], v[136:139], v[168:171], v[112:115]
	v_mfma_f32_16x16x32_bf16 v[108:111], v[128:131], v[176:179], v[108:111]
	v_mfma_f32_16x16x32_bf16 v[104:107], v[136:139], v[176:179], v[104:107]
	v_mfma_f32_16x16x32_bf16 v[100:103], v[128:131], v[184:187], v[100:103]
	v_mfma_f32_16x16x32_bf16 v[96:99], v[136:139], v[184:187], v[96:99]
	v_mfma_f32_16x16x32_bf16 v[124:127], v[132:135], v[164:167], v[124:127]
	v_mfma_f32_16x16x32_bf16 v[120:123], v[140:143], v[164:167], v[120:123]
	v_mfma_f32_16x16x32_bf16 v[116:119], v[132:135], v[172:175], v[116:119]
	v_mfma_f32_16x16x32_bf16 v[112:115], v[140:143], v[172:175], v[112:115]
	v_mfma_f32_16x16x32_bf16 v[108:111], v[132:135], v[180:183], v[108:111]
	v_mfma_f32_16x16x32_bf16 v[104:107], v[140:143], v[180:183], v[104:107]
	v_mfma_f32_16x16x32_bf16 v[100:103], v[132:135], v[188:191], v[100:103]
	v_mfma_f32_16x16x32_bf16 v[96:99], v[140:143], v[188:191], v[96:99]
	v_mfma_f32_16x16x32_bf16 v[92:95], v[144:147], v[160:163], v[92:95]
	v_mfma_f32_16x16x32_bf16 v[88:91], v[152:155], v[160:163], v[88:91]
	v_mfma_f32_16x16x32_bf16 v[84:87], v[144:147], v[168:171], v[84:87]
	v_mfma_f32_16x16x32_bf16 v[80:83], v[152:155], v[168:171], v[80:83]
	v_mfma_f32_16x16x32_bf16 v[76:79], v[144:147], v[176:179], v[76:79]
	v_mfma_f32_16x16x32_bf16 v[72:75], v[152:155], v[176:179], v[72:75]
	v_mfma_f32_16x16x32_bf16 v[68:71], v[144:147], v[184:187], v[68:71]
	v_mfma_f32_16x16x32_bf16 v[64:67], v[152:155], v[184:187], v[64:67]
	v_mfma_f32_16x16x32_bf16 v[92:95], v[148:151], v[164:167], v[92:95]
	v_mfma_f32_16x16x32_bf16 v[88:91], v[156:159], v[164:167], v[88:91]
	v_mfma_f32_16x16x32_bf16 v[84:87], v[148:151], v[172:175], v[84:87]
	v_mfma_f32_16x16x32_bf16 v[80:83], v[156:159], v[172:175], v[80:83]
	v_mfma_f32_16x16x32_bf16 v[76:79], v[148:151], v[180:183], v[76:79]
	v_mfma_f32_16x16x32_bf16 v[72:75], v[156:159], v[180:183], v[72:75]
	v_mfma_f32_16x16x32_bf16 v[68:71], v[148:151], v[188:191], v[68:71]
	v_mfma_f32_16x16x32_bf16 v[64:67], v[156:159], v[188:191], v[64:67]
	s_setprio 0
	s_barrier
; #define PG8_STAGE(bufoff, gbase, voff) do { _Pragma("unroll") for (int _i = 0; _i < 2; ++_i) \
;         __builtin_amdgcn_global_load_lds((const unsigned*)((const char*)(gbase) + (voff)[_i]), (LAS unsigned*)(lds + (bufoff) + ldsw + _i * 8192), 16, 0, 0); } while (0)
; #define PG8_LDA(dst, b, h) do { _Pragma("unroll") for (int m = 0; m < 4; ++m) _Pragma("unroll") for (int k = 0; k < 2; ++k) dst[m][k] = *(const LAS bf16x8*)(lds + PG8_SA(b, h) + aoff + m * 2048 + k * 1024); } while (0)
; #define PG8_MMA(ai, bj, At, Bt) do { __builtin_amdgcn_s_setprio(1); _Pragma("unroll") for (int k = 0; k < 2; ++k) _Pragma("unroll") for (int m = 0; m < 4; ++m) _Pragma("unroll") for (int n = 0; n < 2; ++n) \
;         acc[ai][bj][m][n] = __builtin_amdgcn_mfma_f32_16x16x32_bf16(Bt[n][k], At[m][k], acc[ai][bj][m][n], 0, 0, 0); __builtin_amdgcn_s_setprio(0); } while (0)
; #define PG8_WAIT_V(n) asm volatile("s_waitcnt vmcnt(" #n ")" ::: "memory")
; #define PG8_WAIT_L(n) asm volatile("s_waitcnt lgkmcnt(" #n ")" ::: "memory")
; #define PG8_BAR __builtin_amdgcn_s_barrier()
; #define PG8_SCHED __builtin_amdgcn_sched_barrier(0)
; template <class Epi, bool ALIGN_EPI = PG8_ALIGN, bool SP2 = PG8_SP2>
; __device__ __forceinline__ void gemm_phase(LAS unsigned char* lds, const int tid, const int K, const Order& S, const Epi& E) {
;     ...
;             PG8_LDA(At, 1, 1); PG8_STAGE(PG8_SB(1, 0), b3, voffB); PG8_STAGE(PG8_SB(1, 1), b3 + hstep, voffB); PG8_STAGE(PG8_SA(1, 0), a3, voffA);
;             PG8_WAIT_V(8); PG8_WAIT_L(0); PG8_BAR; PG8_MMA(1, 0, At, B0); PG8_MMA(1, 1, At, B1); PG8_BAR; PG8_SCHED;
;     ...
;         }
;         if constexpr (ALIGN_EPI) { if (wr == 0) PG8_BAR; }
	s_add_i32 s34, s40, s46
	v_lshl_add_u64 v[206:207], v[206:207], 0, s[14:15]
	s_mov_b32 m0, s34
	ds_read_b128 v[160:163], v220 offset:49152
	ds_read_b128 v[164:167], v220 offset:50176
	ds_read_b128 v[168:171], v220 offset:51200
	ds_read_b128 v[172:175], v220 offset:52224
	ds_read_b128 v[176:179], v220 offset:53248
	ds_read_b128 v[180:183], v220 offset:54272
	ds_read_b128 v[184:187], v220 offset:55296
	ds_read_b128 v[188:191], v220 offset:56320
	global_load_lds_dwordx4 v[206:207], off
	s_add_i32 m0, s34, 0x2000
	s_add_u32 s30, s30, 0x40080
	v_lshl_add_u64 v[206:207], v[208:209], 0, s[14:15]
	s_addc_u32 s31, s31, 0
	s_add_i32 s34, s41, s46
	global_load_lds_dwordx4 v[206:207], off
	v_lshl_add_u64 v[206:207], s[30:31], 0, v[194:195]
	s_mov_b32 m0, s34
	s_nop 0
	global_load_lds_dwordx4 v[206:207], off
	v_lshl_add_u64 v[206:207], s[30:31], 0, v[198:199]
	s_add_i32 m0, s34, 0x2000
	s_nop 0
	global_load_lds_dwordx4 v[206:207], off
	v_lshl_add_u64 v[206:207], v[212:213], 0, s[14:15]
	s_mov_b32 m0, s52
	s_nop 0
	global_load_lds_dwordx4 v[206:207], off
	v_lshl_add_u64 v[206:207], v[214:215], 0, s[14:15]
	s_mov_b32 m0, s53
	s_nop 0
	global_load_lds_dwordx4 v[206:207], off
	s_waitcnt vmcnt(8)
	s_waitcnt lgkmcnt(0)
	s_barrier
	s_setprio 1
	s_waitcnt lgkmcnt(0)
	v_mfma_f32_16x16x32_bf16 v[60:63], v[128:131], v[160:163], v[60:63]
	v_mfma_f32_16x16x32_bf16 v[56:59], v[136:139], v[160:163], v[56:59]
	v_mfma_f32_16x16x32_bf16 v[52:55], v[128:131], v[168:171], v[52:55]
	v_mfma_f32_16x16x32_bf16 v[48:51], v[136:139], v[168:171], v[48:51]
	v_mfma_f32_16x16x32_bf16 v[44:47], v[128:131], v[176:179], v[44:47]
	v_mfma_f32_16x16x32_bf16 v[40:43], v[136:139], v[176:179], v[40:43]
	v_mfma_f32_16x16x32_bf16 v[36:39], v[128:131], v[184:187], v[36:39]
	v_mfma_f32_16x16x32_bf16 v[32:35], v[136:139], v[184:187], v[32:35]
	v_mfma_f32_16x16x32_bf16 v[60:63], v[132:135], v[164:167], v[60:63]
	v_mfma_f32_16x16x32_bf16 v[56:59], v[140:143], v[164:167], v[56:59]
	v_mfma_f32_16x16x32_bf16 v[52:55], v[132:135], v[172:175], v[52:55]
	v_mfma_f32_16x16x32_bf16 v[48:51], v[140:143], v[172:175], v[48:51]
	v_mfma_f32_16x16x32_bf16 v[44:47], v[132:135], v[180:183], v[44:47]
	v_mfma_f32_16x16x32_bf16 v[40:43], v[140:143], v[180:183], v[40:43]
	v_mfma_f32_16x16x32_bf16 v[36:39], v[132:135], v[188:191], v[36:39]
	v_mfma_f32_16x16x32_bf16 v[32:35], v[140:143], v[188:191], v[32:35]
	v_mfma_f32_16x16x32_bf16 v[28:31], v[144:147], v[160:163], v[28:31]
	v_mfma_f32_16x16x32_bf16 v[24:27], v[152:155], v[160:163], v[24:27]
	v_mfma_f32_16x16x32_bf16 v[20:23], v[144:147], v[168:171], v[20:23]
	v_mfma_f32_16x16x32_bf16 v[16:19], v[152:155], v[168:171], v[16:19]
	v_mfma_f32_16x16x32_bf16 v[12:15], v[144:147], v[176:179], v[12:15]
	v_mfma_f32_16x16x32_bf16 v[8:11], v[152:155], v[176:179], v[8:11]
	v_mfma_f32_16x16x32_bf16 v[4:7], v[144:147], v[184:187], v[4:7]
	v_mfma_f32_16x16x32_bf16 v[0:3], v[152:155], v[184:187], v[0:3]
	v_mfma_f32_16x16x32_bf16 v[28:31], v[148:151], v[164:167], v[28:31]
	v_mfma_f32_16x16x32_bf16 v[24:27], v[156:159], v[164:167], v[24:27]
	v_mfma_f32_16x16x32_bf16 v[20:23], v[148:151], v[172:175], v[20:23]
	v_mfma_f32_16x16x32_bf16 v[16:19], v[156:159], v[172:175], v[16:19]
	v_mfma_f32_16x16x32_bf16 v[12:15], v[148:151], v[180:183], v[12:15]
	v_mfma_f32_16x16x32_bf16 v[8:11], v[156:159], v[180:183], v[8:11]
	v_mfma_f32_16x16x32_bf16 v[4:7], v[148:151], v[188:191], v[4:7]
	v_mfma_f32_16x16x32_bf16 v[0:3], v[156:159], v[188:191], v[0:3]
	s_setprio 0
	s_barrier
	s_add_i32 s76, s76, 2
	s_add_u32 s74, s74, 0x100
	s_addc_u32 s75, s75, 0
	s_add_u32 s28, s28, 0x100
	s_addc_u32 s29, s29, 0
	s_cmp_gt_u32 s76, 13
	s_cbranch_scc0 .LBB0_1612
	s_and_b64 vcc, exec, s[16:17]
	s_cbranch_vccz .LBB0_1615
	s_barrier

;     __device__ __forceinline__ int nt(const Unit& u) const { return (u.ks < 0 || xsplit == 1) ? ntf : sbase + (u.ks >= sthr ? 2 : 0); }
; #define PG8_STAGE(bufoff, gbase, voff) do { _Pragma("unroll") for (int _i = 0; _i < 2; ++_i) \
;         __builtin_amdgcn_global_load_lds((const unsigned*)((const char*)(gbase) + (voff)[_i]), (LAS unsigned*)(lds + (bufoff) + ldsw + _i * 8192), 16, 0, 0); } while (0)
; #define PG8_LDA(dst, b, h) do { _Pragma("unroll") for (int m = 0; m < 4; ++m) _Pragma("unroll") for (int k = 0; k < 2; ++k) dst[m][k] = *(const LAS bf16x8*)(lds + PG8_SA(b, h) + aoff + m * 2048 + k * 1024); } while (0)
; #define PG8_LDB(dst, b, h) do { _Pragma("unroll") for (int n = 0; n < 2; ++n) _Pragma("unroll") for (int k = 0; k < 2; ++k) dst[n][k] = *(const LAS bf16x8*)(lds + PG8_SB(b, h) + boff + n * 2048 + k * 1024); } while (0)
; #define PG8_MMA(ai, bj, At, Bt) do { __builtin_amdgcn_s_setprio(1); _Pragma("unroll") for (int k = 0; k < 2; ++k) _Pragma("unroll") for (int m = 0; m < 4; ++m) _Pragma("unroll") for (int n = 0; n < 2; ++n) \
;         acc[ai][bj][m][n] = __builtin_amdgcn_mfma_f32_16x16x32_bf16(Bt[n][k], At[m][k], acc[ai][bj][m][n], 0, 0, 0); __builtin_amdgcn_s_setprio(0); } while (0)
; #define PG8_BAR __builtin_amdgcn_s_barrier()
; template <class Epi, bool ALIGN_EPI = PG8_ALIGN, bool SP2 = PG8_SP2>
; __device__ __forceinline__ void gemm_phase(LAS unsigned char* lds, const int tid, const int K, const Order& S, const Epi& E) {
;     ...
;             const bool last = (t == nt - 2);
;             const char* a1 = cA + (size_t)(t + 1) * kstep;
;             const char* a2 = last ? nA : cA + (size_t)(t + 2) * kstep; const char* b2 = last ? nB : cB + (size_t)(t + 2) * kstep;
;             const char* a3 = a2 + kstep; const char* b3 = b2 + kstep;
;             if (last && has_next) S.a_ready(nxt, tid);
;             if constexpr (SP2) {
;             PG8_LDB(B0, 0, 0); PG8_LDB(B1, 0, 1); PG8_SCHED; PG8_LDA(At, 0, 0); PG8_STAGE(PG8_SA(1, 1), a1 + hstep, voffA);
;             PG8_WAIT_V(8); PG8_WAIT_L(0); PG8_BAR; PG8_MMA(0, 0, At, B0); PG8_MMA(0, 1, At, B1); PG8_BAR; PG8_SCHED;
;             PG8_LDA(At, 0, 1); PG8_STAGE(PG8_SB(0, 0), b2, voffB); PG8_STAGE(PG8_SB(0, 1), b2 + hstep, voffB); PG8_STAGE(PG8_SA(0, 0), a2, voffA);
;             PG8_WAIT_V(8); PG8_WAIT_L(0); PG8_BAR; PG8_MMA(1, 0, At, B0); PG8_MMA(1, 1, At, B1); PG8_BAR; PG8_SCHED;
.LBB0_1690:
	ds_read_b128 v[120:123], v167
	ds_read_b128 v[124:127], v167 offset:1024
	ds_read_b128 v[128:131], v167 offset:2048
	ds_read_b128 v[132:135], v167 offset:3072
	ds_read_b128 v[158:161], v168
	ds_read_b128 v[170:173], v168 offset:1024
	ds_read_b128 v[174:177], v168 offset:2048
	ds_read_b128 v[178:181], v168 offset:3072
	s_add_u32 s40, s42, 0xfff80080
	s_addc_u32 s41, s43, -1
	s_cmp_eq_u32 s75, 28
	s_cselect_b32 s47, s27, s41
	s_cselect_b32 s46, s71, s40
	s_cselect_b32 s45, s25, s74
	s_cselect_b32 s44, s72, s73
	v_lshl_add_u64 v[162:163], s[42:43], 0, v[154:155]
	s_add_i32 m0, s37, 0xc000
	ds_read_b128 v[182:185], v169
	ds_read_b128 v[186:189], v169 offset:1024
	ds_read_b128 v[190:193], v169 offset:2048
	ds_read_b128 v[194:197], v169 offset:3072
	ds_read_b128 v[198:201], v169 offset:4096
	ds_read_b128 v[202:205], v169 offset:5120
	ds_read_b128 v[206:209], v169 offset:6144
	ds_read_b128 v[210:213], v169 offset:7168
	global_load_lds_dwordx4 v[162:163], off
	v_lshl_add_u64 v[162:163], s[42:43], 0, v[152:153]
	s_add_i32 m0, s37, 0xe000
	s_nop 0
	global_load_lds_dwordx4 v[162:163], off
	s_waitcnt vmcnt(8)
	s_waitcnt lgkmcnt(0)
	s_barrier
	s_setprio 1
	s_waitcnt lgkmcnt(0)
	v_mfma_f32_16x16x32_bf16 v[140:143], v[120:123], v[182:185], v[140:143]
	v_mfma_f32_16x16x32_bf16 v[136:139], v[128:131], v[182:185], v[136:139]
	v_mfma_f32_16x16x32_bf16 v[116:119], v[120:123], v[190:193], v[116:119]
	v_mfma_f32_16x16x32_bf16 v[104:107], v[128:131], v[190:193], v[104:107]
	v_mfma_f32_16x16x32_bf16 v[100:103], v[120:123], v[198:201], v[100:103]
	v_mfma_f32_16x16x32_bf16 v[88:91], v[128:131], v[198:201], v[88:91]
	v_mfma_f32_16x16x32_bf16 v[84:87], v[120:123], v[206:209], v[84:87]
	v_mfma_f32_16x16x32_bf16 v[72:75], v[128:131], v[206:209], v[72:75]
	v_mfma_f32_16x16x32_bf16 v[140:143], v[124:127], v[186:189], v[140:143]
	v_mfma_f32_16x16x32_bf16 v[136:139], v[132:135], v[186:189], v[136:139]
	v_mfma_f32_16x16x32_bf16 v[116:119], v[124:127], v[194:197], v[116:119]
	v_mfma_f32_16x16x32_bf16 v[104:107], v[132:135], v[194:197], v[104:107]
	v_mfma_f32_16x16x32_bf16 v[100:103], v[124:127], v[202:205], v[100:103]
	v_mfma_f32_16x16x32_bf16 v[88:91], v[132:135], v[202:205], v[88:91]
	v_mfma_f32_16x16x32_bf16 v[84:87], v[124:127], v[210:213], v[84:87]
	v_mfma_f32_16x16x32_bf16 v[72:75], v[132:135], v[210:213], v[72:75]
	v_mfma_f32_16x16x32_bf16 v[112:115], v[158:161], v[182:185], v[112:115]
	v_mfma_f32_16x16x32_bf16 v[108:111], v[174:177], v[182:185], v[108:111]
	v_mfma_f32_16x16x32_bf16 v[96:99], v[158:161], v[190:193], v[96:99]
	v_mfma_f32_16x16x32_bf16 v[92:95], v[174:177], v[190:193], v[92:95]
	v_mfma_f32_16x16x32_bf16 v[80:83], v[158:161], v[198:201], v[80:83]
	v_mfma_f32_16x16x32_bf16 v[76:79], v[174:177], v[198:201], v[76:79]
	v_mfma_f32_16x16x32_bf16 v[68:71], v[158:161], v[206:209], v[68:71]
	v_mfma_f32_16x16x32_bf16 v[64:67], v[174:177], v[206:209], v[64:67]
	v_mfma_f32_16x16x32_bf16 v[112:115], v[170:173], v[186:189], v[112:115]
	v_mfma_f32_16x16x32_bf16 v[108:111], v[178:181], v[186:189], v[108:111]
	v_mfma_f32_16x16x32_bf16 v[96:99], v[170:173], v[194:197], v[96:99]
	v_mfma_f32_16x16x32_bf16 v[92:95], v[178:181], v[194:197], v[92:95]
	v_mfma_f32_16x16x32_bf16 v[80:83], v[170:173], v[202:205], v[80:83]
	v_mfma_f32_16x16x32_bf16 v[76:79], v[178:181], v[202:205], v[76:79]
	v_mfma_f32_16x16x32_bf16 v[68:71], v[170:173], v[210:213], v[68:71]
	v_mfma_f32_16x16x32_bf16 v[64:67], v[178:181], v[210:213], v[64:67]
	s_setprio 0
	s_barrier
	s_add_i32 s40, s63, s54
	v_lshl_add_u64 v[162:163], s[44:45], 0, v[146:147]
	s_mov_b32 m0, s40
	ds_read_b128 v[182:185], v169 offset:16384
	ds_read_b128 v[186:189], v169 offset:17408
	ds_read_b128 v[190:193], v169 offset:18432
	ds_read_b128 v[194:197], v169 offset:19456
	ds_read_b128 v[198:201], v169 offset:20480
	ds_read_b128 v[202:205], v169 offset:21504
	ds_read_b128 v[206:209], v169 offset:22528
	ds_read_b128 v[210:213], v169 offset:23552
	global_load_lds_dwordx4 v[162:163], off
	s_add_i32 m0, s40, 0x2000
	s_add_u32 s76, s44, 0x80000
	v_lshl_add_u64 v[214:215], s[44:45], 0, v[150:151]
	s_addc_u32 s77, s45, 0
	s_add_i32 s40, s64, s54
	global_load_lds_dwordx4 v[214:215], off
	v_lshl_add_u64 v[218:219], s[76:77], 0, v[146:147]
	s_mov_b32 m0, s40
	v_lshl_add_u64 v[220:221], s[46:47], 0, v[148:149]
	global_load_lds_dwordx4 v[218:219], off
	v_lshl_add_u64 v[218:219], s[76:77], 0, v[150:151]
	s_add_i32 m0, s40, 0x2000
	s_nop 0
	global_load_lds_dwordx4 v[218:219], off
	v_lshl_add_u64 v[218:219], s[46:47], 0, v[144:145]
	s_mov_b32 m0, s37
	s_nop 0
	global_load_lds_dwordx4 v[218:219], off
	s_mov_b32 m0, s55
	s_nop 0
	global_load_lds_dwordx4 v[220:221], off
	s_waitcnt vmcnt(8)
	s_waitcnt lgkmcnt(0)
	s_barrier
; #define PG8_STAGE(bufoff, gbase, voff) do { _Pragma("unroll") for (int _i = 0; _i < 2; ++_i) \
;         __builtin_amdgcn_global_load_lds((const unsigned*)((const char*)(gbase) + (voff)[_i]), (LAS unsigned*)(lds + (bufoff) + ldsw + _i * 8192), 16, 0, 0); } while (0)
; #define PG8_LDA(dst, b, h) do { _Pragma("unroll") for (int m = 0; m < 4; ++m) _Pragma("unroll") for (int k = 0; k < 2; ++k) dst[m][k] = *(const LAS bf16x8*)(lds + PG8_SA(b, h) + aoff + m * 2048 + k * 1024); } while (0)
; #define PG8_LDB(dst, b, h) do { _Pragma("unroll") for (int n = 0; n < 2; ++n) _Pragma("unroll") for (int k = 0; k < 2; ++k) dst[n][k] = *(const LAS bf16x8*)(lds + PG8_SB(b, h) + boff + n * 2048 + k * 1024); } while (0)
; #define PG8_MMA(ai, bj, At, Bt) do { __builtin_amdgcn_s_setprio(1); _Pragma("unroll") for (int k = 0; k < 2; ++k) _Pragma("unroll") for (int m = 0; m < 4; ++m) _Pragma("unroll") for (int n = 0; n < 2; ++n) \
;         acc[ai][bj][m][n] = __builtin_amdgcn_mfma_f32_16x16x32_bf16(Bt[n][k], At[m][k], acc[ai][bj][m][n], 0, 0, 0); __builtin_amdgcn_s_setprio(0); } while (0)
; #define PG8_WAIT_V(n) asm volatile("s_waitcnt vmcnt(" #n ")" ::: "memory")
; #define PG8_WAIT_L(n) asm volatile("s_waitcnt lgkmcnt(" #n ")" ::: "memory")
; #define PG8_BAR __builtin_amdgcn_s_barrier()
; #define PG8_SCHED __builtin_amdgcn_sched_barrier(0)
; template <class Epi, bool ALIGN_EPI = PG8_ALIGN, bool SP2 = PG8_SP2>
; __device__ __forceinline__ void gemm_phase(LAS unsigned char* lds, const int tid, const int K, const Order& S, const Epi& E) {
;     ...
;             PG8_WAIT_V(8); PG8_WAIT_L(0); PG8_BAR; PG8_MMA(1, 0, At, B0); PG8_MMA(1, 1, At, B1); PG8_BAR; PG8_SCHED;
;             PG8_LDB(B0, 1, 0); PG8_LDB(B1, 1, 1); PG8_SCHED; PG8_LDA(At, 1, 0); PG8_STAGE(PG8_SA(0, 1), a2 + hstep, voffA);
;             PG8_WAIT_V(8); PG8_WAIT_L(0); PG8_BAR; PG8_MMA(0, 0, At, B0); PG8_MMA(0, 1, At, B1); PG8_BAR; PG8_SCHED;
	s_setprio 1
	s_waitcnt lgkmcnt(0)
	v_mfma_f32_16x16x32_bf16 v[60:63], v[120:123], v[182:185], v[60:63]
	v_mfma_f32_16x16x32_bf16 v[56:59], v[128:131], v[182:185], v[56:59]
	v_mfma_f32_16x16x32_bf16 v[48:51], v[120:123], v[190:193], v[48:51]
	v_mfma_f32_16x16x32_bf16 v[40:43], v[128:131], v[190:193], v[40:43]
	v_mfma_f32_16x16x32_bf16 v[32:35], v[120:123], v[198:201], v[32:35]
	v_mfma_f32_16x16x32_bf16 v[24:27], v[128:131], v[198:201], v[24:27]
	v_mfma_f32_16x16x32_bf16 v[16:19], v[120:123], v[206:209], v[16:19]
	v_mfma_f32_16x16x32_bf16 v[8:11], v[128:131], v[206:209], v[8:11]
	v_mfma_f32_16x16x32_bf16 v[60:63], v[124:127], v[186:189], v[60:63]
	v_mfma_f32_16x16x32_bf16 v[56:59], v[132:135], v[186:189], v[56:59]
	v_mfma_f32_16x16x32_bf16 v[48:51], v[124:127], v[194:197], v[48:51]
	v_mfma_f32_16x16x32_bf16 v[40:43], v[132:135], v[194:197], v[40:43]
	v_mfma_f32_16x16x32_bf16 v[32:35], v[124:127], v[202:205], v[32:35]
	v_mfma_f32_16x16x32_bf16 v[24:27], v[132:135], v[202:205], v[24:27]
	v_mfma_f32_16x16x32_bf16 v[16:19], v[124:127], v[210:213], v[16:19]
	v_mfma_f32_16x16x32_bf16 v[8:11], v[132:135], v[210:213], v[8:11]
	v_mfma_f32_16x16x32_bf16 v[52:55], v[158:161], v[182:185], v[52:55]
	v_mfma_f32_16x16x32_bf16 v[44:47], v[174:177], v[182:185], v[44:47]
	v_mfma_f32_16x16x32_bf16 v[36:39], v[158:161], v[190:193], v[36:39]
	v_mfma_f32_16x16x32_bf16 v[28:31], v[174:177], v[190:193], v[28:31]
	v_mfma_f32_16x16x32_bf16 v[20:23], v[158:161], v[198:201], v[20:23]
	v_mfma_f32_16x16x32_bf16 v[12:15], v[174:177], v[198:201], v[12:15]
	v_mfma_f32_16x16x32_bf16 v[4:7], v[158:161], v[206:209], v[4:7]
	v_mfma_f32_16x16x32_bf16 v[0:3], v[174:177], v[206:209], v[0:3]
	v_mfma_f32_16x16x32_bf16 v[52:55], v[170:173], v[186:189], v[52:55]
	v_mfma_f32_16x16x32_bf16 v[44:47], v[178:181], v[186:189], v[44:47]
	v_mfma_f32_16x16x32_bf16 v[36:39], v[170:173], v[194:197], v[36:39]
	v_mfma_f32_16x16x32_bf16 v[28:31], v[178:181], v[194:197], v[28:31]
	v_mfma_f32_16x16x32_bf16 v[20:23], v[170:173], v[202:205], v[20:23]
	v_mfma_f32_16x16x32_bf16 v[12:15], v[178:181], v[202:205], v[12:15]
	v_mfma_f32_16x16x32_bf16 v[4:7], v[170:173], v[210:213], v[4:7]
	v_mfma_f32_16x16x32_bf16 v[0:3], v[178:181], v[210:213], v[0:3]
	s_setprio 0
	s_barrier
	s_add_i32 s40, 0, 0x18000
	s_add_i32 s41, 0, 0x1c000
	v_add_u32_e32 v132, s40, v165
	v_add_u32_e32 v178, s41, v165
	ds_read_b128 v[120:123], v132
	ds_read_b128 v[124:127], v132 offset:1024
	ds_read_b128 v[128:131], v132 offset:2048
	ds_read_b128 v[132:135], v132 offset:3072
	ds_read_b128 v[158:161], v178
	ds_read_b128 v[170:173], v178 offset:1024
	ds_read_b128 v[174:177], v178 offset:2048
	ds_read_b128 v[178:181], v178 offset:3072
	s_add_u32 s46, s46, 0x80000
	s_addc_u32 s47, s47, 0
	s_mov_b32 m0, s56
	v_lshl_add_u64 v[222:223], s[46:47], 0, v[144:145]
	ds_read_b128 v[182:185], v169 offset:32768
	ds_read_b128 v[186:189], v169 offset:33792
	ds_read_b128 v[190:193], v169 offset:34816
	ds_read_b128 v[194:197], v169 offset:35840
	ds_read_b128 v[198:201], v169 offset:36864
	ds_read_b128 v[202:205], v169 offset:37888
	ds_read_b128 v[206:209], v169 offset:38912
	ds_read_b128 v[210:213], v169 offset:39936
	global_load_lds_dwordx4 v[222:223], off
	v_lshl_add_u64 v[222:223], s[46:47], 0, v[148:149]
	s_mov_b32 m0, s57
	s_nop 0
	global_load_lds_dwordx4 v[222:223], off
	s_waitcnt vmcnt(8)
	s_waitcnt lgkmcnt(0)
	s_barrier
	s_setprio 1
	s_waitcnt lgkmcnt(0)
	v_mfma_f32_16x16x32_bf16 v[140:143], v[120:123], v[182:185], v[140:143]
	v_mfma_f32_16x16x32_bf16 v[136:139], v[128:131], v[182:185], v[136:139]
	v_mfma_f32_16x16x32_bf16 v[116:119], v[120:123], v[190:193], v[116:119]
	v_mfma_f32_16x16x32_bf16 v[104:107], v[128:131], v[190:193], v[104:107]
	v_mfma_f32_16x16x32_bf16 v[100:103], v[120:123], v[198:201], v[100:103]
	v_mfma_f32_16x16x32_bf16 v[88:91], v[128:131], v[198:201], v[88:91]
	v_mfma_f32_16x16x32_bf16 v[84:87], v[120:123], v[206:209], v[84:87]
	v_mfma_f32_16x16x32_bf16 v[72:75], v[128:131], v[206:209], v[72:75]
	v_mfma_f32_16x16x32_bf16 v[140:143], v[124:127], v[186:189], v[140:143]
	v_mfma_f32_16x16x32_bf16 v[136:139], v[132:135], v[186:189], v[136:139]
	v_mfma_f32_16x16x32_bf16 v[116:119], v[124:127], v[194:197], v[116:119]
	v_mfma_f32_16x16x32_bf16 v[104:107], v[132:135], v[194:197], v[104:107]
	v_mfma_f32_16x16x32_bf16 v[100:103], v[124:127], v[202:205], v[100:103]
	v_mfma_f32_16x16x32_bf16 v[88:91], v[132:135], v[202:205], v[88:91]
	v_mfma_f32_16x16x32_bf16 v[84:87], v[124:127], v[210:213], v[84:87]
	v_mfma_f32_16x16x32_bf16 v[72:75], v[132:135], v[210:213], v[72:75]
	v_mfma_f32_16x16x32_bf16 v[112:115], v[158:161], v[182:185], v[112:115]
	v_mfma_f32_16x16x32_bf16 v[108:111], v[174:177], v[182:185], v[108:111]
	v_mfma_f32_16x16x32_bf16 v[96:99], v[158:161], v[190:193], v[96:99]
	v_mfma_f32_16x16x32_bf16 v[92:95], v[174:177], v[190:193], v[92:95]
	v_mfma_f32_16x16x32_bf16 v[80:83], v[158:161], v[198:201], v[80:83]
	v_mfma_f32_16x16x32_bf16 v[76:79], v[174:177], v[198:201], v[76:79]
	v_mfma_f32_16x16x32_bf16 v[68:71], v[158:161], v[206:209], v[68:71]
	v_mfma_f32_16x16x32_bf16 v[64:67], v[174:177], v[206:209], v[64:67]
	v_mfma_f32_16x16x32_bf16 v[112:115], v[170:173], v[186:189], v[112:115]
	v_mfma_f32_16x16x32_bf16 v[108:111], v[178:181], v[186:189], v[108:111]
	v_mfma_f32_16x16x32_bf16 v[96:99], v[170:173], v[194:197], v[96:99]
	v_mfma_f32_16x16x32_bf16 v[92:95], v[178:181], v[194:197], v[92:95]
	v_mfma_f32_16x16x32_bf16 v[80:83], v[170:173], v[202:205], v[80:83]
	v_mfma_f32_16x16x32_bf16 v[76:79], v[178:181], v[202:205], v[76:79]
	v_mfma_f32_16x16x32_bf16 v[68:71], v[170:173], v[210:213], v[68:71]
	v_mfma_f32_16x16x32_bf16 v[64:67], v[178:181], v[210:213], v[64:67]
	s_setprio 0
	s_barrier
; #define PG8_STAGE(bufoff, gbase, voff) do { _Pragma("unroll") for (int _i = 0; _i < 2; ++_i) \
;         __builtin_amdgcn_global_load_lds((const unsigned*)((const char*)(gbase) + (voff)[_i]), (LAS unsigned*)(lds + (bufoff) + ldsw + _i * 8192), 16, 0, 0); } while (0)
; #define PG8_LDA(dst, b, h) do { _Pragma("unroll") for (int m = 0; m < 4; ++m) _Pragma("unroll") for (int k = 0; k < 2; ++k) dst[m][k] = *(const LAS bf16x8*)(lds + PG8_SA(b, h) + aoff + m * 2048 + k * 1024); } while (0)
; #define PG8_MMA(ai, bj, At, Bt) do { __builtin_amdgcn_s_setprio(1); _Pragma("unroll") for (int k = 0; k < 2; ++k) _Pragma("unroll") for (int m = 0; m < 4; ++m) _Pragma("unroll") for (int n = 0; n < 2; ++n) \
;         acc[ai][bj][m][n] = __builtin_amdgcn_mfma_f32_16x16x32_bf16(Bt[n][k], At[m][k], acc[ai][bj][m][n], 0, 0, 0); __builtin_amdgcn_s_setprio(0); } while (0)
; #define PG8_WAIT_V(n) asm volatile("s_waitcnt vmcnt(" #n ")" ::: "memory")
; #define PG8_WAIT_L(n) asm volatile("s_waitcnt lgkmcnt(" #n ")" ::: "memory")
; #define PG8_BAR __builtin_amdgcn_s_barrier()
; #define PG8_SCHED __builtin_amdgcn_sched_barrier(0)
; template <class Epi, bool ALIGN_EPI = PG8_ALIGN, bool SP2 = PG8_SP2>
; __device__ __forceinline__ void gemm_phase(LAS unsigned char* lds, const int tid, const int K, const Order& S, const Epi& E) {
;     ...
;             PG8_LDA(At, 1, 1); PG8_STAGE(PG8_SB(1, 0), b3, voffB); PG8_STAGE(PG8_SB(1, 1), b3 + hstep, voffB); PG8_STAGE(PG8_SA(1, 0), a3, voffA);
;             PG8_WAIT_V(8); PG8_WAIT_L(0); PG8_BAR; PG8_MMA(1, 0, At, B0); PG8_MMA(1, 1, At, B1); PG8_BAR; PG8_SCHED;
;     ...
;         }
;         if constexpr (ALIGN_EPI) { if (wr == 0) PG8_BAR; }
	s_add_i32 s40, s40, s54
	v_lshl_add_u64 v[162:163], v[162:163], 0, s[10:11]
	s_mov_b32 m0, s40
	ds_read_b128 v[182:185], v169 offset:49152
	ds_read_b128 v[186:189], v169 offset:50176
	ds_read_b128 v[190:193], v169 offset:51200
	ds_read_b128 v[194:197], v169 offset:52224
	ds_read_b128 v[198:201], v169 offset:53248
	ds_read_b128 v[202:205], v169 offset:54272
	ds_read_b128 v[206:209], v169 offset:55296
	ds_read_b128 v[210:213], v169 offset:56320
	global_load_lds_dwordx4 v[162:163], off
	s_add_i32 m0, s40, 0x2000
	s_add_u32 s44, s44, 0x80080
	v_lshl_add_u64 v[162:163], v[214:215], 0, s[10:11]
	s_addc_u32 s45, s45, 0
	s_add_i32 s40, s41, s54
	global_load_lds_dwordx4 v[162:163], off
	v_lshl_add_u64 v[162:163], s[44:45], 0, v[146:147]
	s_mov_b32 m0, s40
	s_nop 0
	global_load_lds_dwordx4 v[162:163], off
	v_lshl_add_u64 v[162:163], s[44:45], 0, v[150:151]
	s_add_i32 m0, s40, 0x2000
	s_nop 0
	global_load_lds_dwordx4 v[162:163], off
	v_lshl_add_u64 v[162:163], v[218:219], 0, s[10:11]
	s_mov_b32 m0, s59
	s_nop 0
	global_load_lds_dwordx4 v[162:163], off
	v_lshl_add_u64 v[162:163], v[220:221], 0, s[10:11]
	s_mov_b32 m0, s60
	s_nop 0
	global_load_lds_dwordx4 v[162:163], off
	s_waitcnt vmcnt(8)
	s_waitcnt lgkmcnt(0)
	s_barrier
	s_setprio 1
	s_waitcnt lgkmcnt(0)
	v_mfma_f32_16x16x32_bf16 v[60:63], v[120:123], v[182:185], v[60:63]
	v_mfma_f32_16x16x32_bf16 v[56:59], v[128:131], v[182:185], v[56:59]
	v_mfma_f32_16x16x32_bf16 v[48:51], v[120:123], v[190:193], v[48:51]
	v_mfma_f32_16x16x32_bf16 v[40:43], v[128:131], v[190:193], v[40:43]
	v_mfma_f32_16x16x32_bf16 v[32:35], v[120:123], v[198:201], v[32:35]
	v_mfma_f32_16x16x32_bf16 v[24:27], v[128:131], v[198:201], v[24:27]
	v_mfma_f32_16x16x32_bf16 v[16:19], v[120:123], v[206:209], v[16:19]
	v_mfma_f32_16x16x32_bf16 v[8:11], v[128:131], v[206:209], v[8:11]
	v_mfma_f32_16x16x32_bf16 v[60:63], v[124:127], v[186:189], v[60:63]
	v_mfma_f32_16x16x32_bf16 v[56:59], v[132:135], v[186:189], v[56:59]
	v_mfma_f32_16x16x32_bf16 v[48:51], v[124:127], v[194:197], v[48:51]
	v_mfma_f32_16x16x32_bf16 v[40:43], v[132:135], v[194:197], v[40:43]
	v_mfma_f32_16x16x32_bf16 v[32:35], v[124:127], v[202:205], v[32:35]
	v_mfma_f32_16x16x32_bf16 v[24:27], v[132:135], v[202:205], v[24:27]
	v_mfma_f32_16x16x32_bf16 v[16:19], v[124:127], v[210:213], v[16:19]
	v_mfma_f32_16x16x32_bf16 v[8:11], v[132:135], v[210:213], v[8:11]
	v_mfma_f32_16x16x32_bf16 v[52:55], v[158:161], v[182:185], v[52:55]
	v_mfma_f32_16x16x32_bf16 v[44:47], v[174:177], v[182:185], v[44:47]
	v_mfma_f32_16x16x32_bf16 v[36:39], v[158:161], v[190:193], v[36:39]
	v_mfma_f32_16x16x32_bf16 v[28:31], v[174:177], v[190:193], v[28:31]
	v_mfma_f32_16x16x32_bf16 v[20:23], v[158:161], v[198:201], v[20:23]
	v_mfma_f32_16x16x32_bf16 v[12:15], v[174:177], v[198:201], v[12:15]
	v_mfma_f32_16x16x32_bf16 v[4:7], v[158:161], v[206:209], v[4:7]
	v_mfma_f32_16x16x32_bf16 v[0:3], v[174:177], v[206:209], v[0:3]
	v_mfma_f32_16x16x32_bf16 v[52:55], v[170:173], v[186:189], v[52:55]
	v_mfma_f32_16x16x32_bf16 v[44:47], v[178:181], v[186:189], v[44:47]
	v_mfma_f32_16x16x32_bf16 v[36:39], v[170:173], v[194:197], v[36:39]
	v_mfma_f32_16x16x32_bf16 v[28:31], v[178:181], v[194:197], v[28:31]
	v_mfma_f32_16x16x32_bf16 v[20:23], v[170:173], v[202:205], v[20:23]
	v_mfma_f32_16x16x32_bf16 v[12:15], v[178:181], v[202:205], v[12:15]
	v_mfma_f32_16x16x32_bf16 v[4:7], v[170:173], v[210:213], v[4:7]
	v_mfma_f32_16x16x32_bf16 v[0:3], v[178:181], v[210:213], v[0:3]
	s_setprio 0
	s_barrier
	s_add_i32 s75, s75, 2
	s_add_u32 s73, s73, 0x100
	s_addc_u32 s74, s74, 0
	s_add_u32 s42, s42, 0x100
	s_addc_u32 s43, s43, 0
	s_cmp_gt_u32 s75, 29
	s_cbranch_scc0 .LBB0_1690
	s_and_b64 vcc, exec, s[14:15]
	s_cbranch_vccz .LBB0_1693
	s_barrier

;     __device__ __forceinline__ int nt(const Unit& u) const { return (u.ks < 0 || xsplit == 1) ? ntf : sbase + (u.ks >= sthr ? 2 : 0); }
; #define PG8_STAGE(bufoff, gbase, voff) do { _Pragma("unroll") for (int _i = 0; _i < 2; ++_i) \
;         __builtin_amdgcn_global_load_lds((const unsigned*)((const char*)(gbase) + (voff)[_i]), (LAS unsigned*)(lds + (bufoff) + ldsw + _i * 8192), 16, 0, 0); } while (0)
; #define PG8_LDA(dst, b, h) do { _Pragma("unroll") for (int m = 0; m < 4; ++m) _Pragma("unroll") for (int k = 0; k < 2; ++k) dst[m][k] = *(const LAS bf16x8*)(lds + PG8_SA(b, h) + aoff + m * 2048 + k * 1024); } while (0)
; #define PG8_LDB(dst, b, h) do { _Pragma("unroll") for (int n = 0; n < 2; ++n) _Pragma("unroll") for (int k = 0; k < 2; ++k) dst[n][k] = *(const LAS bf16x8*)(lds + PG8_SB(b, h) + boff + n * 2048 + k * 1024); } while (0)
; #define PG8_MMA(ai, bj, At, Bt) do { __builtin_amdgcn_s_setprio(1); _Pragma("unroll") for (int k = 0; k < 2; ++k) _Pragma("unroll") for (int m = 0; m < 4; ++m) _Pragma("unroll") for (int n = 0; n < 2; ++n) \
;         acc[ai][bj][m][n] = __builtin_amdgcn_mfma_f32_16x16x32_bf16(Bt[n][k], At[m][k], acc[ai][bj][m][n], 0, 0, 0); __builtin_amdgcn_s_setprio(0); } while (0)
; #define PG8_BAR __builtin_amdgcn_s_barrier()
; template <class Epi, bool ALIGN_EPI = PG8_ALIGN, bool SP2 = PG8_SP2>
; __device__ __forceinline__ void gemm_phase(LAS unsigned char* lds, const int tid, const int K, const Order& S, const Epi& E) {
;     ...
;             const bool last = (t == nt - 2);
;             const char* a1 = cA + (size_t)(t + 1) * kstep;
;             const char* a2 = last ? nA : cA + (size_t)(t + 2) * kstep; const char* b2 = last ? nB : cB + (size_t)(t + 2) * kstep;
;             const char* a3 = a2 + kstep; const char* b3 = b2 + kstep;
;             if (last && has_next) S.a_ready(nxt, tid);
;             if constexpr (SP2) {
;             PG8_LDB(B0, 0, 0); PG8_LDB(B1, 0, 1); PG8_SCHED; PG8_LDA(At, 0, 0); PG8_STAGE(PG8_SA(1, 1), a1 + hstep, voffA);
;             PG8_WAIT_V(8); PG8_WAIT_L(0); PG8_BAR; PG8_MMA(0, 0, At, B0); PG8_MMA(0, 1, At, B1); PG8_BAR; PG8_SCHED;
;             PG8_LDA(At, 0, 1); PG8_STAGE(PG8_SB(0, 0), b2, voffB); PG8_STAGE(PG8_SB(0, 1), b2 + hstep, voffB); PG8_STAGE(PG8_SA(0, 0), a2, voffA);
;             PG8_WAIT_V(8); PG8_WAIT_L(0); PG8_BAR; PG8_MMA(1, 0, At, B0); PG8_MMA(1, 1, At, B1); PG8_BAR; PG8_SCHED;
.LBB0_1808:
	ds_read_b128 v[48:51], v221
	ds_read_b128 v[52:55], v221 offset:1024
	ds_read_b128 v[56:59], v221 offset:2048
	ds_read_b128 v[60:63], v221 offset:3072
	ds_read_b128 v[72:75], v222
	ds_read_b128 v[76:79], v222 offset:1024
	ds_read_b128 v[136:139], v222 offset:2048
	ds_read_b128 v[140:143], v222 offset:3072
	s_add_u32 s40, s48, 0xfff80080
	s_addc_u32 s41, s49, -1
	s_cmp_eq_u32 s79, 28
	s_cselect_b32 s53, s31, s41
	s_cselect_b32 s52, s45, s40
	s_cselect_b32 s51, s29, s78
	s_cselect_b32 s50, s76, s77
	v_lshl_add_u64 v[206:207], s[48:49], 0, v[194:195]
	s_add_i32 m0, s47, 0xc000
	ds_read_b128 v[144:147], v223
	ds_read_b128 v[148:151], v223 offset:1024
	ds_read_b128 v[152:155], v223 offset:2048
	ds_read_b128 v[160:163], v223 offset:3072
	ds_read_b128 v[176:179], v223 offset:4096
	ds_read_b128 v[180:183], v223 offset:5120
	ds_read_b128 v[198:201], v223 offset:6144
	ds_read_b128 v[202:205], v223 offset:7168
	global_load_lds_dwordx4 v[206:207], off
	v_lshl_add_u64 v[206:207], s[48:49], 0, v[192:193]
	s_add_i32 m0, s47, 0xe000
	s_nop 0
	global_load_lds_dwordx4 v[206:207], off
	s_waitcnt vmcnt(8)
	s_waitcnt lgkmcnt(0)
	s_barrier
	s_setprio 1
	s_waitcnt lgkmcnt(0)
	v_mfma_f32_16x16x32_bf16 v[172:175], v[48:51], v[144:147], v[172:175]
	v_mfma_f32_16x16x32_bf16 v[84:87], v[56:59], v[144:147], v[84:87]
	v_mfma_f32_16x16x32_bf16 v[164:167], v[48:51], v[152:155], v[164:167]
	v_mfma_f32_16x16x32_bf16 v[68:71], v[56:59], v[152:155], v[68:71]
	v_mfma_f32_16x16x32_bf16 v[132:135], v[48:51], v[176:179], v[132:135]
	v_mfma_f32_16x16x32_bf16 v[44:47], v[56:59], v[176:179], v[44:47]
	v_mfma_f32_16x16x32_bf16 v[124:127], v[48:51], v[198:201], v[124:127]
	v_mfma_f32_16x16x32_bf16 v[36:39], v[56:59], v[198:201], v[36:39]
	v_mfma_f32_16x16x32_bf16 v[172:175], v[52:55], v[148:151], v[172:175]
	v_mfma_f32_16x16x32_bf16 v[84:87], v[60:63], v[148:151], v[84:87]
	v_mfma_f32_16x16x32_bf16 v[164:167], v[52:55], v[160:163], v[164:167]
	v_mfma_f32_16x16x32_bf16 v[68:71], v[60:63], v[160:163], v[68:71]
	v_mfma_f32_16x16x32_bf16 v[132:135], v[52:55], v[180:183], v[132:135]
	v_mfma_f32_16x16x32_bf16 v[44:47], v[60:63], v[180:183], v[44:47]
	v_mfma_f32_16x16x32_bf16 v[124:127], v[52:55], v[202:205], v[124:127]
	v_mfma_f32_16x16x32_bf16 v[36:39], v[60:63], v[202:205], v[36:39]
	v_mfma_f32_16x16x32_bf16 v[80:83], v[136:139], v[144:147], v[80:83]
	v_mfma_f32_16x16x32_bf16 v[64:67], v[136:139], v[152:155], v[64:67]
	v_mfma_f32_16x16x32_bf16 v[128:131], v[72:75], v[176:179], v[128:131]
	v_mfma_f32_16x16x32_bf16 v[40:43], v[136:139], v[176:179], v[40:43]
	v_mfma_f32_16x16x32_bf16 v[120:123], v[72:75], v[198:201], v[120:123]
	v_mfma_f32_16x16x32_bf16 v[32:35], v[136:139], v[198:201], v[32:35]
	v_mfma_f32_16x16x32_bf16 v[168:171], v[72:75], v[144:147], v[168:171]
	v_mfma_f32_16x16x32_bf16 v[144:147], v[72:75], v[152:155], v[156:159]
	v_mfma_f32_16x16x32_bf16 v[80:83], v[140:143], v[148:151], v[80:83]
	v_mfma_f32_16x16x32_bf16 v[64:67], v[140:143], v[160:163], v[64:67]
	v_mfma_f32_16x16x32_bf16 v[128:131], v[76:79], v[180:183], v[128:131]
	v_mfma_f32_16x16x32_bf16 v[40:43], v[140:143], v[180:183], v[40:43]
	v_mfma_f32_16x16x32_bf16 v[120:123], v[76:79], v[202:205], v[120:123]
	v_mfma_f32_16x16x32_bf16 v[32:35], v[140:143], v[202:205], v[32:35]
	v_mfma_f32_16x16x32_bf16 v[152:155], v[76:79], v[148:151], v[168:171]
	v_mfma_f32_16x16x32_bf16 v[144:147], v[76:79], v[160:163], v[144:147]
	s_setprio 0
	s_barrier
	s_add_i32 s40, s73, s59
	v_lshl_add_u64 v[214:215], s[50:51], 0, v[186:187]
	s_mov_b32 m0, s40
	ds_read_b128 v[148:151], v223 offset:16384
	ds_read_b128 v[156:159], v223 offset:17408
	ds_read_b128 v[160:163], v223 offset:18432
	ds_read_b128 v[168:171], v223 offset:19456
	ds_read_b128 v[176:179], v223 offset:20480
	ds_read_b128 v[180:183], v223 offset:21504
	ds_read_b128 v[198:201], v223 offset:22528
	ds_read_b128 v[202:205], v223 offset:23552
	global_load_lds_dwordx4 v[214:215], off
	s_add_i32 m0, s40, 0x2000
	s_add_u32 s80, s50, 0x80000
	v_lshl_add_u64 v[224:225], s[50:51], 0, v[190:191]
	s_addc_u32 s81, s51, 0
	s_add_i32 s40, s74, s59
	global_load_lds_dwordx4 v[224:225], off
	v_lshl_add_u64 v[206:207], s[80:81], 0, v[186:187]
	s_mov_b32 m0, s40
	v_lshl_add_u64 v[226:227], s[52:53], 0, v[184:185]
	global_load_lds_dwordx4 v[206:207], off
	v_lshl_add_u64 v[206:207], s[80:81], 0, v[190:191]
	s_add_i32 m0, s40, 0x2000
	v_lshl_add_u64 v[228:229], s[52:53], 0, v[188:189]
	global_load_lds_dwordx4 v[206:207], off
	s_mov_b32 m0, s47
	s_nop 0
	global_load_lds_dwordx4 v[226:227], off
	s_mov_b32 m0, s60
	s_nop 0
	global_load_lds_dwordx4 v[228:229], off
	s_waitcnt vmcnt(8)
	s_waitcnt lgkmcnt(0)
	s_barrier
; #define PG8_STAGE(bufoff, gbase, voff) do { _Pragma("unroll") for (int _i = 0; _i < 2; ++_i) \
;         __builtin_amdgcn_global_load_lds((const unsigned*)((const char*)(gbase) + (voff)[_i]), (LAS unsigned*)(lds + (bufoff) + ldsw + _i * 8192), 16, 0, 0); } while (0)
; #define PG8_LDA(dst, b, h) do { _Pragma("unroll") for (int m = 0; m < 4; ++m) _Pragma("unroll") for (int k = 0; k < 2; ++k) dst[m][k] = *(const LAS bf16x8*)(lds + PG8_SA(b, h) + aoff + m * 2048 + k * 1024); } while (0)
; #define PG8_LDB(dst, b, h) do { _Pragma("unroll") for (int n = 0; n < 2; ++n) _Pragma("unroll") for (int k = 0; k < 2; ++k) dst[n][k] = *(const LAS bf16x8*)(lds + PG8_SB(b, h) + boff + n * 2048 + k * 1024); } while (0)
; #define PG8_MMA(ai, bj, At, Bt) do { __builtin_amdgcn_s_setprio(1); _Pragma("unroll") for (int k = 0; k < 2; ++k) _Pragma("unroll") for (int m = 0; m < 4; ++m) _Pragma("unroll") for (int n = 0; n < 2; ++n) \
;         acc[ai][bj][m][n] = __builtin_amdgcn_mfma_f32_16x16x32_bf16(Bt[n][k], At[m][k], acc[ai][bj][m][n], 0, 0, 0); __builtin_amdgcn_s_setprio(0); } while (0)
; #define PG8_WAIT_V(n) asm volatile("s_waitcnt vmcnt(" #n ")" ::: "memory")
; #define PG8_WAIT_L(n) asm volatile("s_waitcnt lgkmcnt(" #n ")" ::: "memory")
; #define PG8_BAR __builtin_amdgcn_s_barrier()
; #define PG8_SCHED __builtin_amdgcn_sched_barrier(0)
; template <class Epi, bool ALIGN_EPI = PG8_ALIGN, bool SP2 = PG8_SP2>
; __device__ __forceinline__ void gemm_phase(LAS unsigned char* lds, const int tid, const int K, const Order& S, const Epi& E) {
;     ...
;             PG8_WAIT_V(8); PG8_WAIT_L(0); PG8_BAR; PG8_MMA(1, 0, At, B0); PG8_MMA(1, 1, At, B1); PG8_BAR; PG8_SCHED;
;             PG8_LDB(B0, 1, 0); PG8_LDB(B1, 1, 1); PG8_SCHED; PG8_LDA(At, 1, 0); PG8_STAGE(PG8_SA(0, 1), a2 + hstep, voffA);
;             PG8_WAIT_V(8); PG8_WAIT_L(0); PG8_BAR; PG8_MMA(0, 0, At, B0); PG8_MMA(0, 1, At, B1); PG8_BAR; PG8_SCHED;
	s_setprio 1
	s_waitcnt lgkmcnt(0)
	v_mfma_f32_16x16x32_bf16 v[28:31], v[56:59], v[148:151], v[28:31]
	v_mfma_f32_16x16x32_bf16 v[108:111], v[48:51], v[160:163], v[108:111]
	v_mfma_f32_16x16x32_bf16 v[20:23], v[56:59], v[160:163], v[20:23]
	v_mfma_f32_16x16x32_bf16 v[100:103], v[48:51], v[176:179], v[100:103]
	v_mfma_f32_16x16x32_bf16 v[12:15], v[56:59], v[176:179], v[12:15]
	v_mfma_f32_16x16x32_bf16 v[4:7], v[56:59], v[198:201], v[4:7]
	v_mfma_f32_16x16x32_bf16 v[116:119], v[48:51], v[148:151], v[116:119]
	v_mfma_f32_16x16x32_bf16 v[48:51], v[48:51], v[198:201], v[92:95]
	v_mfma_f32_16x16x32_bf16 v[28:31], v[60:63], v[156:159], v[28:31]
	v_mfma_f32_16x16x32_bf16 v[92:95], v[52:55], v[168:171], v[108:111]
	v_mfma_f32_16x16x32_bf16 v[20:23], v[60:63], v[168:171], v[20:23]
	v_mfma_f32_16x16x32_bf16 v[100:103], v[52:55], v[180:183], v[100:103]
	v_mfma_f32_16x16x32_bf16 v[12:15], v[60:63], v[180:183], v[12:15]
	v_mfma_f32_16x16x32_bf16 v[4:7], v[60:63], v[202:205], v[4:7]
	v_mfma_f32_16x16x32_bf16 v[56:59], v[52:55], v[156:159], v[116:119]
	v_mfma_f32_16x16x32_bf16 v[48:51], v[52:55], v[202:205], v[48:51]
	v_mfma_f32_16x16x32_bf16 v[24:27], v[136:139], v[148:151], v[24:27]
	v_mfma_f32_16x16x32_bf16 v[16:19], v[136:139], v[160:163], v[16:19]
	v_mfma_f32_16x16x32_bf16 v[96:99], v[72:75], v[176:179], v[96:99]
	v_mfma_f32_16x16x32_bf16 v[8:11], v[136:139], v[176:179], v[8:11]
	v_mfma_f32_16x16x32_bf16 v[0:3], v[136:139], v[198:201], v[0:3]
	v_mfma_f32_16x16x32_bf16 v[52:55], v[72:75], v[148:151], v[112:115]
	v_mfma_f32_16x16x32_bf16 v[60:63], v[72:75], v[160:163], v[104:107]
	v_mfma_f32_16x16x32_bf16 v[72:75], v[72:75], v[198:201], v[88:91]
	v_mfma_f32_16x16x32_bf16 v[24:27], v[140:143], v[156:159], v[24:27]
	v_mfma_f32_16x16x32_bf16 v[16:19], v[140:143], v[168:171], v[16:19]
	v_mfma_f32_16x16x32_bf16 v[88:91], v[76:79], v[180:183], v[96:99]
	v_mfma_f32_16x16x32_bf16 v[8:11], v[140:143], v[180:183], v[8:11]
	v_mfma_f32_16x16x32_bf16 v[0:3], v[140:143], v[202:205], v[0:3]
	v_mfma_f32_16x16x32_bf16 v[52:55], v[76:79], v[156:159], v[52:55]
	v_mfma_f32_16x16x32_bf16 v[60:63], v[76:79], v[168:171], v[60:63]
	v_mfma_f32_16x16x32_bf16 v[72:75], v[76:79], v[202:205], v[72:75]
	s_setprio 0
	s_barrier
	s_add_i32 s40, 0, 0x18000
	v_add_u32_e32 v108, s40, v219
	s_add_i32 s41, 0, 0x1c000
	ds_read_b128 v[76:79], v108
	ds_read_b128 v[96:99], v108 offset:1024
	ds_read_b128 v[104:107], v108 offset:2048
	ds_read_b128 v[112:115], v108 offset:3072
	v_add_u32_e32 v108, s41, v219
	ds_read_b128 v[136:139], v108
	ds_read_b128 v[140:143], v108 offset:1024
	ds_read_b128 v[148:151], v108 offset:2048
	ds_read_b128 v[160:163], v108 offset:3072
	s_add_u32 s52, s52, 0x80000
	s_addc_u32 s53, s53, 0
	s_mov_b32 m0, s61
	v_lshl_add_u64 v[206:207], s[52:53], 0, v[184:185]
	ds_read_b128 v[108:111], v223 offset:32768
	ds_read_b128 v[116:119], v223 offset:33792
	ds_read_b128 v[156:159], v223 offset:34816
	ds_read_b128 v[176:179], v223 offset:35840
	ds_read_b128 v[168:171], v223 offset:36864
	ds_read_b128 v[180:183], v223 offset:37888
	ds_read_b128 v[198:201], v223 offset:38912
	ds_read_b128 v[202:205], v223 offset:39936
	global_load_lds_dwordx4 v[206:207], off
	v_lshl_add_u64 v[206:207], s[52:53], 0, v[188:189]
	s_mov_b32 m0, s62
	s_nop 0
	global_load_lds_dwordx4 v[206:207], off
	s_waitcnt vmcnt(8)
	s_waitcnt lgkmcnt(0)
	s_barrier
	s_setprio 1
	s_waitcnt lgkmcnt(0)
	v_mfma_f32_16x16x32_bf16 v[172:175], v[76:79], v[108:111], v[172:175]
	v_mfma_f32_16x16x32_bf16 v[84:87], v[104:107], v[108:111], v[84:87]
	v_mfma_f32_16x16x32_bf16 v[164:167], v[76:79], v[156:159], v[164:167]
	v_mfma_f32_16x16x32_bf16 v[68:71], v[104:107], v[156:159], v[68:71]
	v_mfma_f32_16x16x32_bf16 v[132:135], v[76:79], v[168:171], v[132:135]
	v_mfma_f32_16x16x32_bf16 v[44:47], v[104:107], v[168:171], v[44:47]
	v_mfma_f32_16x16x32_bf16 v[124:127], v[76:79], v[198:201], v[124:127]
	v_mfma_f32_16x16x32_bf16 v[36:39], v[104:107], v[198:201], v[36:39]
	v_mfma_f32_16x16x32_bf16 v[172:175], v[96:99], v[116:119], v[172:175]
	v_mfma_f32_16x16x32_bf16 v[84:87], v[112:115], v[116:119], v[84:87]
	v_mfma_f32_16x16x32_bf16 v[164:167], v[96:99], v[176:179], v[164:167]
	v_mfma_f32_16x16x32_bf16 v[68:71], v[112:115], v[176:179], v[68:71]
	v_mfma_f32_16x16x32_bf16 v[132:135], v[96:99], v[180:183], v[132:135]
	v_mfma_f32_16x16x32_bf16 v[44:47], v[112:115], v[180:183], v[44:47]
	v_mfma_f32_16x16x32_bf16 v[124:127], v[96:99], v[202:205], v[124:127]
	v_mfma_f32_16x16x32_bf16 v[36:39], v[112:115], v[202:205], v[36:39]
	v_mfma_f32_16x16x32_bf16 v[152:155], v[136:139], v[108:111], v[152:155]
	v_mfma_f32_16x16x32_bf16 v[80:83], v[148:151], v[108:111], v[80:83]
	v_mfma_f32_16x16x32_bf16 v[108:111], v[136:139], v[156:159], v[144:147]
	v_mfma_f32_16x16x32_bf16 v[64:67], v[148:151], v[156:159], v[64:67]
	v_mfma_f32_16x16x32_bf16 v[128:131], v[136:139], v[168:171], v[128:131]
	v_mfma_f32_16x16x32_bf16 v[40:43], v[148:151], v[168:171], v[40:43]
	v_mfma_f32_16x16x32_bf16 v[120:123], v[136:139], v[198:201], v[120:123]
	v_mfma_f32_16x16x32_bf16 v[32:35], v[148:151], v[198:201], v[32:35]
	v_mfma_f32_16x16x32_bf16 v[168:171], v[140:143], v[116:119], v[152:155]
	v_mfma_f32_16x16x32_bf16 v[80:83], v[160:163], v[116:119], v[80:83]
	v_mfma_f32_16x16x32_bf16 v[156:159], v[140:143], v[176:179], v[108:111]
	v_mfma_f32_16x16x32_bf16 v[64:67], v[160:163], v[176:179], v[64:67]
	v_mfma_f32_16x16x32_bf16 v[128:131], v[140:143], v[180:183], v[128:131]
	v_mfma_f32_16x16x32_bf16 v[40:43], v[160:163], v[180:183], v[40:43]
	v_mfma_f32_16x16x32_bf16 v[120:123], v[140:143], v[202:205], v[120:123]
	v_mfma_f32_16x16x32_bf16 v[32:35], v[160:163], v[202:205], v[32:35]
	s_setprio 0
	s_barrier
; #define PG8_STAGE(bufoff, gbase, voff) do { _Pragma("unroll") for (int _i = 0; _i < 2; ++_i) \
;         __builtin_amdgcn_global_load_lds((const unsigned*)((const char*)(gbase) + (voff)[_i]), (LAS unsigned*)(lds + (bufoff) + ldsw + _i * 8192), 16, 0, 0); } while (0)
; #define PG8_LDA(dst, b, h) do { _Pragma("unroll") for (int m = 0; m < 4; ++m) _Pragma("unroll") for (int k = 0; k < 2; ++k) dst[m][k] = *(const LAS bf16x8*)(lds + PG8_SA(b, h) + aoff + m * 2048 + k * 1024); } while (0)
; #define PG8_MMA(ai, bj, At, Bt) do { __builtin_amdgcn_s_setprio(1); _Pragma("unroll") for (int k = 0; k < 2; ++k) _Pragma("unroll") for (int m = 0; m < 4; ++m) _Pragma("unroll") for (int n = 0; n < 2; ++n) \
;         acc[ai][bj][m][n] = __builtin_amdgcn_mfma_f32_16x16x32_bf16(Bt[n][k], At[m][k], acc[ai][bj][m][n], 0, 0, 0); __builtin_amdgcn_s_setprio(0); } while (0)
; #define PG8_WAIT_V(n) asm volatile("s_waitcnt vmcnt(" #n ")" ::: "memory")
; #define PG8_WAIT_L(n) asm volatile("s_waitcnt lgkmcnt(" #n ")" ::: "memory")
; #define PG8_BAR __builtin_amdgcn_s_barrier()
; #define PG8_SCHED __builtin_amdgcn_sched_barrier(0)
; template <class Epi, bool ALIGN_EPI = PG8_ALIGN, bool SP2 = PG8_SP2>
; __device__ __forceinline__ void gemm_phase(LAS unsigned char* lds, const int tid, const int K, const Order& S, const Epi& E) {
;     ...
;             PG8_LDA(At, 1, 1); PG8_STAGE(PG8_SB(1, 0), b3, voffB); PG8_STAGE(PG8_SB(1, 1), b3 + hstep, voffB); PG8_STAGE(PG8_SA(1, 0), a3, voffA);
;             PG8_WAIT_V(8); PG8_WAIT_L(0); PG8_BAR; PG8_MMA(1, 0, At, B0); PG8_MMA(1, 1, At, B1); PG8_BAR; PG8_SCHED;
;     ...
;         }
;         if constexpr (ALIGN_EPI) { if (wr == 0) PG8_BAR; }
	s_add_i32 s40, s40, s59
	v_lshl_add_u64 v[108:109], v[214:215], 0, s[14:15]
	s_mov_b32 m0, s40
	ds_read_b128 v[144:147], v223 offset:49152
	ds_read_b128 v[152:155], v223 offset:50176
	ds_read_b128 v[176:179], v223 offset:51200
	ds_read_b128 v[180:183], v223 offset:52224
	ds_read_b128 v[198:201], v223 offset:53248
	ds_read_b128 v[202:205], v223 offset:54272
	ds_read_b128 v[206:209], v223 offset:55296
	ds_read_b128 v[210:213], v223 offset:56320
	global_load_lds_dwordx4 v[108:109], off
	s_add_i32 m0, s40, 0x2000
	s_add_u32 s50, s50, 0x80080
	v_lshl_add_u64 v[108:109], v[224:225], 0, s[14:15]
	s_addc_u32 s51, s51, 0
	s_add_i32 s40, s41, s59
	global_load_lds_dwordx4 v[108:109], off
	v_lshl_add_u64 v[108:109], s[50:51], 0, v[186:187]
	s_mov_b32 m0, s40
	s_nop 0
	global_load_lds_dwordx4 v[108:109], off
	v_lshl_add_u64 v[108:109], s[50:51], 0, v[190:191]
	s_add_i32 m0, s40, 0x2000
	s_nop 0
	global_load_lds_dwordx4 v[108:109], off
	v_lshl_add_u64 v[108:109], v[226:227], 0, s[14:15]
	s_mov_b32 m0, s67
	s_nop 0
	global_load_lds_dwordx4 v[108:109], off
	v_lshl_add_u64 v[108:109], v[228:229], 0, s[14:15]
	s_mov_b32 m0, s68
	s_nop 0
	global_load_lds_dwordx4 v[108:109], off
	s_waitcnt vmcnt(8)
	s_waitcnt lgkmcnt(0)
	s_barrier
	s_setprio 1
	s_waitcnt lgkmcnt(0)
	v_mfma_f32_16x16x32_bf16 v[56:59], v[76:79], v[144:147], v[56:59]
	v_mfma_f32_16x16x32_bf16 v[28:31], v[104:107], v[144:147], v[28:31]
	v_mfma_f32_16x16x32_bf16 v[92:95], v[76:79], v[176:179], v[92:95]
	v_mfma_f32_16x16x32_bf16 v[20:23], v[104:107], v[176:179], v[20:23]
	v_mfma_f32_16x16x32_bf16 v[100:103], v[76:79], v[198:201], v[100:103]
	v_mfma_f32_16x16x32_bf16 v[12:15], v[104:107], v[198:201], v[12:15]
	v_mfma_f32_16x16x32_bf16 v[48:51], v[76:79], v[206:209], v[48:51]
	v_mfma_f32_16x16x32_bf16 v[4:7], v[104:107], v[206:209], v[4:7]
	v_mfma_f32_16x16x32_bf16 v[116:119], v[96:99], v[152:155], v[56:59]
	v_mfma_f32_16x16x32_bf16 v[28:31], v[112:115], v[152:155], v[28:31]
	v_mfma_f32_16x16x32_bf16 v[108:111], v[96:99], v[180:183], v[92:95]
	v_mfma_f32_16x16x32_bf16 v[20:23], v[112:115], v[180:183], v[20:23]
	v_mfma_f32_16x16x32_bf16 v[100:103], v[96:99], v[202:205], v[100:103]
	v_mfma_f32_16x16x32_bf16 v[12:15], v[112:115], v[202:205], v[12:15]
	v_mfma_f32_16x16x32_bf16 v[92:95], v[96:99], v[210:213], v[48:51]
	v_mfma_f32_16x16x32_bf16 v[4:7], v[112:115], v[210:213], v[4:7]
	v_mfma_f32_16x16x32_bf16 v[48:51], v[136:139], v[144:147], v[52:55]
	v_mfma_f32_16x16x32_bf16 v[24:27], v[148:151], v[144:147], v[24:27]
	v_mfma_f32_16x16x32_bf16 v[52:55], v[136:139], v[176:179], v[60:63]
	v_mfma_f32_16x16x32_bf16 v[16:19], v[148:151], v[176:179], v[16:19]
	v_mfma_f32_16x16x32_bf16 v[56:59], v[136:139], v[198:201], v[88:91]
	v_mfma_f32_16x16x32_bf16 v[8:11], v[148:151], v[198:201], v[8:11]
	v_mfma_f32_16x16x32_bf16 v[60:63], v[136:139], v[206:209], v[72:75]
	v_mfma_f32_16x16x32_bf16 v[0:3], v[148:151], v[206:209], v[0:3]
	v_mfma_f32_16x16x32_bf16 v[112:115], v[140:143], v[152:155], v[48:51]
	v_mfma_f32_16x16x32_bf16 v[24:27], v[160:163], v[152:155], v[24:27]
	v_mfma_f32_16x16x32_bf16 v[104:107], v[140:143], v[180:183], v[52:55]
	v_mfma_f32_16x16x32_bf16 v[16:19], v[160:163], v[180:183], v[16:19]
	v_mfma_f32_16x16x32_bf16 v[96:99], v[140:143], v[202:205], v[56:59]
	v_mfma_f32_16x16x32_bf16 v[8:11], v[160:163], v[202:205], v[8:11]
	v_mfma_f32_16x16x32_bf16 v[88:91], v[140:143], v[210:213], v[60:63]
	v_mfma_f32_16x16x32_bf16 v[0:3], v[160:163], v[210:213], v[0:3]
	s_setprio 0
	s_barrier
	s_add_i32 s79, s79, 2
	s_add_u32 s77, s77, 0x100
	s_addc_u32 s78, s78, 0
	s_add_u32 s48, s48, 0x100
	s_addc_u32 s49, s49, 0
	s_cmp_gt_u32 s79, 29
	s_cbranch_scc0 .LBB0_1808
	s_and_b64 vcc, exec, s[16:17]
	s_cbranch_vccz .LBB0_1811
	s_barrier

;     __device__ __forceinline__ int nt(const Unit& u) const { return (u.ks < 0 || xsplit == 1) ? ntf : sbase + (u.ks >= sthr ? 2 : 0); }
; #define PG8_STAGE(bufoff, gbase, voff) do { _Pragma("unroll") for (int _i = 0; _i < 2; ++_i) \
;         __builtin_amdgcn_global_load_lds((const unsigned*)((const char*)(gbase) + (voff)[_i]), (LAS unsigned*)(lds + (bufoff) + ldsw + _i * 8192), 16, 0, 0); } while (0)
; #define PG8_LDA(dst, b, h) do { _Pragma("unroll") for (int m = 0; m < 4; ++m) _Pragma("unroll") for (int k = 0; k < 2; ++k) dst[m][k] = *(const LAS bf16x8*)(lds + PG8_SA(b, h) + aoff + m * 2048 + k * 1024); } while (0)
; #define PG8_LDB(dst, b, h) do { _Pragma("unroll") for (int n = 0; n < 2; ++n) _Pragma("unroll") for (int k = 0; k < 2; ++k) dst[n][k] = *(const LAS bf16x8*)(lds + PG8_SB(b, h) + boff + n * 2048 + k * 1024); } while (0)
; #define PG8_MMA(ai, bj, At, Bt) do { __builtin_amdgcn_s_setprio(1); _Pragma("unroll") for (int k = 0; k < 2; ++k) _Pragma("unroll") for (int m = 0; m < 4; ++m) _Pragma("unroll") for (int n = 0; n < 2; ++n) \
;         acc[ai][bj][m][n] = __builtin_amdgcn_mfma_f32_16x16x32_bf16(Bt[n][k], At[m][k], acc[ai][bj][m][n], 0, 0, 0); __builtin_amdgcn_s_setprio(0); } while (0)
; template <class Epi, bool ALIGN_EPI = PG8_ALIGN, bool SP2 = PG8_SP2>
; __device__ __forceinline__ void gemm_phase(LAS unsigned char* lds, const int tid, const int K, const Order& S, const Epi& E) {
;     ...
;         for (int t = 0; t < nt; t += 2) {
;             const bool last = (t == nt - 2);
;             const char* a1 = cA + (size_t)(t + 1) * kstep;
;             const char* a2 = last ? nA : cA + (size_t)(t + 2) * kstep; const char* b2 = last ? nB : cB + (size_t)(t + 2) * kstep;
;             const char* a3 = a2 + kstep; const char* b3 = b2 + kstep;
;             if (last && has_next) S.a_ready(nxt, tid);
;             if constexpr (SP2) {
;             PG8_LDB(B0, 0, 0); PG8_LDB(B1, 0, 1); PG8_SCHED; PG8_LDA(At, 0, 0); PG8_STAGE(PG8_SA(1, 1), a1 + hstep, voffA);
;             PG8_WAIT_V(8); PG8_WAIT_L(0); PG8_BAR; PG8_MMA(0, 0, At, B0); PG8_MMA(0, 1, At, B1); PG8_BAR; PG8_SCHED;
;             PG8_LDA(At, 0, 1); PG8_STAGE(PG8_SB(0, 0), b2, voffB); PG8_STAGE(PG8_SB(0, 1), b2 + hstep, voffB); PG8_STAGE(PG8_SA(0, 0), a2, voffA);
;             PG8_WAIT_V(8); PG8_WAIT_L(0); PG8_BAR; PG8_MMA(1, 0, At, B0); PG8_MMA(1, 1, At, B1); PG8_BAR; PG8_SCHED;
.LBB0_1952:
	ds_read_b128 v[120:123], v167
	ds_read_b128 v[124:127], v167 offset:1024
	ds_read_b128 v[128:131], v167 offset:2048
	ds_read_b128 v[132:135], v167 offset:3072
	ds_read_b128 v[158:161], v168
	ds_read_b128 v[170:173], v168 offset:1024
	ds_read_b128 v[174:177], v168 offset:2048
	ds_read_b128 v[178:181], v168 offset:3072
	s_add_u32 s34, s30, 0x100
	s_addc_u32 s35, s31, 0
	s_cmpk_eq_i32 s73, 0x52
	s_cselect_b32 s43, s27, s35
	s_cselect_b32 s42, s26, s34
	s_cselect_b32 s37, s29, s72
	s_cselect_b32 s36, s28, s71
	v_lshl_add_u64 v[162:163], s[30:31], 0, v[154:155]
	s_add_i32 m0, s51, 0xc000
	ds_read_b128 v[182:185], v169
	ds_read_b128 v[186:189], v169 offset:1024
	ds_read_b128 v[190:193], v169 offset:2048
	ds_read_b128 v[194:197], v169 offset:3072
	ds_read_b128 v[198:201], v169 offset:4096
	ds_read_b128 v[202:205], v169 offset:5120
	ds_read_b128 v[206:209], v169 offset:6144
	ds_read_b128 v[210:213], v169 offset:7168
	global_load_lds_dwordx4 v[162:163], off
	v_lshl_add_u64 v[162:163], s[30:31], 0, v[152:153]
	s_add_i32 m0, s51, 0xe000
	s_nop 0
	global_load_lds_dwordx4 v[162:163], off
	s_waitcnt vmcnt(8)
	s_waitcnt lgkmcnt(0)
	s_barrier
	s_setprio 1
	s_waitcnt lgkmcnt(0)
	v_mfma_f32_16x16x32_bf16 v[140:143], v[120:123], v[182:185], v[140:143]
	v_mfma_f32_16x16x32_bf16 v[136:139], v[128:131], v[182:185], v[136:139]
	v_mfma_f32_16x16x32_bf16 v[116:119], v[120:123], v[190:193], v[116:119]
	v_mfma_f32_16x16x32_bf16 v[104:107], v[128:131], v[190:193], v[104:107]
	v_mfma_f32_16x16x32_bf16 v[100:103], v[120:123], v[198:201], v[100:103]
	v_mfma_f32_16x16x32_bf16 v[88:91], v[128:131], v[198:201], v[88:91]
	v_mfma_f32_16x16x32_bf16 v[84:87], v[120:123], v[206:209], v[84:87]
	v_mfma_f32_16x16x32_bf16 v[72:75], v[128:131], v[206:209], v[72:75]
	v_mfma_f32_16x16x32_bf16 v[140:143], v[124:127], v[186:189], v[140:143]
	v_mfma_f32_16x16x32_bf16 v[136:139], v[132:135], v[186:189], v[136:139]
	v_mfma_f32_16x16x32_bf16 v[116:119], v[124:127], v[194:197], v[116:119]
	v_mfma_f32_16x16x32_bf16 v[104:107], v[132:135], v[194:197], v[104:107]
	v_mfma_f32_16x16x32_bf16 v[100:103], v[124:127], v[202:205], v[100:103]
	v_mfma_f32_16x16x32_bf16 v[88:91], v[132:135], v[202:205], v[88:91]
	v_mfma_f32_16x16x32_bf16 v[84:87], v[124:127], v[210:213], v[84:87]
	v_mfma_f32_16x16x32_bf16 v[72:75], v[132:135], v[210:213], v[72:75]
	v_mfma_f32_16x16x32_bf16 v[112:115], v[158:161], v[182:185], v[112:115]
	v_mfma_f32_16x16x32_bf16 v[108:111], v[174:177], v[182:185], v[108:111]
	v_mfma_f32_16x16x32_bf16 v[96:99], v[158:161], v[190:193], v[96:99]
	v_mfma_f32_16x16x32_bf16 v[92:95], v[174:177], v[190:193], v[92:95]
	v_mfma_f32_16x16x32_bf16 v[80:83], v[158:161], v[198:201], v[80:83]
	v_mfma_f32_16x16x32_bf16 v[76:79], v[174:177], v[198:201], v[76:79]
	v_mfma_f32_16x16x32_bf16 v[68:71], v[158:161], v[206:209], v[68:71]
	v_mfma_f32_16x16x32_bf16 v[64:67], v[174:177], v[206:209], v[64:67]
	v_mfma_f32_16x16x32_bf16 v[112:115], v[170:173], v[186:189], v[112:115]
	v_mfma_f32_16x16x32_bf16 v[108:111], v[178:181], v[186:189], v[108:111]
	v_mfma_f32_16x16x32_bf16 v[96:99], v[170:173], v[194:197], v[96:99]
	v_mfma_f32_16x16x32_bf16 v[92:95], v[178:181], v[194:197], v[92:95]
	v_mfma_f32_16x16x32_bf16 v[80:83], v[170:173], v[202:205], v[80:83]
	v_mfma_f32_16x16x32_bf16 v[76:79], v[178:181], v[202:205], v[76:79]
	v_mfma_f32_16x16x32_bf16 v[68:71], v[170:173], v[210:213], v[68:71]
	v_mfma_f32_16x16x32_bf16 v[64:67], v[178:181], v[210:213], v[64:67]
	s_setprio 0
	s_barrier
	s_add_i32 s30, s60, s50
	v_lshl_add_u64 v[162:163], s[36:37], 0, v[146:147]
	s_mov_b32 m0, s30
	ds_read_b128 v[182:185], v169 offset:16384
	ds_read_b128 v[186:189], v169 offset:17408
	ds_read_b128 v[190:193], v169 offset:18432
	ds_read_b128 v[194:197], v169 offset:19456
	ds_read_b128 v[198:201], v169 offset:20480
	ds_read_b128 v[202:205], v169 offset:21504
	ds_read_b128 v[206:209], v169 offset:22528
	ds_read_b128 v[210:213], v169 offset:23552
	global_load_lds_dwordx4 v[162:163], off
	s_add_i32 m0, s30, 0x2000
	s_add_u32 s30, s36, 0x158000
	v_lshl_add_u64 v[214:215], s[36:37], 0, v[150:151]
	s_addc_u32 s31, s37, 0
	s_add_i32 s40, s61, s50
	global_load_lds_dwordx4 v[214:215], off
	v_lshl_add_u64 v[218:219], s[30:31], 0, v[146:147]
	s_mov_b32 m0, s40
	v_lshl_add_u64 v[220:221], s[42:43], 0, v[148:149]
	global_load_lds_dwordx4 v[218:219], off
	v_lshl_add_u64 v[218:219], s[30:31], 0, v[150:151]
	s_add_i32 m0, s40, 0x2000
	s_nop 0
	global_load_lds_dwordx4 v[218:219], off
	v_lshl_add_u64 v[218:219], s[42:43], 0, v[144:145]
	s_mov_b32 m0, s51
	s_nop 0
	global_load_lds_dwordx4 v[218:219], off
	s_mov_b32 m0, s52
	s_nop 0
	global_load_lds_dwordx4 v[220:221], off
	s_waitcnt vmcnt(8)
	s_waitcnt lgkmcnt(0)
	s_barrier
; #define PG8_STAGE(bufoff, gbase, voff) do { _Pragma("unroll") for (int _i = 0; _i < 2; ++_i) \
;         __builtin_amdgcn_global_load_lds((const unsigned*)((const char*)(gbase) + (voff)[_i]), (LAS unsigned*)(lds + (bufoff) + ldsw + _i * 8192), 16, 0, 0); } while (0)
; #define PG8_LDA(dst, b, h) do { _Pragma("unroll") for (int m = 0; m < 4; ++m) _Pragma("unroll") for (int k = 0; k < 2; ++k) dst[m][k] = *(const LAS bf16x8*)(lds + PG8_SA(b, h) + aoff + m * 2048 + k * 1024); } while (0)
; #define PG8_LDB(dst, b, h) do { _Pragma("unroll") for (int n = 0; n < 2; ++n) _Pragma("unroll") for (int k = 0; k < 2; ++k) dst[n][k] = *(const LAS bf16x8*)(lds + PG8_SB(b, h) + boff + n * 2048 + k * 1024); } while (0)
; #define PG8_MMA(ai, bj, At, Bt) do { __builtin_amdgcn_s_setprio(1); _Pragma("unroll") for (int k = 0; k < 2; ++k) _Pragma("unroll") for (int m = 0; m < 4; ++m) _Pragma("unroll") for (int n = 0; n < 2; ++n) \
;         acc[ai][bj][m][n] = __builtin_amdgcn_mfma_f32_16x16x32_bf16(Bt[n][k], At[m][k], acc[ai][bj][m][n], 0, 0, 0); __builtin_amdgcn_s_setprio(0); } while (0)
; #define PG8_WAIT_V(n) asm volatile("s_waitcnt vmcnt(" #n ")" ::: "memory")
; #define PG8_WAIT_L(n) asm volatile("s_waitcnt lgkmcnt(" #n ")" ::: "memory")
; #define PG8_BAR __builtin_amdgcn_s_barrier()
; #define PG8_SCHED __builtin_amdgcn_sched_barrier(0)
; template <class Epi, bool ALIGN_EPI = PG8_ALIGN, bool SP2 = PG8_SP2>
; __device__ __forceinline__ void gemm_phase(LAS unsigned char* lds, const int tid, const int K, const Order& S, const Epi& E) {
;     ...
;             PG8_WAIT_V(8); PG8_WAIT_L(0); PG8_BAR; PG8_MMA(1, 0, At, B0); PG8_MMA(1, 1, At, B1); PG8_BAR; PG8_SCHED;
;             PG8_LDB(B0, 1, 0); PG8_LDB(B1, 1, 1); PG8_SCHED; PG8_LDA(At, 1, 0); PG8_STAGE(PG8_SA(0, 1), a2 + hstep, voffA);
;             PG8_WAIT_V(8); PG8_WAIT_L(0); PG8_BAR; PG8_MMA(0, 0, At, B0); PG8_MMA(0, 1, At, B1); PG8_BAR; PG8_SCHED;
	s_setprio 1
	s_waitcnt lgkmcnt(0)
	v_mfma_f32_16x16x32_bf16 v[60:63], v[120:123], v[182:185], v[60:63]
	v_mfma_f32_16x16x32_bf16 v[56:59], v[128:131], v[182:185], v[56:59]
	v_mfma_f32_16x16x32_bf16 v[48:51], v[120:123], v[190:193], v[48:51]
	v_mfma_f32_16x16x32_bf16 v[40:43], v[128:131], v[190:193], v[40:43]
	v_mfma_f32_16x16x32_bf16 v[32:35], v[120:123], v[198:201], v[32:35]
	v_mfma_f32_16x16x32_bf16 v[24:27], v[128:131], v[198:201], v[24:27]
	v_mfma_f32_16x16x32_bf16 v[16:19], v[120:123], v[206:209], v[16:19]
	v_mfma_f32_16x16x32_bf16 v[8:11], v[128:131], v[206:209], v[8:11]
	v_mfma_f32_16x16x32_bf16 v[60:63], v[124:127], v[186:189], v[60:63]
	v_mfma_f32_16x16x32_bf16 v[56:59], v[132:135], v[186:189], v[56:59]
	v_mfma_f32_16x16x32_bf16 v[48:51], v[124:127], v[194:197], v[48:51]
	v_mfma_f32_16x16x32_bf16 v[40:43], v[132:135], v[194:197], v[40:43]
	v_mfma_f32_16x16x32_bf16 v[32:35], v[124:127], v[202:205], v[32:35]
	v_mfma_f32_16x16x32_bf16 v[24:27], v[132:135], v[202:205], v[24:27]
	v_mfma_f32_16x16x32_bf16 v[16:19], v[124:127], v[210:213], v[16:19]
	v_mfma_f32_16x16x32_bf16 v[8:11], v[132:135], v[210:213], v[8:11]
	v_mfma_f32_16x16x32_bf16 v[52:55], v[158:161], v[182:185], v[52:55]
	v_mfma_f32_16x16x32_bf16 v[44:47], v[174:177], v[182:185], v[44:47]
	v_mfma_f32_16x16x32_bf16 v[36:39], v[158:161], v[190:193], v[36:39]
	v_mfma_f32_16x16x32_bf16 v[28:31], v[174:177], v[190:193], v[28:31]
	v_mfma_f32_16x16x32_bf16 v[20:23], v[158:161], v[198:201], v[20:23]
	v_mfma_f32_16x16x32_bf16 v[12:15], v[174:177], v[198:201], v[12:15]
	v_mfma_f32_16x16x32_bf16 v[4:7], v[158:161], v[206:209], v[4:7]
	v_mfma_f32_16x16x32_bf16 v[0:3], v[174:177], v[206:209], v[0:3]
	v_mfma_f32_16x16x32_bf16 v[52:55], v[170:173], v[186:189], v[52:55]
	v_mfma_f32_16x16x32_bf16 v[44:47], v[178:181], v[186:189], v[44:47]
	v_mfma_f32_16x16x32_bf16 v[36:39], v[170:173], v[194:197], v[36:39]
	v_mfma_f32_16x16x32_bf16 v[28:31], v[178:181], v[194:197], v[28:31]
	v_mfma_f32_16x16x32_bf16 v[20:23], v[170:173], v[202:205], v[20:23]
	v_mfma_f32_16x16x32_bf16 v[12:15], v[178:181], v[202:205], v[12:15]
	v_mfma_f32_16x16x32_bf16 v[4:7], v[170:173], v[210:213], v[4:7]
	v_mfma_f32_16x16x32_bf16 v[0:3], v[178:181], v[210:213], v[0:3]
	s_setprio 0
	s_barrier
	s_add_i32 s40, 0, 0x18000
	s_add_i32 s41, 0, 0x1c000
	v_add_u32_e32 v132, s40, v165
	v_add_u32_e32 v178, s41, v165
	ds_read_b128 v[120:123], v132
	ds_read_b128 v[124:127], v132 offset:1024
	ds_read_b128 v[128:131], v132 offset:2048
	ds_read_b128 v[132:135], v132 offset:3072
	ds_read_b128 v[158:161], v178
	ds_read_b128 v[170:173], v178 offset:1024
	ds_read_b128 v[174:177], v178 offset:2048
	ds_read_b128 v[178:181], v178 offset:3072
	s_add_u32 s30, s42, 0x158000
	s_addc_u32 s31, s43, 0
	s_mov_b32 m0, s53
	v_lshl_add_u64 v[222:223], s[30:31], 0, v[144:145]
	ds_read_b128 v[182:185], v169 offset:32768
	ds_read_b128 v[186:189], v169 offset:33792
	ds_read_b128 v[190:193], v169 offset:34816
	ds_read_b128 v[194:197], v169 offset:35840
	ds_read_b128 v[198:201], v169 offset:36864
	ds_read_b128 v[202:205], v169 offset:37888
	ds_read_b128 v[206:209], v169 offset:38912
	ds_read_b128 v[210:213], v169 offset:39936
	global_load_lds_dwordx4 v[222:223], off
	v_lshl_add_u64 v[222:223], s[30:31], 0, v[148:149]
	s_mov_b32 m0, s54
	s_nop 0
	global_load_lds_dwordx4 v[222:223], off
	s_waitcnt vmcnt(8)
	s_waitcnt lgkmcnt(0)
	s_barrier
	s_setprio 1
	s_waitcnt lgkmcnt(0)
	v_mfma_f32_16x16x32_bf16 v[140:143], v[120:123], v[182:185], v[140:143]
	v_mfma_f32_16x16x32_bf16 v[136:139], v[128:131], v[182:185], v[136:139]
	v_mfma_f32_16x16x32_bf16 v[116:119], v[120:123], v[190:193], v[116:119]
	v_mfma_f32_16x16x32_bf16 v[104:107], v[128:131], v[190:193], v[104:107]
	v_mfma_f32_16x16x32_bf16 v[100:103], v[120:123], v[198:201], v[100:103]
	v_mfma_f32_16x16x32_bf16 v[88:91], v[128:131], v[198:201], v[88:91]
	v_mfma_f32_16x16x32_bf16 v[84:87], v[120:123], v[206:209], v[84:87]
	v_mfma_f32_16x16x32_bf16 v[72:75], v[128:131], v[206:209], v[72:75]
	v_mfma_f32_16x16x32_bf16 v[140:143], v[124:127], v[186:189], v[140:143]
	v_mfma_f32_16x16x32_bf16 v[136:139], v[132:135], v[186:189], v[136:139]
	v_mfma_f32_16x16x32_bf16 v[116:119], v[124:127], v[194:197], v[116:119]
	v_mfma_f32_16x16x32_bf16 v[104:107], v[132:135], v[194:197], v[104:107]
	v_mfma_f32_16x16x32_bf16 v[100:103], v[124:127], v[202:205], v[100:103]
	v_mfma_f32_16x16x32_bf16 v[88:91], v[132:135], v[202:205], v[88:91]
	v_mfma_f32_16x16x32_bf16 v[84:87], v[124:127], v[210:213], v[84:87]
	v_mfma_f32_16x16x32_bf16 v[72:75], v[132:135], v[210:213], v[72:75]
	v_mfma_f32_16x16x32_bf16 v[112:115], v[158:161], v[182:185], v[112:115]
	v_mfma_f32_16x16x32_bf16 v[108:111], v[174:177], v[182:185], v[108:111]
	v_mfma_f32_16x16x32_bf16 v[96:99], v[158:161], v[190:193], v[96:99]
	v_mfma_f32_16x16x32_bf16 v[92:95], v[174:177], v[190:193], v[92:95]
	v_mfma_f32_16x16x32_bf16 v[80:83], v[158:161], v[198:201], v[80:83]
	v_mfma_f32_16x16x32_bf16 v[76:79], v[174:177], v[198:201], v[76:79]
	v_mfma_f32_16x16x32_bf16 v[68:71], v[158:161], v[206:209], v[68:71]
	v_mfma_f32_16x16x32_bf16 v[64:67], v[174:177], v[206:209], v[64:67]
	v_mfma_f32_16x16x32_bf16 v[112:115], v[170:173], v[186:189], v[112:115]
	v_mfma_f32_16x16x32_bf16 v[108:111], v[178:181], v[186:189], v[108:111]
	v_mfma_f32_16x16x32_bf16 v[96:99], v[170:173], v[194:197], v[96:99]
	v_mfma_f32_16x16x32_bf16 v[92:95], v[178:181], v[194:197], v[92:95]
	v_mfma_f32_16x16x32_bf16 v[80:83], v[170:173], v[202:205], v[80:83]
	v_mfma_f32_16x16x32_bf16 v[76:79], v[178:181], v[202:205], v[76:79]
	v_mfma_f32_16x16x32_bf16 v[68:71], v[170:173], v[210:213], v[68:71]
	v_mfma_f32_16x16x32_bf16 v[64:67], v[178:181], v[210:213], v[64:67]
	s_setprio 0
	s_barrier
;     __device__ __forceinline__ int nt(const Unit& u) const { return (u.ks < 0 || xsplit == 1) ? ntf : sbase + (u.ks >= sthr ? 2 : 0); }
; #define PG8_STAGE(bufoff, gbase, voff) do { _Pragma("unroll") for (int _i = 0; _i < 2; ++_i) \
;         __builtin_amdgcn_global_load_lds((const unsigned*)((const char*)(gbase) + (voff)[_i]), (LAS unsigned*)(lds + (bufoff) + ldsw + _i * 8192), 16, 0, 0); } while (0)
; #define PG8_LDA(dst, b, h) do { _Pragma("unroll") for (int m = 0; m < 4; ++m) _Pragma("unroll") for (int k = 0; k < 2; ++k) dst[m][k] = *(const LAS bf16x8*)(lds + PG8_SA(b, h) + aoff + m * 2048 + k * 1024); } while (0)
; #define PG8_MMA(ai, bj, At, Bt) do { __builtin_amdgcn_s_setprio(1); _Pragma("unroll") for (int k = 0; k < 2; ++k) _Pragma("unroll") for (int m = 0; m < 4; ++m) _Pragma("unroll") for (int n = 0; n < 2; ++n) \
;         acc[ai][bj][m][n] = __builtin_amdgcn_mfma_f32_16x16x32_bf16(Bt[n][k], At[m][k], acc[ai][bj][m][n], 0, 0, 0); __builtin_amdgcn_s_setprio(0); } while (0)
; #define PG8_WAIT_V(n) asm volatile("s_waitcnt vmcnt(" #n ")" ::: "memory")
; #define PG8_WAIT_L(n) asm volatile("s_waitcnt lgkmcnt(" #n ")" ::: "memory")
; #define PG8_BAR __builtin_amdgcn_s_barrier()
; #define PG8_SCHED __builtin_amdgcn_sched_barrier(0)
; template <class Epi, bool ALIGN_EPI = PG8_ALIGN, bool SP2 = PG8_SP2>
; __device__ __forceinline__ void gemm_phase(LAS unsigned char* lds, const int tid, const int K, const Order& S, const Epi& E) {
;     ...
;         for (int t = 0; t < nt; t += 2) {
;     ...
;             PG8_LDA(At, 1, 1); PG8_STAGE(PG8_SB(1, 0), b3, voffB); PG8_STAGE(PG8_SB(1, 1), b3 + hstep, voffB); PG8_STAGE(PG8_SA(1, 0), a3, voffA);
;             PG8_WAIT_V(8); PG8_WAIT_L(0); PG8_BAR; PG8_MMA(1, 0, At, B0); PG8_MMA(1, 1, At, B1); PG8_BAR; PG8_SCHED;
;     ...
;         if constexpr (ALIGN_EPI) { if (wr == 0) PG8_BAR; }
	s_add_i32 s30, s40, s50
	v_lshl_add_u64 v[162:163], v[162:163], 0, s[10:11]
	s_mov_b32 m0, s30
	ds_read_b128 v[182:185], v169 offset:49152
	ds_read_b128 v[186:189], v169 offset:50176
	ds_read_b128 v[190:193], v169 offset:51200
	ds_read_b128 v[194:197], v169 offset:52224
	ds_read_b128 v[198:201], v169 offset:53248
	ds_read_b128 v[202:205], v169 offset:54272
	ds_read_b128 v[206:209], v169 offset:55296
	ds_read_b128 v[210:213], v169 offset:56320
	global_load_lds_dwordx4 v[162:163], off
	s_add_i32 m0, s30, 0x2000
	s_add_u32 s30, s36, 0x158080
	v_lshl_add_u64 v[162:163], v[214:215], 0, s[10:11]
	s_addc_u32 s31, s37, 0
	s_add_i32 s36, s41, s50
	global_load_lds_dwordx4 v[162:163], off
	v_lshl_add_u64 v[162:163], s[30:31], 0, v[146:147]
	s_mov_b32 m0, s36
	s_nop 0
	global_load_lds_dwordx4 v[162:163], off
	v_lshl_add_u64 v[162:163], s[30:31], 0, v[150:151]
	s_add_i32 m0, s36, 0x2000
	s_nop 0
	global_load_lds_dwordx4 v[162:163], off
	v_lshl_add_u64 v[162:163], v[218:219], 0, s[10:11]
	s_mov_b32 m0, s56
	s_nop 0
	global_load_lds_dwordx4 v[162:163], off
	v_lshl_add_u64 v[162:163], v[220:221], 0, s[10:11]
	s_mov_b32 m0, s57
	s_nop 0
	global_load_lds_dwordx4 v[162:163], off
	s_waitcnt vmcnt(8)
	s_waitcnt lgkmcnt(0)
	s_barrier
	s_setprio 1
	s_waitcnt lgkmcnt(0)
	v_mfma_f32_16x16x32_bf16 v[60:63], v[120:123], v[182:185], v[60:63]
	v_mfma_f32_16x16x32_bf16 v[56:59], v[128:131], v[182:185], v[56:59]
	v_mfma_f32_16x16x32_bf16 v[48:51], v[120:123], v[190:193], v[48:51]
	v_mfma_f32_16x16x32_bf16 v[40:43], v[128:131], v[190:193], v[40:43]
	v_mfma_f32_16x16x32_bf16 v[32:35], v[120:123], v[198:201], v[32:35]
	v_mfma_f32_16x16x32_bf16 v[24:27], v[128:131], v[198:201], v[24:27]
	v_mfma_f32_16x16x32_bf16 v[16:19], v[120:123], v[206:209], v[16:19]
	v_mfma_f32_16x16x32_bf16 v[8:11], v[128:131], v[206:209], v[8:11]
	v_mfma_f32_16x16x32_bf16 v[60:63], v[124:127], v[186:189], v[60:63]
	v_mfma_f32_16x16x32_bf16 v[56:59], v[132:135], v[186:189], v[56:59]
	v_mfma_f32_16x16x32_bf16 v[48:51], v[124:127], v[194:197], v[48:51]
	v_mfma_f32_16x16x32_bf16 v[40:43], v[132:135], v[194:197], v[40:43]
	v_mfma_f32_16x16x32_bf16 v[32:35], v[124:127], v[202:205], v[32:35]
	v_mfma_f32_16x16x32_bf16 v[24:27], v[132:135], v[202:205], v[24:27]
	v_mfma_f32_16x16x32_bf16 v[16:19], v[124:127], v[210:213], v[16:19]
	v_mfma_f32_16x16x32_bf16 v[8:11], v[132:135], v[210:213], v[8:11]
	v_mfma_f32_16x16x32_bf16 v[52:55], v[158:161], v[182:185], v[52:55]
	v_mfma_f32_16x16x32_bf16 v[44:47], v[174:177], v[182:185], v[44:47]
	v_mfma_f32_16x16x32_bf16 v[36:39], v[158:161], v[190:193], v[36:39]
	v_mfma_f32_16x16x32_bf16 v[28:31], v[174:177], v[190:193], v[28:31]
	v_mfma_f32_16x16x32_bf16 v[20:23], v[158:161], v[198:201], v[20:23]
	v_mfma_f32_16x16x32_bf16 v[12:15], v[174:177], v[198:201], v[12:15]
	v_mfma_f32_16x16x32_bf16 v[4:7], v[158:161], v[206:209], v[4:7]
	v_mfma_f32_16x16x32_bf16 v[0:3], v[174:177], v[206:209], v[0:3]
	v_mfma_f32_16x16x32_bf16 v[52:55], v[170:173], v[186:189], v[52:55]
	v_mfma_f32_16x16x32_bf16 v[44:47], v[178:181], v[186:189], v[44:47]
	v_mfma_f32_16x16x32_bf16 v[36:39], v[170:173], v[194:197], v[36:39]
	v_mfma_f32_16x16x32_bf16 v[28:31], v[178:181], v[194:197], v[28:31]
	v_mfma_f32_16x16x32_bf16 v[20:23], v[170:173], v[202:205], v[20:23]
	v_mfma_f32_16x16x32_bf16 v[12:15], v[178:181], v[202:205], v[12:15]
	v_mfma_f32_16x16x32_bf16 v[4:7], v[170:173], v[210:213], v[4:7]
	v_mfma_f32_16x16x32_bf16 v[0:3], v[178:181], v[210:213], v[0:3]
	s_setprio 0
	s_barrier
	s_add_i32 s73, s73, 2
	s_add_u32 s71, s71, 0x100
	s_addc_u32 s72, s72, 0
	s_cmpk_gt_u32 s73, 0x53
	s_mov_b64 s[30:31], s[34:35]
	s_cbranch_scc0 .LBB0_1952
	s_and_b64 vcc, exec, s[14:15]
	s_cbranch_vccz .LBB0_1955
	s_barrier
